# all GEMM epilogues (in-proj, merged, w_out, xq, xo, ff1): st_rows16 lane exchange (4 DPP + 8 cndmask) replaced by two direct 16-byte stores per lane at hi?addrB:addrA and +64 B
# baseline (speedup 1.0000x reference)
;   DI void operator()(g8::Acc& acc, int pm, int pn, int wr, int wc, int fr, int fq) const {
;     ...
;     const int seg = pn >> 2;
;     const float* rope = (const float*)(p.ws + OFF_ROPE);
;     bf16_t* dst; unsigned ld; int cofs;
;     if (seg < 5) { dst = slot(p, seg + 1); ld = 1024; cofs = seg * 1024; } else { dst = (bf16_t*)p.out; ld = 2048; cofs = 5 * 1024; }
;     const float qs = (seg == 0) ? 0.125f * LOG2E : 1.0f;
;     const float sgn = (fq == 0) ? -1.0f : 1.0f; const bool use = fq < 2;
;     const unsigned col0 = (unsigned)(pn * BM + wc * 64 - cofs);
; #pragma unroll
;     for (int ai = 0; ai < 2; ++ai)
; #pragma unroll
;       for (int m = 0; m < 4; ++m) {
;         const int row0 = pm * BM + ai * HALF + wr * 64 + m * 16, row = row0 + fr;
;         u32x4 w[2];
; #pragma unroll
;         for (int bj = 0; bj < 2; ++bj) {
;           f32x4 o0 = acc[ai][bj][m][0], o1 = acc[ai][bj][m][1];
;           if (seg < 2) {
;             if (bj == 0) {
;               const f32x4 c0 = gld<f32x4>(rope, (unsigned)row * 64u), c1 = gld<f32x4>(rope, (unsigned)row * 64u + 16u), s0 = gld<f32x4>(rope, (unsigned)row * 64u + 32u) * sgn, s1 = gld<f32x4>(rope, (unsigned)row * 64u + 48u) * sgn;
;               f32x4 p0, p1;
; #pragma unroll
;               for (int e = 0; e < 4; ++e) { p0[e] = __shfl_xor(o0[e], 16); p1[e] = __shfl_xor(o1[e], 16); }
;               const f32x4 r0 = o0 * c0 + p0 * s0, r1 = o1 * c1 + p1 * s1;
; #pragma unroll
;               for (int e = 0; e < 4; ++e) { o0[e] = use ? r0[e] : o0[e]; o1[e] = use ? r1[e] : o1[e]; }
;             }
;             o0 = o0 * qs; o1 = o1 * qs;
;           } else if (seg == 3 || seg == 4) {
; #pragma unroll
;             for (int e = 0; e < 4; ++e) {
;               { const float xx = o0[e], y2 = (-2.0f * 0.7978845608028654f * LOG2E) * (xx + 0.044715f * xx * xx * xx); o0[e] = xx * __builtin_amdgcn_rcpf(1.0f + __builtin_amdgcn_exp2f(y2)); }
;               { const float xx = o1[e], y2 = (-2.0f * 0.7978845608028654f * LOG2E) * (xx + 0.044715f * xx * xx * xx); o1[e] = xx * __builtin_amdgcn_rcpf(1.0f + __builtin_amdgcn_exp2f(y2)); }
;             }
;           } else if (seg >= 5) {
; #pragma unroll
;             for (int e = 0; e < 4; ++e) { o0[e] = __builtin_amdgcn_rcpf(1.0f + __builtin_amdgcn_exp2f(-LOG2E * o0[e])); o1[e] = __builtin_amdgcn_rcpf(1.0f + __builtin_amdgcn_exp2f(-LOG2E * o1[e])); }
;           }
.LBB0_180:
	s_cmp_lt_i32 s90, 5
	s_cselect_b64 s[0:1], -1, 0
	s_ashr_i32 s91, s90, 31
	s_lshl_b64 s[20:21], s[90:91], 26
	s_add_u32 s19, s44, s20
	s_addc_u32 s20, s45, s21
	s_add_u32 s19, s19, 0x4000000
	s_addc_u32 s22, s20, 0
	s_min_i32 s23, s90, 5
	s_and_b64 s[20:21], s[0:1], exec
	s_cselect_b32 s91, s22, s73
	s_cselect_b32 s90, s19, s72
	s_lshl_b32 s19, s92, 8
	s_or_b32 s19, s19, s77
	s_lshl_b32 s20, s23, 10
	s_sub_i32 s19, s19, s20
	v_or_b32_e32 v112, s19, v156
	v_or_b32_e32 v116, v112, v159
	v_or_b32_e32 v112, v112, v160
	v_cvt_pk_bf16_f32 v232, v146, v147
	v_lshlrev_b32_e32 v146, 1, v112
	v_cvt_pk_bf16_f32 v236, v120, v121
	s_and_b64 s[0:1], s[0:1], exec
	v_lshlrev_b32_e32 v147, 1, v116
	v_cvt_pk_bf16_f32 v237, v122, v123
	v_cvt_pk_bf16_f32 v238, v124, v125
	v_cvt_pk_bf16_f32 v239, v126, v127
	v_cvt_pk_bf16_f32 v233, v148, v149
	v_cvt_pk_bf16_f32 v234, v150, v151
	v_cvt_pk_bf16_f32 v235, v152, v153
	s_cselect_b32 s19, 11, 12
	v_or_b32_e32 v120, s18, v158
	v_lshl_add_u32 v121, v120, s19, v147
	s_and_b64 vcc, exec, s[10:11]
	v_or_b32_e32 v112, 8, v120
	v_lshl_add_u32 v112, v112, s19, v146
	s_mov_b64 s[0:1], -1
	v_cndmask_b32_e64 v240, v121, v112, s[6:7]
	global_store_dwordx4 v240, v[232:235], s[90:91] nt
	global_store_dwordx4 v240, v[236:239], s[90:91] offset:64 nt
	s_cbranch_vccnz .LBB0_188
	s_and_b64 vcc, exec, s[8:9]
	s_cbranch_vccnz .LBB0_185
	s_andn2_b64 vcc, exec, s[88:89]
	v_mov_b32_e32 v115, v111
	v_mov_b32_e32 v114, v110
	v_mov_b32_e32 v113, v109
	v_mov_b32_e32 v112, v108
	v_mov_b32_e32 v119, v107
	v_mov_b32_e32 v118, v106
	v_mov_b32_e32 v117, v105
	v_mov_b32_e32 v116, v104
	s_cbranch_vccnz .LBB0_184
	v_mul_f32_e32 v113, 0xbfb8aa3b, v104
	v_exp_f32_e32 v113, v113
	v_mul_f32_e32 v114, 0xbfb8aa3b, v109
	v_mul_f32_e32 v115, 0xbfb8aa3b, v105
	v_exp_f32_e32 v114, v114
	v_exp_f32_e32 v115, v115
	v_add_f32_e32 v113, 1.0, v113
	v_rcp_f32_e32 v116, v113
	v_add_f32_e32 v113, 1.0, v114
	v_add_f32_e32 v114, 1.0, v115
	v_mul_f32_e32 v115, 0xbfb8aa3b, v110
	v_mul_f32_e32 v117, 0xbfb8aa3b, v106
	v_exp_f32_e32 v115, v115
	v_exp_f32_e32 v118, v117
	v_rcp_f32_e32 v117, v114
	v_mul_f32_e32 v112, 0xbfb8aa3b, v108
	v_add_f32_e32 v114, 1.0, v115
	v_add_f32_e32 v115, 1.0, v118
	v_mul_f32_e32 v118, 0xbfb8aa3b, v111
	v_exp_f32_e32 v119, v118
	v_mul_f32_e32 v118, 0xbfb8aa3b, v107
	v_exp_f32_e32 v112, v112
	v_exp_f32_e32 v120, v118
	v_rcp_f32_e32 v118, v115
	v_add_f32_e32 v115, 1.0, v119
	v_add_f32_e32 v112, 1.0, v112
	v_add_f32_e32 v119, 1.0, v120
	v_rcp_f32_e32 v112, v112
	v_rcp_f32_e32 v113, v113
	v_rcp_f32_e32 v114, v114
	v_rcp_f32_e32 v115, v115
	v_rcp_f32_e32 v119, v119

;   DI void operator()(g8::Acc& acc, int pm, int pn, int wr, int wc, int fr, int fq) const {
;     ...
;     const int seg = pn >> 2;
;     const float* rope = (const float*)(p.ws + OFF_ROPE);
;     bf16_t* dst; unsigned ld; int cofs;
;     if (seg < 5) { dst = slot(p, seg + 1); ld = 1024; cofs = seg * 1024; } else { dst = (bf16_t*)p.out; ld = 2048; cofs = 5 * 1024; }
;     const float qs = (seg == 0) ? 0.125f * LOG2E : 1.0f;
;     const float sgn = (fq == 0) ? -1.0f : 1.0f; const bool use = fq < 2;
;     const unsigned col0 = (unsigned)(pn * BM + wc * 64 - cofs);
; #pragma unroll
;     for (int ai = 0; ai < 2; ++ai)
; #pragma unroll
;       for (int m = 0; m < 4; ++m) {
;         const int row0 = pm * BM + ai * HALF + wr * 64 + m * 16, row = row0 + fr;
;         u32x4 w[2];
; #pragma unroll
;         for (int bj = 0; bj < 2; ++bj) {
;           f32x4 o0 = acc[ai][bj][m][0], o1 = acc[ai][bj][m][1];
;           if (seg < 2) {
;             if (bj == 0) {
;               const f32x4 c0 = gld<f32x4>(rope, (unsigned)row * 64u), c1 = gld<f32x4>(rope, (unsigned)row * 64u + 16u), s0 = gld<f32x4>(rope, (unsigned)row * 64u + 32u) * sgn, s1 = gld<f32x4>(rope, (unsigned)row * 64u + 48u) * sgn;
;               f32x4 p0, p1;
; #pragma unroll
;               for (int e = 0; e < 4; ++e) { p0[e] = __shfl_xor(o0[e], 16); p1[e] = __shfl_xor(o1[e], 16); }
;               const f32x4 r0 = o0 * c0 + p0 * s0, r1 = o1 * c1 + p1 * s1;
; #pragma unroll
;               for (int e = 0; e < 4; ++e) { o0[e] = use ? r0[e] : o0[e]; o1[e] = use ? r1[e] : o1[e]; }
;             }
;             o0 = o0 * qs; o1 = o1 * qs;
;           } else if (seg == 3 || seg == 4) {
; #pragma unroll
;             for (int e = 0; e < 4; ++e) {
;               { const float xx = o0[e], y2 = (-2.0f * 0.7978845608028654f * LOG2E) * (xx + 0.044715f * xx * xx * xx); o0[e] = xx * __builtin_amdgcn_rcpf(1.0f + __builtin_amdgcn_exp2f(y2)); }
;               { const float xx = o1[e], y2 = (-2.0f * 0.7978845608028654f * LOG2E) * (xx + 0.044715f * xx * xx * xx); o1[e] = xx * __builtin_amdgcn_rcpf(1.0f + __builtin_amdgcn_exp2f(y2)); }
;             }
;           } else if (seg >= 5) {
; #pragma unroll
;             for (int e = 0; e < 4; ++e) { o0[e] = __builtin_amdgcn_rcpf(1.0f + __builtin_amdgcn_exp2f(-LOG2E * o0[e])); o1[e] = __builtin_amdgcn_rcpf(1.0f + __builtin_amdgcn_exp2f(-LOG2E * o1[e])); }
;           }
.LBB0_200:
	v_cvt_pk_bf16_f32 v236, v104, v105
	v_cvt_pk_bf16_f32 v232, v112, v113
	v_cvt_pk_bf16_f32 v237, v106, v107
	v_cvt_pk_bf16_f32 v238, v108, v109
	v_cvt_pk_bf16_f32 v239, v110, v111
	v_cvt_pk_bf16_f32 v233, v114, v115
	v_cvt_pk_bf16_f32 v234, v116, v117
	v_cvt_pk_bf16_f32 v235, v118, v119
	v_or_b32_e32 v104, s20, v158
	v_lshl_add_u32 v105, v104, s19, v147
	s_and_b64 vcc, exec, s[10:11]
	v_or_b32_e32 v96, 8, v104
	v_lshl_add_u32 v96, v96, s19, v146
	s_mov_b64 s[0:1], -1
	v_cndmask_b32_e64 v240, v105, v96, s[6:7]
	global_store_dwordx4 v240, v[232:235], s[90:91] nt
	global_store_dwordx4 v240, v[236:239], s[90:91] offset:64 nt
	s_cbranch_vccnz .LBB0_208
	s_and_b64 vcc, exec, s[8:9]
	s_cbranch_vccnz .LBB0_205
	s_andn2_b64 vcc, exec, s[88:89]
	v_mov_b32_e32 v99, v95
	v_mov_b32_e32 v98, v94
	v_mov_b32_e32 v97, v93
	v_mov_b32_e32 v96, v92
	v_mov_b32_e32 v103, v91
	v_mov_b32_e32 v102, v90
	v_mov_b32_e32 v101, v89
	v_mov_b32_e32 v100, v88
	s_cbranch_vccnz .LBB0_204
	v_mul_f32_e32 v97, 0xbfb8aa3b, v88
	v_exp_f32_e32 v97, v97
	v_mul_f32_e32 v98, 0xbfb8aa3b, v93
	v_mul_f32_e32 v99, 0xbfb8aa3b, v89
	v_exp_f32_e32 v98, v98
	v_exp_f32_e32 v99, v99
	v_add_f32_e32 v97, 1.0, v97
	v_rcp_f32_e32 v100, v97
	v_add_f32_e32 v97, 1.0, v98
	v_add_f32_e32 v98, 1.0, v99
	v_mul_f32_e32 v99, 0xbfb8aa3b, v94
	v_mul_f32_e32 v101, 0xbfb8aa3b, v90
	v_exp_f32_e32 v99, v99
	v_exp_f32_e32 v102, v101
	v_rcp_f32_e32 v101, v98
	v_mul_f32_e32 v96, 0xbfb8aa3b, v92
	v_add_f32_e32 v98, 1.0, v99
	v_add_f32_e32 v99, 1.0, v102
	v_mul_f32_e32 v102, 0xbfb8aa3b, v95
	v_exp_f32_e32 v103, v102
	v_mul_f32_e32 v102, 0xbfb8aa3b, v91
	v_exp_f32_e32 v96, v96
	v_exp_f32_e32 v104, v102
	v_rcp_f32_e32 v102, v99
	v_add_f32_e32 v99, 1.0, v103
	v_add_f32_e32 v96, 1.0, v96
	v_add_f32_e32 v103, 1.0, v104
	v_rcp_f32_e32 v96, v96
	v_rcp_f32_e32 v97, v97
	v_rcp_f32_e32 v98, v98
	v_rcp_f32_e32 v99, v99
	v_rcp_f32_e32 v103, v103

;   DI void operator()(g8::Acc& acc, int pm, int pn, int wr, int wc, int fr, int fq) const {
;     ...
;     const int seg = pn >> 2;
;     const float* rope = (const float*)(p.ws + OFF_ROPE);
;     bf16_t* dst; unsigned ld; int cofs;
;     if (seg < 5) { dst = slot(p, seg + 1); ld = 1024; cofs = seg * 1024; } else { dst = (bf16_t*)p.out; ld = 2048; cofs = 5 * 1024; }
;     const float qs = (seg == 0) ? 0.125f * LOG2E : 1.0f;
;     const float sgn = (fq == 0) ? -1.0f : 1.0f; const bool use = fq < 2;
;     const unsigned col0 = (unsigned)(pn * BM + wc * 64 - cofs);
; #pragma unroll
;     for (int ai = 0; ai < 2; ++ai)
; #pragma unroll
;       for (int m = 0; m < 4; ++m) {
;         const int row0 = pm * BM + ai * HALF + wr * 64 + m * 16, row = row0 + fr;
;         u32x4 w[2];
; #pragma unroll
;         for (int bj = 0; bj < 2; ++bj) {
;           f32x4 o0 = acc[ai][bj][m][0], o1 = acc[ai][bj][m][1];
;           if (seg < 2) {
;             if (bj == 0) {
;               const f32x4 c0 = gld<f32x4>(rope, (unsigned)row * 64u), c1 = gld<f32x4>(rope, (unsigned)row * 64u + 16u), s0 = gld<f32x4>(rope, (unsigned)row * 64u + 32u) * sgn, s1 = gld<f32x4>(rope, (unsigned)row * 64u + 48u) * sgn;
;               f32x4 p0, p1;
; #pragma unroll
;               for (int e = 0; e < 4; ++e) { p0[e] = __shfl_xor(o0[e], 16); p1[e] = __shfl_xor(o1[e], 16); }
;               const f32x4 r0 = o0 * c0 + p0 * s0, r1 = o1 * c1 + p1 * s1;
; #pragma unroll
;               for (int e = 0; e < 4; ++e) { o0[e] = use ? r0[e] : o0[e]; o1[e] = use ? r1[e] : o1[e]; }
;             }
;             o0 = o0 * qs; o1 = o1 * qs;
;           } else if (seg == 3 || seg == 4) {
; #pragma unroll
;             for (int e = 0; e < 4; ++e) {
;               { const float xx = o0[e], y2 = (-2.0f * 0.7978845608028654f * LOG2E) * (xx + 0.044715f * xx * xx * xx); o0[e] = xx * __builtin_amdgcn_rcpf(1.0f + __builtin_amdgcn_exp2f(y2)); }
;               { const float xx = o1[e], y2 = (-2.0f * 0.7978845608028654f * LOG2E) * (xx + 0.044715f * xx * xx * xx); o1[e] = xx * __builtin_amdgcn_rcpf(1.0f + __builtin_amdgcn_exp2f(y2)); }
;             }
;           } else if (seg >= 5) {
; #pragma unroll
;             for (int e = 0; e < 4; ++e) { o0[e] = __builtin_amdgcn_rcpf(1.0f + __builtin_amdgcn_exp2f(-LOG2E * o0[e])); o1[e] = __builtin_amdgcn_rcpf(1.0f + __builtin_amdgcn_exp2f(-LOG2E * o1[e])); }
;           }
.LBB0_220:
	v_cvt_pk_bf16_f32 v236, v88, v89
	v_cvt_pk_bf16_f32 v232, v96, v97
	v_cvt_pk_bf16_f32 v237, v90, v91
	v_cvt_pk_bf16_f32 v238, v92, v93
	v_cvt_pk_bf16_f32 v239, v94, v95
	v_cvt_pk_bf16_f32 v233, v98, v99
	v_cvt_pk_bf16_f32 v234, v100, v101
	v_cvt_pk_bf16_f32 v235, v102, v103
	v_or_b32_e32 v88, s20, v158
	v_lshl_add_u32 v89, v88, s19, v147
	s_and_b64 vcc, exec, s[10:11]
	v_or_b32_e32 v80, 8, v88
	v_lshl_add_u32 v80, v80, s19, v146
	s_mov_b64 s[0:1], -1
	v_cndmask_b32_e64 v240, v89, v80, s[6:7]
	global_store_dwordx4 v240, v[232:235], s[90:91] nt
	global_store_dwordx4 v240, v[236:239], s[90:91] offset:64 nt
	s_cbranch_vccnz .LBB0_228
	s_and_b64 vcc, exec, s[8:9]
	s_cbranch_vccnz .LBB0_225
	s_andn2_b64 vcc, exec, s[88:89]
	v_mov_b32_e32 v83, v79
	v_mov_b32_e32 v82, v78
	v_mov_b32_e32 v81, v77
	v_mov_b32_e32 v80, v76
	v_mov_b32_e32 v87, v75
	v_mov_b32_e32 v86, v74
	v_mov_b32_e32 v85, v73
	v_mov_b32_e32 v84, v72
	s_cbranch_vccnz .LBB0_224
	v_mul_f32_e32 v81, 0xbfb8aa3b, v72
	v_exp_f32_e32 v81, v81
	v_mul_f32_e32 v82, 0xbfb8aa3b, v77
	v_mul_f32_e32 v83, 0xbfb8aa3b, v73
	v_exp_f32_e32 v82, v82
	v_exp_f32_e32 v83, v83
	v_add_f32_e32 v81, 1.0, v81
	v_rcp_f32_e32 v84, v81
	v_add_f32_e32 v81, 1.0, v82
	v_add_f32_e32 v82, 1.0, v83
	v_mul_f32_e32 v83, 0xbfb8aa3b, v78
	v_mul_f32_e32 v85, 0xbfb8aa3b, v74
	v_exp_f32_e32 v83, v83
	v_exp_f32_e32 v86, v85
	v_rcp_f32_e32 v85, v82
	v_mul_f32_e32 v80, 0xbfb8aa3b, v76
	v_add_f32_e32 v82, 1.0, v83
	v_add_f32_e32 v83, 1.0, v86
	v_mul_f32_e32 v86, 0xbfb8aa3b, v79
	v_exp_f32_e32 v87, v86
	v_mul_f32_e32 v86, 0xbfb8aa3b, v75
	v_exp_f32_e32 v80, v80
	v_exp_f32_e32 v88, v86
	v_rcp_f32_e32 v86, v83
	v_add_f32_e32 v83, 1.0, v87
	v_add_f32_e32 v80, 1.0, v80
	v_add_f32_e32 v87, 1.0, v88
	v_rcp_f32_e32 v80, v80
	v_rcp_f32_e32 v81, v81
	v_rcp_f32_e32 v82, v82
	v_rcp_f32_e32 v83, v83
	v_rcp_f32_e32 v87, v87

;   DI void operator()(g8::Acc& acc, int pm, int pn, int wr, int wc, int fr, int fq) const {
;     ...
;     const int seg = pn >> 2;
;     const float* rope = (const float*)(p.ws + OFF_ROPE);
;     bf16_t* dst; unsigned ld; int cofs;
;     if (seg < 5) { dst = slot(p, seg + 1); ld = 1024; cofs = seg * 1024; } else { dst = (bf16_t*)p.out; ld = 2048; cofs = 5 * 1024; }
;     const float qs = (seg == 0) ? 0.125f * LOG2E : 1.0f;
;     const float sgn = (fq == 0) ? -1.0f : 1.0f; const bool use = fq < 2;
;     const unsigned col0 = (unsigned)(pn * BM + wc * 64 - cofs);
; #pragma unroll
;     for (int ai = 0; ai < 2; ++ai)
; #pragma unroll
;       for (int m = 0; m < 4; ++m) {
;         const int row0 = pm * BM + ai * HALF + wr * 64 + m * 16, row = row0 + fr;
;         u32x4 w[2];
; #pragma unroll
;         for (int bj = 0; bj < 2; ++bj) {
;           f32x4 o0 = acc[ai][bj][m][0], o1 = acc[ai][bj][m][1];
;           if (seg < 2) {
;             if (bj == 0) {
;               const f32x4 c0 = gld<f32x4>(rope, (unsigned)row * 64u), c1 = gld<f32x4>(rope, (unsigned)row * 64u + 16u), s0 = gld<f32x4>(rope, (unsigned)row * 64u + 32u) * sgn, s1 = gld<f32x4>(rope, (unsigned)row * 64u + 48u) * sgn;
;               f32x4 p0, p1;
; #pragma unroll
;               for (int e = 0; e < 4; ++e) { p0[e] = __shfl_xor(o0[e], 16); p1[e] = __shfl_xor(o1[e], 16); }
;               const f32x4 r0 = o0 * c0 + p0 * s0, r1 = o1 * c1 + p1 * s1;
; #pragma unroll
;               for (int e = 0; e < 4; ++e) { o0[e] = use ? r0[e] : o0[e]; o1[e] = use ? r1[e] : o1[e]; }
;             }
;             o0 = o0 * qs; o1 = o1 * qs;
;           } else if (seg == 3 || seg == 4) {
; #pragma unroll
;             for (int e = 0; e < 4; ++e) {
;               { const float xx = o0[e], y2 = (-2.0f * 0.7978845608028654f * LOG2E) * (xx + 0.044715f * xx * xx * xx); o0[e] = xx * __builtin_amdgcn_rcpf(1.0f + __builtin_amdgcn_exp2f(y2)); }
;               { const float xx = o1[e], y2 = (-2.0f * 0.7978845608028654f * LOG2E) * (xx + 0.044715f * xx * xx * xx); o1[e] = xx * __builtin_amdgcn_rcpf(1.0f + __builtin_amdgcn_exp2f(y2)); }
;             }
;           } else if (seg >= 5) {
; #pragma unroll
;             for (int e = 0; e < 4; ++e) { o0[e] = __builtin_amdgcn_rcpf(1.0f + __builtin_amdgcn_exp2f(-LOG2E * o0[e])); o1[e] = __builtin_amdgcn_rcpf(1.0f + __builtin_amdgcn_exp2f(-LOG2E * o1[e])); }
;           }
.LBB0_240:
	v_cvt_pk_bf16_f32 v236, v72, v73
	v_cvt_pk_bf16_f32 v232, v80, v81
	v_cvt_pk_bf16_f32 v237, v74, v75
	v_cvt_pk_bf16_f32 v238, v76, v77
	v_cvt_pk_bf16_f32 v239, v78, v79
	v_cvt_pk_bf16_f32 v233, v82, v83
	v_cvt_pk_bf16_f32 v234, v84, v85
	v_cvt_pk_bf16_f32 v235, v86, v87
	v_or_b32_e32 v72, s20, v158
	v_lshl_add_u32 v73, v72, s19, v147
	s_and_b64 vcc, exec, s[10:11]
	v_or_b32_e32 v64, 8, v72
	v_lshl_add_u32 v64, v64, s19, v146
	s_mov_b64 s[0:1], -1
	v_cndmask_b32_e64 v240, v73, v64, s[6:7]
	global_store_dwordx4 v240, v[232:235], s[90:91] nt
	global_store_dwordx4 v240, v[236:239], s[90:91] offset:64 nt
	s_cbranch_vccnz .LBB0_248
	s_and_b64 vcc, exec, s[8:9]
	s_cbranch_vccnz .LBB0_245
	s_andn2_b64 vcc, exec, s[88:89]
	v_mov_b32_e32 v67, v63
	v_mov_b32_e32 v66, v62
	v_mov_b32_e32 v65, v61
	v_mov_b32_e32 v64, v60
	v_mov_b32_e32 v71, v59
	v_mov_b32_e32 v70, v58
	v_mov_b32_e32 v69, v57
	v_mov_b32_e32 v68, v56
	s_cbranch_vccnz .LBB0_244
	v_mul_f32_e32 v65, 0xbfb8aa3b, v56
	v_exp_f32_e32 v65, v65
	v_mul_f32_e32 v66, 0xbfb8aa3b, v61
	v_mul_f32_e32 v67, 0xbfb8aa3b, v57
	v_exp_f32_e32 v66, v66
	v_exp_f32_e32 v67, v67
	v_add_f32_e32 v65, 1.0, v65
	v_rcp_f32_e32 v68, v65
	v_add_f32_e32 v65, 1.0, v66
	v_add_f32_e32 v66, 1.0, v67
	v_mul_f32_e32 v67, 0xbfb8aa3b, v62
	v_mul_f32_e32 v69, 0xbfb8aa3b, v58
	v_exp_f32_e32 v67, v67
	v_exp_f32_e32 v70, v69
	v_rcp_f32_e32 v69, v66
	v_mul_f32_e32 v64, 0xbfb8aa3b, v60
	v_add_f32_e32 v66, 1.0, v67
	v_add_f32_e32 v67, 1.0, v70
	v_mul_f32_e32 v70, 0xbfb8aa3b, v63
	v_exp_f32_e32 v71, v70
	v_mul_f32_e32 v70, 0xbfb8aa3b, v59
	v_exp_f32_e32 v64, v64
	v_exp_f32_e32 v72, v70
	v_rcp_f32_e32 v70, v67
	v_add_f32_e32 v67, 1.0, v71
	v_add_f32_e32 v64, 1.0, v64
	v_add_f32_e32 v71, 1.0, v72
	v_rcp_f32_e32 v64, v64
	v_rcp_f32_e32 v65, v65
	v_rcp_f32_e32 v66, v66
	v_rcp_f32_e32 v67, v67
	v_rcp_f32_e32 v71, v71

;   DI void operator()(g8::Acc& acc, int pm, int pn, int wr, int wc, int fr, int fq) const {
;     ...
;     const int seg = pn >> 2;
;     const float* rope = (const float*)(p.ws + OFF_ROPE);
;     bf16_t* dst; unsigned ld; int cofs;
;     if (seg < 5) { dst = slot(p, seg + 1); ld = 1024; cofs = seg * 1024; } else { dst = (bf16_t*)p.out; ld = 2048; cofs = 5 * 1024; }
;     const float qs = (seg == 0) ? 0.125f * LOG2E : 1.0f;
;     const float sgn = (fq == 0) ? -1.0f : 1.0f; const bool use = fq < 2;
;     const unsigned col0 = (unsigned)(pn * BM + wc * 64 - cofs);
; #pragma unroll
;     for (int ai = 0; ai < 2; ++ai)
; #pragma unroll
;       for (int m = 0; m < 4; ++m) {
;         const int row0 = pm * BM + ai * HALF + wr * 64 + m * 16, row = row0 + fr;
;         u32x4 w[2];
; #pragma unroll
;         for (int bj = 0; bj < 2; ++bj) {
;           f32x4 o0 = acc[ai][bj][m][0], o1 = acc[ai][bj][m][1];
;           if (seg < 2) {
;             if (bj == 0) {
;               const f32x4 c0 = gld<f32x4>(rope, (unsigned)row * 64u), c1 = gld<f32x4>(rope, (unsigned)row * 64u + 16u), s0 = gld<f32x4>(rope, (unsigned)row * 64u + 32u) * sgn, s1 = gld<f32x4>(rope, (unsigned)row * 64u + 48u) * sgn;
;               f32x4 p0, p1;
; #pragma unroll
;               for (int e = 0; e < 4; ++e) { p0[e] = __shfl_xor(o0[e], 16); p1[e] = __shfl_xor(o1[e], 16); }
;               const f32x4 r0 = o0 * c0 + p0 * s0, r1 = o1 * c1 + p1 * s1;
; #pragma unroll
;               for (int e = 0; e < 4; ++e) { o0[e] = use ? r0[e] : o0[e]; o1[e] = use ? r1[e] : o1[e]; }
;             }
;             o0 = o0 * qs; o1 = o1 * qs;
;           } else if (seg == 3 || seg == 4) {
; #pragma unroll
;             for (int e = 0; e < 4; ++e) {
;               { const float xx = o0[e], y2 = (-2.0f * 0.7978845608028654f * LOG2E) * (xx + 0.044715f * xx * xx * xx); o0[e] = xx * __builtin_amdgcn_rcpf(1.0f + __builtin_amdgcn_exp2f(y2)); }
;               { const float xx = o1[e], y2 = (-2.0f * 0.7978845608028654f * LOG2E) * (xx + 0.044715f * xx * xx * xx); o1[e] = xx * __builtin_amdgcn_rcpf(1.0f + __builtin_amdgcn_exp2f(y2)); }
;             }
;           } else if (seg >= 5) {
; #pragma unroll
;             for (int e = 0; e < 4; ++e) { o0[e] = __builtin_amdgcn_rcpf(1.0f + __builtin_amdgcn_exp2f(-LOG2E * o0[e])); o1[e] = __builtin_amdgcn_rcpf(1.0f + __builtin_amdgcn_exp2f(-LOG2E * o1[e])); }
;           }
.LBB0_260:
	v_cvt_pk_bf16_f32 v236, v56, v57
	v_cvt_pk_bf16_f32 v232, v64, v65
	v_cvt_pk_bf16_f32 v237, v58, v59
	v_cvt_pk_bf16_f32 v238, v60, v61
	v_cvt_pk_bf16_f32 v239, v62, v63
	v_cvt_pk_bf16_f32 v233, v66, v67
	v_cvt_pk_bf16_f32 v234, v68, v69
	v_cvt_pk_bf16_f32 v235, v70, v71
	v_or_b32_e32 v56, s20, v158
	v_lshl_add_u32 v57, v56, s19, v147
	s_and_b64 vcc, exec, s[10:11]
	v_or_b32_e32 v48, 8, v56
	v_lshl_add_u32 v48, v48, s19, v146
	s_mov_b64 s[0:1], -1
	v_cndmask_b32_e64 v240, v57, v48, s[6:7]
	global_store_dwordx4 v240, v[232:235], s[90:91] nt
	global_store_dwordx4 v240, v[236:239], s[90:91] offset:64 nt
	s_cbranch_vccnz .LBB0_268
	s_and_b64 vcc, exec, s[8:9]
	s_cbranch_vccnz .LBB0_265
	s_andn2_b64 vcc, exec, s[88:89]
	v_mov_b32_e32 v51, v47
	v_mov_b32_e32 v50, v46
	v_mov_b32_e32 v49, v45
	v_mov_b32_e32 v48, v44
	v_mov_b32_e32 v55, v43
	v_mov_b32_e32 v54, v42
	v_mov_b32_e32 v53, v41
	v_mov_b32_e32 v52, v40
	s_cbranch_vccnz .LBB0_264
	v_mul_f32_e32 v49, 0xbfb8aa3b, v40
	v_exp_f32_e32 v49, v49
	v_mul_f32_e32 v50, 0xbfb8aa3b, v45
	v_mul_f32_e32 v51, 0xbfb8aa3b, v41
	v_exp_f32_e32 v50, v50
	v_exp_f32_e32 v51, v51
	v_add_f32_e32 v49, 1.0, v49
	v_rcp_f32_e32 v52, v49
	v_add_f32_e32 v49, 1.0, v50
	v_add_f32_e32 v50, 1.0, v51
	v_mul_f32_e32 v51, 0xbfb8aa3b, v46
	v_mul_f32_e32 v53, 0xbfb8aa3b, v42
	v_exp_f32_e32 v51, v51
	v_exp_f32_e32 v54, v53
	v_rcp_f32_e32 v53, v50
	v_mul_f32_e32 v48, 0xbfb8aa3b, v44
	v_add_f32_e32 v50, 1.0, v51
	v_add_f32_e32 v51, 1.0, v54
	v_mul_f32_e32 v54, 0xbfb8aa3b, v47
	v_exp_f32_e32 v55, v54
	v_mul_f32_e32 v54, 0xbfb8aa3b, v43
	v_exp_f32_e32 v48, v48
	v_exp_f32_e32 v56, v54
	v_rcp_f32_e32 v54, v51
	v_add_f32_e32 v51, 1.0, v55
	v_add_f32_e32 v48, 1.0, v48
	v_add_f32_e32 v55, 1.0, v56
	v_rcp_f32_e32 v48, v48
	v_rcp_f32_e32 v49, v49
	v_rcp_f32_e32 v50, v50
	v_rcp_f32_e32 v51, v51
	v_rcp_f32_e32 v55, v55

;   DI void operator()(g8::Acc& acc, int pm, int pn, int wr, int wc, int fr, int fq) const {
;     ...
;     const int seg = pn >> 2;
;     const float* rope = (const float*)(p.ws + OFF_ROPE);
;     bf16_t* dst; unsigned ld; int cofs;
;     if (seg < 5) { dst = slot(p, seg + 1); ld = 1024; cofs = seg * 1024; } else { dst = (bf16_t*)p.out; ld = 2048; cofs = 5 * 1024; }
;     const float qs = (seg == 0) ? 0.125f * LOG2E : 1.0f;
;     const float sgn = (fq == 0) ? -1.0f : 1.0f; const bool use = fq < 2;
;     const unsigned col0 = (unsigned)(pn * BM + wc * 64 - cofs);
; #pragma unroll
;     for (int ai = 0; ai < 2; ++ai)
; #pragma unroll
;       for (int m = 0; m < 4; ++m) {
;         const int row0 = pm * BM + ai * HALF + wr * 64 + m * 16, row = row0 + fr;
;         u32x4 w[2];
; #pragma unroll
;         for (int bj = 0; bj < 2; ++bj) {
;           f32x4 o0 = acc[ai][bj][m][0], o1 = acc[ai][bj][m][1];
;           if (seg < 2) {
;             if (bj == 0) {
;               const f32x4 c0 = gld<f32x4>(rope, (unsigned)row * 64u), c1 = gld<f32x4>(rope, (unsigned)row * 64u + 16u), s0 = gld<f32x4>(rope, (unsigned)row * 64u + 32u) * sgn, s1 = gld<f32x4>(rope, (unsigned)row * 64u + 48u) * sgn;
;               f32x4 p0, p1;
; #pragma unroll
;               for (int e = 0; e < 4; ++e) { p0[e] = __shfl_xor(o0[e], 16); p1[e] = __shfl_xor(o1[e], 16); }
;               const f32x4 r0 = o0 * c0 + p0 * s0, r1 = o1 * c1 + p1 * s1;
; #pragma unroll
;               for (int e = 0; e < 4; ++e) { o0[e] = use ? r0[e] : o0[e]; o1[e] = use ? r1[e] : o1[e]; }
;             }
;             o0 = o0 * qs; o1 = o1 * qs;
;           } else if (seg == 3 || seg == 4) {
; #pragma unroll
;             for (int e = 0; e < 4; ++e) {
;               { const float xx = o0[e], y2 = (-2.0f * 0.7978845608028654f * LOG2E) * (xx + 0.044715f * xx * xx * xx); o0[e] = xx * __builtin_amdgcn_rcpf(1.0f + __builtin_amdgcn_exp2f(y2)); }
;               { const float xx = o1[e], y2 = (-2.0f * 0.7978845608028654f * LOG2E) * (xx + 0.044715f * xx * xx * xx); o1[e] = xx * __builtin_amdgcn_rcpf(1.0f + __builtin_amdgcn_exp2f(y2)); }
;             }
;           } else if (seg >= 5) {
; #pragma unroll
;             for (int e = 0; e < 4; ++e) { o0[e] = __builtin_amdgcn_rcpf(1.0f + __builtin_amdgcn_exp2f(-LOG2E * o0[e])); o1[e] = __builtin_amdgcn_rcpf(1.0f + __builtin_amdgcn_exp2f(-LOG2E * o1[e])); }
;           }
.LBB0_280:
	v_cvt_pk_bf16_f32 v236, v40, v41
	v_cvt_pk_bf16_f32 v232, v48, v49
	v_cvt_pk_bf16_f32 v237, v42, v43
	v_cvt_pk_bf16_f32 v238, v44, v45
	v_cvt_pk_bf16_f32 v239, v46, v47
	v_cvt_pk_bf16_f32 v233, v50, v51
	v_cvt_pk_bf16_f32 v234, v52, v53
	v_cvt_pk_bf16_f32 v235, v54, v55
	v_or_b32_e32 v40, s20, v158
	v_lshl_add_u32 v41, v40, s19, v147
	s_and_b64 vcc, exec, s[10:11]
	v_or_b32_e32 v32, 8, v40
	v_lshl_add_u32 v32, v32, s19, v146
	s_mov_b64 s[0:1], -1
	v_cndmask_b32_e64 v240, v41, v32, s[6:7]
	global_store_dwordx4 v240, v[232:235], s[90:91] nt
	global_store_dwordx4 v240, v[236:239], s[90:91] offset:64 nt
	s_cbranch_vccnz .LBB0_288
	s_and_b64 vcc, exec, s[8:9]
	s_cbranch_vccnz .LBB0_285
	s_andn2_b64 vcc, exec, s[88:89]
	v_mov_b32_e32 v35, v31
	v_mov_b32_e32 v34, v30
	v_mov_b32_e32 v33, v29
	v_mov_b32_e32 v32, v28
	v_mov_b32_e32 v39, v27
	v_mov_b32_e32 v38, v26
	v_mov_b32_e32 v37, v25
	v_mov_b32_e32 v36, v24
	s_cbranch_vccnz .LBB0_284
	v_mul_f32_e32 v33, 0xbfb8aa3b, v24
	v_exp_f32_e32 v33, v33
	v_mul_f32_e32 v34, 0xbfb8aa3b, v29
	v_mul_f32_e32 v35, 0xbfb8aa3b, v25
	v_exp_f32_e32 v34, v34
	v_exp_f32_e32 v35, v35
	v_add_f32_e32 v33, 1.0, v33
	v_rcp_f32_e32 v36, v33
	v_add_f32_e32 v33, 1.0, v34
	v_add_f32_e32 v34, 1.0, v35
	v_mul_f32_e32 v35, 0xbfb8aa3b, v30
	v_mul_f32_e32 v37, 0xbfb8aa3b, v26
	v_exp_f32_e32 v35, v35
	v_exp_f32_e32 v38, v37
	v_rcp_f32_e32 v37, v34
	v_mul_f32_e32 v32, 0xbfb8aa3b, v28
	v_add_f32_e32 v34, 1.0, v35
	v_add_f32_e32 v35, 1.0, v38
	v_mul_f32_e32 v38, 0xbfb8aa3b, v31
	v_exp_f32_e32 v39, v38
	v_mul_f32_e32 v38, 0xbfb8aa3b, v27
	v_exp_f32_e32 v32, v32
	v_exp_f32_e32 v40, v38
	v_rcp_f32_e32 v38, v35
	v_add_f32_e32 v35, 1.0, v39
	v_add_f32_e32 v32, 1.0, v32
	v_add_f32_e32 v39, 1.0, v40
	v_rcp_f32_e32 v32, v32
	v_rcp_f32_e32 v33, v33
	v_rcp_f32_e32 v34, v34
	v_rcp_f32_e32 v35, v35
	v_rcp_f32_e32 v39, v39

;   DI void operator()(g8::Acc& acc, int pm, int pn, int wr, int wc, int fr, int fq) const {
;     ...
;     const int seg = pn >> 2;
;     const float* rope = (const float*)(p.ws + OFF_ROPE);
;     bf16_t* dst; unsigned ld; int cofs;
;     if (seg < 5) { dst = slot(p, seg + 1); ld = 1024; cofs = seg * 1024; } else { dst = (bf16_t*)p.out; ld = 2048; cofs = 5 * 1024; }
;     const float qs = (seg == 0) ? 0.125f * LOG2E : 1.0f;
;     const float sgn = (fq == 0) ? -1.0f : 1.0f; const bool use = fq < 2;
;     const unsigned col0 = (unsigned)(pn * BM + wc * 64 - cofs);
; #pragma unroll
;     for (int ai = 0; ai < 2; ++ai)
; #pragma unroll
;       for (int m = 0; m < 4; ++m) {
;         const int row0 = pm * BM + ai * HALF + wr * 64 + m * 16, row = row0 + fr;
;         u32x4 w[2];
; #pragma unroll
;         for (int bj = 0; bj < 2; ++bj) {
;           f32x4 o0 = acc[ai][bj][m][0], o1 = acc[ai][bj][m][1];
;           if (seg < 2) {
;             if (bj == 0) {
;               const f32x4 c0 = gld<f32x4>(rope, (unsigned)row * 64u), c1 = gld<f32x4>(rope, (unsigned)row * 64u + 16u), s0 = gld<f32x4>(rope, (unsigned)row * 64u + 32u) * sgn, s1 = gld<f32x4>(rope, (unsigned)row * 64u + 48u) * sgn;
;               f32x4 p0, p1;
; #pragma unroll
;               for (int e = 0; e < 4; ++e) { p0[e] = __shfl_xor(o0[e], 16); p1[e] = __shfl_xor(o1[e], 16); }
;               const f32x4 r0 = o0 * c0 + p0 * s0, r1 = o1 * c1 + p1 * s1;
; #pragma unroll
;               for (int e = 0; e < 4; ++e) { o0[e] = use ? r0[e] : o0[e]; o1[e] = use ? r1[e] : o1[e]; }
;             }
;             o0 = o0 * qs; o1 = o1 * qs;
;           } else if (seg == 3 || seg == 4) {
; #pragma unroll
;             for (int e = 0; e < 4; ++e) {
;               { const float xx = o0[e], y2 = (-2.0f * 0.7978845608028654f * LOG2E) * (xx + 0.044715f * xx * xx * xx); o0[e] = xx * __builtin_amdgcn_rcpf(1.0f + __builtin_amdgcn_exp2f(y2)); }
;               { const float xx = o1[e], y2 = (-2.0f * 0.7978845608028654f * LOG2E) * (xx + 0.044715f * xx * xx * xx); o1[e] = xx * __builtin_amdgcn_rcpf(1.0f + __builtin_amdgcn_exp2f(y2)); }
;             }
;           } else if (seg >= 5) {
; #pragma unroll
;             for (int e = 0; e < 4; ++e) { o0[e] = __builtin_amdgcn_rcpf(1.0f + __builtin_amdgcn_exp2f(-LOG2E * o0[e])); o1[e] = __builtin_amdgcn_rcpf(1.0f + __builtin_amdgcn_exp2f(-LOG2E * o1[e])); }
;           }
.LBB0_300:
	v_cvt_pk_bf16_f32 v236, v24, v25
	v_cvt_pk_bf16_f32 v232, v32, v33
	v_cvt_pk_bf16_f32 v237, v26, v27
	v_cvt_pk_bf16_f32 v238, v28, v29
	v_cvt_pk_bf16_f32 v239, v30, v31
	v_cvt_pk_bf16_f32 v233, v34, v35
	v_cvt_pk_bf16_f32 v234, v36, v37
	v_cvt_pk_bf16_f32 v235, v38, v39
	v_or_b32_e32 v24, s20, v158
	v_lshl_add_u32 v25, v24, s19, v147
	s_and_b64 vcc, exec, s[10:11]
	v_or_b32_e32 v16, 8, v24
	v_lshl_add_u32 v16, v16, s19, v146
	s_mov_b64 s[0:1], -1
	v_cndmask_b32_e64 v240, v25, v16, s[6:7]
	global_store_dwordx4 v240, v[232:235], s[90:91] nt
	global_store_dwordx4 v240, v[236:239], s[90:91] offset:64 nt
	s_cbranch_vccnz .LBB0_308
	s_and_b64 vcc, exec, s[8:9]
	s_cbranch_vccnz .LBB0_305
	s_andn2_b64 vcc, exec, s[88:89]
	v_mov_b32_e32 v19, v15
	v_mov_b32_e32 v18, v14
	v_mov_b32_e32 v17, v13
	v_mov_b32_e32 v16, v12
	v_mov_b32_e32 v23, v11
	v_mov_b32_e32 v22, v10
	v_mov_b32_e32 v21, v9
	v_mov_b32_e32 v20, v8
	s_cbranch_vccnz .LBB0_304
	v_mul_f32_e32 v17, 0xbfb8aa3b, v8
	v_exp_f32_e32 v17, v17
	v_mul_f32_e32 v18, 0xbfb8aa3b, v13
	v_mul_f32_e32 v19, 0xbfb8aa3b, v9
	v_exp_f32_e32 v18, v18
	v_exp_f32_e32 v19, v19
	v_add_f32_e32 v17, 1.0, v17
	v_rcp_f32_e32 v20, v17
	v_add_f32_e32 v17, 1.0, v18
	v_add_f32_e32 v18, 1.0, v19
	v_mul_f32_e32 v19, 0xbfb8aa3b, v14
	v_mul_f32_e32 v21, 0xbfb8aa3b, v10
	v_exp_f32_e32 v19, v19
	v_exp_f32_e32 v22, v21
	v_rcp_f32_e32 v21, v18
	v_mul_f32_e32 v16, 0xbfb8aa3b, v12
	v_add_f32_e32 v18, 1.0, v19
	v_add_f32_e32 v19, 1.0, v22
	v_mul_f32_e32 v22, 0xbfb8aa3b, v15
	v_exp_f32_e32 v23, v22
	v_mul_f32_e32 v22, 0xbfb8aa3b, v11
	v_exp_f32_e32 v16, v16
	v_exp_f32_e32 v24, v22
	v_rcp_f32_e32 v22, v19
	v_add_f32_e32 v19, 1.0, v23
	v_add_f32_e32 v16, 1.0, v16
	v_add_f32_e32 v23, 1.0, v24
	v_rcp_f32_e32 v16, v16
	v_rcp_f32_e32 v17, v17
	v_rcp_f32_e32 v18, v18
	v_rcp_f32_e32 v19, v19
	v_rcp_f32_e32 v23, v23

;   DI void operator()(g8::Acc& acc, int pm, int pn, int wr, int wc, int fr, int fq) const {
;     ...
;     const int seg = pn >> 2;
;     const float* rope = (const float*)(p.ws + OFF_ROPE);
;     bf16_t* dst; unsigned ld; int cofs;
;     if (seg < 5) { dst = slot(p, seg + 1); ld = 1024; cofs = seg * 1024; } else { dst = (bf16_t*)p.out; ld = 2048; cofs = 5 * 1024; }
;     const float qs = (seg == 0) ? 0.125f * LOG2E : 1.0f;
;     const float sgn = (fq == 0) ? -1.0f : 1.0f; const bool use = fq < 2;
;     const unsigned col0 = (unsigned)(pn * BM + wc * 64 - cofs);
; #pragma unroll
;     for (int ai = 0; ai < 2; ++ai)
; #pragma unroll
;       for (int m = 0; m < 4; ++m) {
;         const int row0 = pm * BM + ai * HALF + wr * 64 + m * 16, row = row0 + fr;
;         u32x4 w[2];
; #pragma unroll
;         for (int bj = 0; bj < 2; ++bj) {
;           f32x4 o0 = acc[ai][bj][m][0], o1 = acc[ai][bj][m][1];
;           if (seg < 2) {
;             if (bj == 0) {
;               const f32x4 c0 = gld<f32x4>(rope, (unsigned)row * 64u), c1 = gld<f32x4>(rope, (unsigned)row * 64u + 16u), s0 = gld<f32x4>(rope, (unsigned)row * 64u + 32u) * sgn, s1 = gld<f32x4>(rope, (unsigned)row * 64u + 48u) * sgn;
;               f32x4 p0, p1;
; #pragma unroll
;               for (int e = 0; e < 4; ++e) { p0[e] = __shfl_xor(o0[e], 16); p1[e] = __shfl_xor(o1[e], 16); }
;               const f32x4 r0 = o0 * c0 + p0 * s0, r1 = o1 * c1 + p1 * s1;
; #pragma unroll
;               for (int e = 0; e < 4; ++e) { o0[e] = use ? r0[e] : o0[e]; o1[e] = use ? r1[e] : o1[e]; }
;             }
;             o0 = o0 * qs; o1 = o1 * qs;
;           } else if (seg == 3 || seg == 4) {
; #pragma unroll
;             for (int e = 0; e < 4; ++e) {
;               { const float xx = o0[e], y2 = (-2.0f * 0.7978845608028654f * LOG2E) * (xx + 0.044715f * xx * xx * xx); o0[e] = xx * __builtin_amdgcn_rcpf(1.0f + __builtin_amdgcn_exp2f(y2)); }
;               { const float xx = o1[e], y2 = (-2.0f * 0.7978845608028654f * LOG2E) * (xx + 0.044715f * xx * xx * xx); o1[e] = xx * __builtin_amdgcn_rcpf(1.0f + __builtin_amdgcn_exp2f(y2)); }
;             }
;           } else if (seg >= 5) {
; #pragma unroll
;             for (int e = 0; e < 4; ++e) { o0[e] = __builtin_amdgcn_rcpf(1.0f + __builtin_amdgcn_exp2f(-LOG2E * o0[e])); o1[e] = __builtin_amdgcn_rcpf(1.0f + __builtin_amdgcn_exp2f(-LOG2E * o1[e])); }
;           }
.LBB0_320:
	v_cvt_pk_bf16_f32 v236, v8, v9
	v_cvt_pk_bf16_f32 v232, v16, v17
	v_cvt_pk_bf16_f32 v237, v10, v11
	v_cvt_pk_bf16_f32 v238, v12, v13
	v_cvt_pk_bf16_f32 v239, v14, v15
	v_cvt_pk_bf16_f32 v235, v22, v23
	v_cvt_pk_bf16_f32 v234, v20, v21
	v_cvt_pk_bf16_f32 v233, v18, v19
	v_or_b32_e32 v8, s18, v158
	v_lshl_add_u32 v9, v8, s19, v147
	s_andn2_b64 vcc, exec, s[64:65]
	v_or_b32_e32 v0, 8, v8
	v_lshl_add_u32 v0, v0, s19, v146
	s_mov_b64 s[0:1], -1
	v_cndmask_b32_e64 v240, v9, v0, s[6:7]
	global_store_dwordx4 v240, v[232:235], s[90:91] nt
	global_store_dwordx4 v240, v[236:239], s[90:91] offset:64 nt
	s_cbranch_vccnz .LBB0_153
	s_andn2_b64 vcc, exec, s[50:51]
	s_cbranch_vccnz .LBB0_152
	s_barrier
	s_branch .LBB0_152

; template <class T> DI T gld_nt(const void* base, unsigned off) { return __builtin_nontemporal_load((const T*)((const char*)base + off)); }
; DI u32x4 pk8(const f32x4& a, const f32x4& b) { u32x4 w; w.x = pk2(a[0], a[1]); w.y = pk2(a[2], a[3]); w.z = pk2(b[0], b[1]); w.w = pk2(b[2], b[3]); return w; }
; DI void unpk8(const u32x4& w, f32x4& a, f32x4& b) { a[0] = bf_lo(w.x); a[1] = bf_hi(w.x); a[2] = bf_lo(w.y); a[3] = bf_hi(w.y); b[0] = bf_lo(w.z); b[1] = bf_hi(w.z); b[2] = bf_lo(w.w); b[3] = bf_hi(w.w); }
; template <bool NT = false> DI void st_rows16(void* base, unsigned pitch_b, unsigned row0, unsigned col0, int fr, int fq, const u32x4& w0, const u32x4& w1) {
;   u32x4 x;
; #pragma unroll
;   for (int e = 0; e < 4; ++e) x[e] = (unsigned)__builtin_amdgcn_update_dpp(0, (int)w1[e], 0x128  , 0xf, 0xf, false);
;   const bool hi = fr >= 8;
;   u32x4 pa, pb;
; #pragma unroll
;   for (int e = 0; e < 4; ++e) { pa[e] = hi ? x[e] : w0[e]; pb[e] = hi ? w0[e] : x[e]; }
;   const unsigned ra = row0 + (unsigned)(fr & 7), ca = col0 + 8u * fq + (hi ? 32u : 0u), cb = col0 + 8u * fq + (hi ? 0u : 32u);
;   if (NT) { __builtin_nontemporal_store(pa, (u32x4*)((char*)base + (ra * pitch_b + ca * 2u))); __builtin_nontemporal_store(pb, (u32x4*)((char*)base + ((ra + 8u) * pitch_b + cb * 2u))); }
;   else { gst<u32x4>(base, ra * pitch_b + ca * 2u, pa); gst<u32x4>(base, (ra + 8u) * pitch_b + cb * 2u, pb); }
; }
;   DI void operator()(g8::Acc& acc, int pm, int pn, int wr, int wc, int fr, int fq) const {
;     ...
;     for (int ai = 0; ai < 2; ++ai)
; #pragma unroll
;       for (int m = 0; m < 4; ++m) {
;         const int row0 = pm * BM + ai * HALF + wr * 64 + m * 16, row = row0 + fr; u32x4 wv[2];
; #pragma unroll
;         for (int bj = 0; bj < 2; ++bj) {
;           const int col8 = pn * BM + wc * 64 + bj * 32 + fq * 8; const unsigned go = ((unsigned)row * 2048u + (unsigned)(1024 + col8)) * 2u;
;           f32x4 s0, s1; unpk8(gld_nt<u32x4>(gates, go), s0, s1);
; #pragma unroll
;           for (int e = 0; e < 4; ++e) { s0[e] = fmaxf(s0[e], 1e-30f); s1[e] = fmaxf(s1[e], 1e-30f); }
;           wv[bj] = pk8(acc[ai][bj][m][0] * s0, acc[ai][bj][m][1] * s1);
;         }
;         st_rows16(dst, DM * 2u, (unsigned)row0, (unsigned)(pn * BM + wc * 64), fr, fq, wv[0], wv[1]);
.LBB0_485:
	s_and_b64 vcc, exec, s[52:53]
	s_cbranch_vccz .LBB0_493
	s_lshl_b32 s0, s58, 8
	s_add_i32 s0, s0, s15
	v_lshl_add_u32 v153, s33, 9, v143
	v_or_b32_e32 v151, s0, v140
	v_lshl_add_u32 v151, v151, 12, v153
	global_load_dwordx4 v[154:157], v151, s[72:73] nt
	global_load_dwordx4 v[158:161], v151, s[72:73] offset:64 nt
	v_lshl_or_b32 v151, s33, 8, v145
	v_or_b32_e32 v152, v151, v146
	v_or_b32_e32 v151, v151, v147
	v_lshlrev_b32_e32 v152, 1, v152
	v_lshl_add_u32 v151, v151, 1, v150
	s_or_b32 s1, s0, 16
	s_waitcnt vmcnt(0)
	v_lshlrev_b32_e32 v162, 16, v154
	v_and_b32_e32 v154, 0xffff0000, v154
	v_lshlrev_b32_e32 v163, 16, v155
	v_and_b32_e32 v155, 0xffff0000, v155
	v_lshlrev_b32_e32 v164, 16, v156
	v_and_b32_e32 v156, 0xffff0000, v156
	v_lshlrev_b32_e32 v165, 16, v157
	v_and_b32_e32 v157, 0xffff0000, v157
	v_lshlrev_b32_e32 v166, 16, v158
	v_and_b32_e32 v158, 0xffff0000, v158
	v_lshlrev_b32_e32 v167, 16, v159
	v_and_b32_e32 v159, 0xffff0000, v159
	v_lshlrev_b32_e32 v168, 16, v160
	v_and_b32_e32 v160, 0xffff0000, v160
	v_lshlrev_b32_e32 v169, 16, v161
	v_and_b32_e32 v161, 0xffff0000, v161
	v_max_f32_e32 v162, v162, v162
	v_max_f32_e32 v164, v164, v164
	v_max_f32_e32 v174, v154, v154
	v_max_f32_e32 v175, v156, v156
	v_max_f32_e32 v163, v163, v163
	v_max_f32_e32 v165, v165, v165
	v_max_f32_e32 v176, v155, v155
	v_max_f32_e32 v177, v157, v157
	v_max_f32_e32 v166, v166, v166
	v_max_f32_e32 v168, v168, v168
	v_max_f32_e32 v178, v158, v158
	v_max_f32_e32 v179, v160, v160
	v_max_f32_e32 v167, v167, v167
	v_max_f32_e32 v169, v169, v169
	v_max_f32_e32 v180, v159, v159
	v_max_f32_e32 v181, v161, v161
	v_max_f32_e32 v154, 0xda24260, v162
	v_max_f32_e32 v156, 0xda24260, v164
	v_max_f32_e32 v155, 0xda24260, v174
	v_max_f32_e32 v157, 0xda24260, v175
	v_max_f32_e32 v158, 0xda24260, v163
	v_max_f32_e32 v160, 0xda24260, v165
	v_max_f32_e32 v159, 0xda24260, v176
	v_max_f32_e32 v161, 0xda24260, v177
	v_max_f32_e32 v162, 0xda24260, v166
	v_max_f32_e32 v164, 0xda24260, v168
	v_max_f32_e32 v163, 0xda24260, v178
	v_max_f32_e32 v165, 0xda24260, v179
	v_max_f32_e32 v166, 0xda24260, v167
	v_max_f32_e32 v168, 0xda24260, v169
	v_max_f32_e32 v167, 0xda24260, v180
	v_max_f32_e32 v169, 0xda24260, v181
	v_pk_mul_f32 v[158:159], v[126:127], v[158:159]
	v_pk_mul_f32 v[154:155], v[124:125], v[154:155]
	v_pk_mul_f32 v[160:161], v[122:123], v[160:161]
	v_pk_mul_f32 v[156:157], v[120:121], v[156:157]
	v_pk_mul_f32 v[166:167], v[94:95], v[166:167]
	v_pk_mul_f32 v[162:163], v[92:93], v[162:163]
	v_pk_mul_f32 v[168:169], v[90:91], v[168:169]
	v_pk_mul_f32 v[164:165], v[88:89], v[164:165]
	v_cvt_pk_bf16_f32 v232, v154, v155
	v_cvt_pk_bf16_f32 v233, v158, v159
	v_cvt_pk_bf16_f32 v234, v156, v157
	v_cvt_pk_bf16_f32 v235, v160, v161
	v_cvt_pk_bf16_f32 v236, v162, v163
	v_cvt_pk_bf16_f32 v237, v166, v167
	v_cvt_pk_bf16_f32 v238, v164, v165
	v_cvt_pk_bf16_f32 v239, v168, v169
	v_or_b32_e32 v162, s0, v144
	v_lshlrev_b32_e32 v162, 11, v162
	v_add_u32_e32 v163, v152, v162
	v_add_u32_e32 v154, v151, v162
	v_cndmask_b32_e64 v240, v163, v154, s[4:5]
	global_store_dwordx4 v240, v[232:235], s[12:13]
	global_store_dwordx4 v240, v[236:239], s[12:13] offset:64
	v_or_b32_e32 v154, s1, v140
	v_lshl_add_u32 v158, v154, 12, v153
	global_load_dwordx4 v[154:157], v158, s[72:73] nt
	s_nop 0
	global_load_dwordx4 v[158:161], v158, s[72:73] offset:64 nt
	s_waitcnt vmcnt(1)
	v_lshlrev_b32_e32 v162, 16, v154
	v_and_b32_e32 v154, 0xffff0000, v154
	v_lshlrev_b32_e32 v163, 16, v155
	v_and_b32_e32 v155, 0xffff0000, v155
	v_lshlrev_b32_e32 v164, 16, v156
	v_and_b32_e32 v156, 0xffff0000, v156
	v_lshlrev_b32_e32 v165, 16, v157
	v_and_b32_e32 v157, 0xffff0000, v157
	s_waitcnt vmcnt(0)
	v_lshlrev_b32_e32 v166, 16, v158
	v_and_b32_e32 v158, 0xffff0000, v158
	v_lshlrev_b32_e32 v167, 16, v159
	v_and_b32_e32 v159, 0xffff0000, v159
	v_lshlrev_b32_e32 v168, 16, v160
	v_and_b32_e32 v160, 0xffff0000, v160
	v_lshlrev_b32_e32 v169, 16, v161
	v_and_b32_e32 v161, 0xffff0000, v161
	v_max_f32_e32 v162, v162, v162
	v_max_f32_e32 v164, v164, v164
	v_max_f32_e32 v174, v154, v154
	v_max_f32_e32 v175, v156, v156
	v_max_f32_e32 v163, v163, v163
	v_max_f32_e32 v165, v165, v165
	v_max_f32_e32 v176, v155, v155
	v_max_f32_e32 v177, v157, v157
	v_max_f32_e32 v166, v166, v166
	v_max_f32_e32 v168, v168, v168
	v_max_f32_e32 v178, v158, v158
	v_max_f32_e32 v179, v160, v160
	v_max_f32_e32 v167, v167, v167
	v_max_f32_e32 v169, v169, v169
	v_max_f32_e32 v180, v159, v159
	v_max_f32_e32 v181, v161, v161
	v_max_f32_e32 v154, 0xda24260, v162
	v_max_f32_e32 v156, 0xda24260, v164
	v_max_f32_e32 v155, 0xda24260, v174
	v_max_f32_e32 v157, 0xda24260, v175
	v_max_f32_e32 v158, 0xda24260, v163
	v_max_f32_e32 v160, 0xda24260, v165
	v_max_f32_e32 v159, 0xda24260, v176
	v_max_f32_e32 v161, 0xda24260, v177
	v_max_f32_e32 v162, 0xda24260, v166
	v_max_f32_e32 v164, 0xda24260, v168
	v_max_f32_e32 v163, 0xda24260, v178
	v_max_f32_e32 v165, 0xda24260, v179
	v_max_f32_e32 v166, 0xda24260, v167
	v_max_f32_e32 v168, 0xda24260, v169
	v_max_f32_e32 v167, 0xda24260, v180
	v_max_f32_e32 v169, 0xda24260, v181
	v_pk_mul_f32 v[158:159], v[118:119], v[158:159]
	v_pk_mul_f32 v[154:155], v[116:117], v[154:155]
	v_pk_mul_f32 v[160:161], v[114:115], v[160:161]
	v_pk_mul_f32 v[156:157], v[112:113], v[156:157]
	v_pk_mul_f32 v[166:167], v[86:87], v[166:167]
	v_pk_mul_f32 v[162:163], v[84:85], v[162:163]
	v_pk_mul_f32 v[168:169], v[82:83], v[168:169]
	v_pk_mul_f32 v[164:165], v[80:81], v[164:165]
	v_cvt_pk_bf16_f32 v232, v154, v155
	v_cvt_pk_bf16_f32 v233, v158, v159
	v_cvt_pk_bf16_f32 v234, v156, v157
	v_cvt_pk_bf16_f32 v235, v160, v161
	v_cvt_pk_bf16_f32 v236, v162, v163
	v_cvt_pk_bf16_f32 v237, v166, v167
	v_cvt_pk_bf16_f32 v238, v164, v165
	v_cvt_pk_bf16_f32 v239, v168, v169
	v_or_b32_e32 v162, s1, v144
	v_lshlrev_b32_e32 v162, 11, v162
	v_add_u32_e32 v163, v152, v162
	s_or_b32 s1, s0, 32
	v_add_u32_e32 v154, v151, v162
	v_cndmask_b32_e64 v240, v163, v154, s[4:5]
	global_store_dwordx4 v240, v[232:235], s[12:13]
	global_store_dwordx4 v240, v[236:239], s[12:13] offset:64
	v_or_b32_e32 v154, s1, v140
	v_lshl_add_u32 v158, v154, 12, v153
	global_load_dwordx4 v[154:157], v158, s[72:73] nt
	s_nop 0
	global_load_dwordx4 v[158:161], v158, s[72:73] offset:64 nt
	s_waitcnt vmcnt(1)
; template <class T> DI T gld_nt(const void* base, unsigned off) { return __builtin_nontemporal_load((const T*)((const char*)base + off)); }
; DI u32x4 pk8(const f32x4& a, const f32x4& b) { u32x4 w; w.x = pk2(a[0], a[1]); w.y = pk2(a[2], a[3]); w.z = pk2(b[0], b[1]); w.w = pk2(b[2], b[3]); return w; }
; DI void unpk8(const u32x4& w, f32x4& a, f32x4& b) { a[0] = bf_lo(w.x); a[1] = bf_hi(w.x); a[2] = bf_lo(w.y); a[3] = bf_hi(w.y); b[0] = bf_lo(w.z); b[1] = bf_hi(w.z); b[2] = bf_lo(w.w); b[3] = bf_hi(w.w); }
; template <bool NT = false> DI void st_rows16(void* base, unsigned pitch_b, unsigned row0, unsigned col0, int fr, int fq, const u32x4& w0, const u32x4& w1) {
;   u32x4 x;
; #pragma unroll
;   for (int e = 0; e < 4; ++e) x[e] = (unsigned)__builtin_amdgcn_update_dpp(0, (int)w1[e], 0x128  , 0xf, 0xf, false);
;   const bool hi = fr >= 8;
;   u32x4 pa, pb;
; #pragma unroll
;   for (int e = 0; e < 4; ++e) { pa[e] = hi ? x[e] : w0[e]; pb[e] = hi ? w0[e] : x[e]; }
;   const unsigned ra = row0 + (unsigned)(fr & 7), ca = col0 + 8u * fq + (hi ? 32u : 0u), cb = col0 + 8u * fq + (hi ? 0u : 32u);
;   if (NT) { __builtin_nontemporal_store(pa, (u32x4*)((char*)base + (ra * pitch_b + ca * 2u))); __builtin_nontemporal_store(pb, (u32x4*)((char*)base + ((ra + 8u) * pitch_b + cb * 2u))); }
;   else { gst<u32x4>(base, ra * pitch_b + ca * 2u, pa); gst<u32x4>(base, (ra + 8u) * pitch_b + cb * 2u, pb); }
; }
;   DI void operator()(g8::Acc& acc, int pm, int pn, int wr, int wc, int fr, int fq) const {
;     ...
;     for (int ai = 0; ai < 2; ++ai)
; #pragma unroll
;       for (int m = 0; m < 4; ++m) {
;         const int row0 = pm * BM + ai * HALF + wr * 64 + m * 16, row = row0 + fr; u32x4 wv[2];
; #pragma unroll
;         for (int bj = 0; bj < 2; ++bj) {
;           const int col8 = pn * BM + wc * 64 + bj * 32 + fq * 8; const unsigned go = ((unsigned)row * 2048u + (unsigned)(1024 + col8)) * 2u;
;           f32x4 s0, s1; unpk8(gld_nt<u32x4>(gates, go), s0, s1);
; #pragma unroll
;           for (int e = 0; e < 4; ++e) { s0[e] = fmaxf(s0[e], 1e-30f); s1[e] = fmaxf(s1[e], 1e-30f); }
;           wv[bj] = pk8(acc[ai][bj][m][0] * s0, acc[ai][bj][m][1] * s1);
;         }
;         st_rows16(dst, DM * 2u, (unsigned)row0, (unsigned)(pn * BM + wc * 64), fr, fq, wv[0], wv[1]);
	v_lshlrev_b32_e32 v162, 16, v154
	v_and_b32_e32 v154, 0xffff0000, v154
	v_lshlrev_b32_e32 v163, 16, v155
	v_and_b32_e32 v155, 0xffff0000, v155
	v_lshlrev_b32_e32 v164, 16, v156
	v_and_b32_e32 v156, 0xffff0000, v156
	v_lshlrev_b32_e32 v165, 16, v157
	v_and_b32_e32 v157, 0xffff0000, v157
	s_waitcnt vmcnt(0)
	v_lshlrev_b32_e32 v166, 16, v158
	v_and_b32_e32 v158, 0xffff0000, v158
	v_lshlrev_b32_e32 v167, 16, v159
	v_and_b32_e32 v159, 0xffff0000, v159
	v_lshlrev_b32_e32 v168, 16, v160
	v_and_b32_e32 v160, 0xffff0000, v160
	v_lshlrev_b32_e32 v169, 16, v161
	v_and_b32_e32 v161, 0xffff0000, v161
	v_max_f32_e32 v162, v162, v162
	v_max_f32_e32 v164, v164, v164
	v_max_f32_e32 v174, v154, v154
	v_max_f32_e32 v175, v156, v156
	v_max_f32_e32 v163, v163, v163
	v_max_f32_e32 v165, v165, v165
	v_max_f32_e32 v176, v155, v155
	v_max_f32_e32 v177, v157, v157
	v_max_f32_e32 v166, v166, v166
	v_max_f32_e32 v168, v168, v168
	v_max_f32_e32 v178, v158, v158
	v_max_f32_e32 v179, v160, v160
	v_max_f32_e32 v167, v167, v167
	v_max_f32_e32 v169, v169, v169
	v_max_f32_e32 v180, v159, v159
	v_max_f32_e32 v181, v161, v161
	v_max_f32_e32 v154, 0xda24260, v162
	v_max_f32_e32 v156, 0xda24260, v164
	v_max_f32_e32 v155, 0xda24260, v174
	v_max_f32_e32 v157, 0xda24260, v175
	v_max_f32_e32 v158, 0xda24260, v163
	v_max_f32_e32 v160, 0xda24260, v165
	v_max_f32_e32 v159, 0xda24260, v176
	v_max_f32_e32 v161, 0xda24260, v177
	v_max_f32_e32 v162, 0xda24260, v166
	v_max_f32_e32 v164, 0xda24260, v168
	v_max_f32_e32 v163, 0xda24260, v178
	v_max_f32_e32 v165, 0xda24260, v179
	v_max_f32_e32 v166, 0xda24260, v167
	v_max_f32_e32 v168, 0xda24260, v169
	v_max_f32_e32 v167, 0xda24260, v180
	v_max_f32_e32 v169, 0xda24260, v181
	v_pk_mul_f32 v[158:159], v[110:111], v[158:159]
	v_pk_mul_f32 v[154:155], v[108:109], v[154:155]
	v_pk_mul_f32 v[160:161], v[106:107], v[160:161]
	v_pk_mul_f32 v[156:157], v[104:105], v[156:157]
	v_pk_mul_f32 v[166:167], v[78:79], v[166:167]
	v_pk_mul_f32 v[162:163], v[76:77], v[162:163]
	v_pk_mul_f32 v[168:169], v[74:75], v[168:169]
	v_pk_mul_f32 v[164:165], v[72:73], v[164:165]
	v_cvt_pk_bf16_f32 v232, v154, v155
	v_cvt_pk_bf16_f32 v233, v158, v159
	v_cvt_pk_bf16_f32 v234, v156, v157
	v_cvt_pk_bf16_f32 v235, v160, v161
	v_cvt_pk_bf16_f32 v236, v162, v163
	v_cvt_pk_bf16_f32 v237, v166, v167
	v_cvt_pk_bf16_f32 v238, v164, v165
	v_cvt_pk_bf16_f32 v239, v168, v169
	v_or_b32_e32 v162, s1, v144
	v_lshlrev_b32_e32 v162, 11, v162
	v_add_u32_e32 v163, v152, v162
	s_or_b32 s1, s0, 48
	v_add_u32_e32 v154, v151, v162
	v_cndmask_b32_e64 v240, v163, v154, s[4:5]
	global_store_dwordx4 v240, v[232:235], s[12:13]
	global_store_dwordx4 v240, v[236:239], s[12:13] offset:64
	v_or_b32_e32 v154, s1, v140
	v_lshl_add_u32 v158, v154, 12, v153
	global_load_dwordx4 v[154:157], v158, s[72:73] nt
	s_nop 0
	global_load_dwordx4 v[158:161], v158, s[72:73] offset:64 nt
	s_waitcnt vmcnt(1)
	v_lshlrev_b32_e32 v162, 16, v154
	v_and_b32_e32 v154, 0xffff0000, v154
	v_lshlrev_b32_e32 v163, 16, v155
	v_and_b32_e32 v155, 0xffff0000, v155
	v_lshlrev_b32_e32 v164, 16, v156
	v_lshlrev_b32_e32 v165, 16, v157
	v_and_b32_e32 v157, 0xffff0000, v157
	s_waitcnt vmcnt(0)
	v_lshlrev_b32_e32 v166, 16, v158
	v_and_b32_e32 v158, 0xffff0000, v158
	v_lshlrev_b32_e32 v168, 16, v160
	v_and_b32_e32 v160, 0xffff0000, v160
	v_lshlrev_b32_e32 v169, 16, v161
	v_and_b32_e32 v161, 0xffff0000, v161
	v_and_b32_e32 v156, 0xffff0000, v156
	v_lshlrev_b32_e32 v167, 16, v159
	v_and_b32_e32 v159, 0xffff0000, v159
	v_max_f32_e32 v162, v162, v162
	v_max_f32_e32 v164, v164, v164
	v_max_f32_e32 v173, v154, v154
	v_max_f32_e32 v163, v163, v163
	v_max_f32_e32 v165, v165, v165
	v_max_f32_e32 v175, v155, v155
	v_max_f32_e32 v176, v157, v157
	v_max_f32_e32 v166, v166, v166
	v_max_f32_e32 v168, v168, v168
	v_max_f32_e32 v177, v158, v158
	v_max_f32_e32 v178, v160, v160
	v_max_f32_e32 v169, v169, v169
	v_max_f32_e32 v180, v161, v161
	v_max_f32_e32 v174, v156, v156
	v_max_f32_e32 v167, v167, v167
	v_max_f32_e32 v179, v159, v159
	v_max_f32_e32 v154, 0xda24260, v162
	v_max_f32_e32 v156, 0xda24260, v164
	v_max_f32_e32 v155, 0xda24260, v173
	v_max_f32_e32 v158, 0xda24260, v163
	v_max_f32_e32 v160, 0xda24260, v165
	v_max_f32_e32 v159, 0xda24260, v175
	v_max_f32_e32 v161, 0xda24260, v176
	v_max_f32_e32 v162, 0xda24260, v166
	v_max_f32_e32 v164, 0xda24260, v168
	v_max_f32_e32 v163, 0xda24260, v177
	v_max_f32_e32 v165, 0xda24260, v178
	v_max_f32_e32 v168, 0xda24260, v169
	v_max_f32_e32 v169, 0xda24260, v180
	v_max_f32_e32 v157, 0xda24260, v174
	v_max_f32_e32 v166, 0xda24260, v167
	v_max_f32_e32 v167, 0xda24260, v179
	v_pk_mul_f32 v[158:159], v[102:103], v[158:159]
	v_pk_mul_f32 v[154:155], v[100:101], v[154:155]
	v_pk_mul_f32 v[160:161], v[98:99], v[160:161]
	v_pk_mul_f32 v[162:163], v[68:69], v[162:163]
	v_pk_mul_f32 v[168:169], v[66:67], v[168:169]
	v_pk_mul_f32 v[164:165], v[64:65], v[164:165]
	v_pk_mul_f32 v[156:157], v[96:97], v[156:157]
	v_pk_mul_f32 v[166:167], v[70:71], v[166:167]
	v_cvt_pk_bf16_f32 v232, v154, v155
	v_cvt_pk_bf16_f32 v233, v158, v159
	v_cvt_pk_bf16_f32 v235, v160, v161
	v_cvt_pk_bf16_f32 v236, v162, v163
	v_cvt_pk_bf16_f32 v238, v164, v165
	v_cvt_pk_bf16_f32 v239, v168, v169
	v_cvt_pk_bf16_f32 v234, v156, v157
	v_cvt_pk_bf16_f32 v237, v166, v167
	v_or_b32_e32 v162, s1, v144
	v_lshlrev_b32_e32 v162, 11, v162
	v_add_u32_e32 v163, v152, v162
	s_add_i32 s1, s0, 0x80
	v_add_u32_e32 v154, v151, v162
	v_cndmask_b32_e64 v240, v163, v154, s[4:5]
	global_store_dwordx4 v240, v[232:235], s[12:13]
	global_store_dwordx4 v240, v[236:239], s[12:13] offset:64
	v_or_b32_e32 v154, s1, v140
	s_nop 0
	v_lshl_add_u32 v158, v154, 12, v153
	global_load_dwordx4 v[154:157], v158, s[72:73] nt
	s_nop 0
	global_load_dwordx4 v[158:161], v158, s[72:73] offset:64 nt
	s_waitcnt vmcnt(1)
; template <class T> DI T gld_nt(const void* base, unsigned off) { return __builtin_nontemporal_load((const T*)((const char*)base + off)); }
; DI u32x4 pk8(const f32x4& a, const f32x4& b) { u32x4 w; w.x = pk2(a[0], a[1]); w.y = pk2(a[2], a[3]); w.z = pk2(b[0], b[1]); w.w = pk2(b[2], b[3]); return w; }
; DI void unpk8(const u32x4& w, f32x4& a, f32x4& b) { a[0] = bf_lo(w.x); a[1] = bf_hi(w.x); a[2] = bf_lo(w.y); a[3] = bf_hi(w.y); b[0] = bf_lo(w.z); b[1] = bf_hi(w.z); b[2] = bf_lo(w.w); b[3] = bf_hi(w.w); }
; template <bool NT = false> DI void st_rows16(void* base, unsigned pitch_b, unsigned row0, unsigned col0, int fr, int fq, const u32x4& w0, const u32x4& w1) {
;   u32x4 x;
; #pragma unroll
;   for (int e = 0; e < 4; ++e) x[e] = (unsigned)__builtin_amdgcn_update_dpp(0, (int)w1[e], 0x128  , 0xf, 0xf, false);
;   const bool hi = fr >= 8;
;   u32x4 pa, pb;
; #pragma unroll
;   for (int e = 0; e < 4; ++e) { pa[e] = hi ? x[e] : w0[e]; pb[e] = hi ? w0[e] : x[e]; }
;   const unsigned ra = row0 + (unsigned)(fr & 7), ca = col0 + 8u * fq + (hi ? 32u : 0u), cb = col0 + 8u * fq + (hi ? 0u : 32u);
;   if (NT) { __builtin_nontemporal_store(pa, (u32x4*)((char*)base + (ra * pitch_b + ca * 2u))); __builtin_nontemporal_store(pb, (u32x4*)((char*)base + ((ra + 8u) * pitch_b + cb * 2u))); }
;   else { gst<u32x4>(base, ra * pitch_b + ca * 2u, pa); gst<u32x4>(base, (ra + 8u) * pitch_b + cb * 2u, pb); }
; }
;   DI void operator()(g8::Acc& acc, int pm, int pn, int wr, int wc, int fr, int fq) const {
;     ...
;     for (int ai = 0; ai < 2; ++ai)
; #pragma unroll
;       for (int m = 0; m < 4; ++m) {
;         const int row0 = pm * BM + ai * HALF + wr * 64 + m * 16, row = row0 + fr; u32x4 wv[2];
; #pragma unroll
;         for (int bj = 0; bj < 2; ++bj) {
;           const int col8 = pn * BM + wc * 64 + bj * 32 + fq * 8; const unsigned go = ((unsigned)row * 2048u + (unsigned)(1024 + col8)) * 2u;
;           f32x4 s0, s1; unpk8(gld_nt<u32x4>(gates, go), s0, s1);
; #pragma unroll
;           for (int e = 0; e < 4; ++e) { s0[e] = fmaxf(s0[e], 1e-30f); s1[e] = fmaxf(s1[e], 1e-30f); }
;           wv[bj] = pk8(acc[ai][bj][m][0] * s0, acc[ai][bj][m][1] * s1);
;         }
;         st_rows16(dst, DM * 2u, (unsigned)row0, (unsigned)(pn * BM + wc * 64), fr, fq, wv[0], wv[1]);
	v_lshlrev_b32_e32 v162, 16, v154
	v_and_b32_e32 v154, 0xffff0000, v154
	v_lshlrev_b32_e32 v163, 16, v155
	v_lshlrev_b32_e32 v164, 16, v156
	v_and_b32_e32 v156, 0xffff0000, v156
	s_waitcnt vmcnt(0)
	v_lshlrev_b32_e32 v166, 16, v158
	v_and_b32_e32 v158, 0xffff0000, v158
	v_lshlrev_b32_e32 v167, 16, v159
	v_and_b32_e32 v159, 0xffff0000, v159
	v_and_b32_e32 v155, 0xffff0000, v155
	v_lshlrev_b32_e32 v165, 16, v157
	v_and_b32_e32 v157, 0xffff0000, v157
	v_lshlrev_b32_e32 v168, 16, v160
	v_and_b32_e32 v160, 0xffff0000, v160
	v_max_f32_e32 v162, v162, v162
	v_max_f32_e32 v164, v164, v164
	v_max_f32_e32 v171, v154, v154
	v_max_f32_e32 v172, v156, v156
	v_max_f32_e32 v163, v163, v163
	v_max_f32_e32 v166, v166, v166
	v_max_f32_e32 v175, v158, v158
	v_max_f32_e32 v167, v167, v167
	v_max_f32_e32 v177, v159, v159
	v_lshlrev_b32_e32 v169, 16, v161
	v_and_b32_e32 v161, 0xffff0000, v161
	v_max_f32_e32 v165, v165, v165
	v_max_f32_e32 v173, v155, v155
	v_max_f32_e32 v174, v157, v157
	v_max_f32_e32 v168, v168, v168
	v_max_f32_e32 v176, v160, v160
	v_max_f32_e32 v154, 0xda24260, v162
	v_max_f32_e32 v156, 0xda24260, v164
	v_max_f32_e32 v155, 0xda24260, v171
	v_max_f32_e32 v157, 0xda24260, v172
	v_max_f32_e32 v158, 0xda24260, v163
	v_max_f32_e32 v162, 0xda24260, v166
	v_max_f32_e32 v163, 0xda24260, v175
	v_max_f32_e32 v166, 0xda24260, v167
	v_max_f32_e32 v167, 0xda24260, v177
	v_max_f32_e32 v169, v169, v169
	v_max_f32_e32 v178, v161, v161
	v_max_f32_e32 v160, 0xda24260, v165
	v_max_f32_e32 v159, 0xda24260, v173
	v_max_f32_e32 v164, 0xda24260, v168
	v_max_f32_e32 v165, 0xda24260, v176
	v_pk_mul_f32 v[154:155], v[60:61], v[154:155]
	v_pk_mul_f32 v[156:157], v[56:57], v[156:157]
	v_pk_mul_f32 v[166:167], v[30:31], v[166:167]
	v_pk_mul_f32 v[162:163], v[28:29], v[162:163]
	v_max_f32_e32 v161, 0xda24260, v174
	v_max_f32_e32 v168, 0xda24260, v169
	v_max_f32_e32 v169, 0xda24260, v178
	v_pk_mul_f32 v[158:159], v[62:63], v[158:159]
	v_pk_mul_f32 v[164:165], v[24:25], v[164:165]
	v_cvt_pk_bf16_f32 v232, v154, v155
	v_cvt_pk_bf16_f32 v234, v156, v157
	v_cvt_pk_bf16_f32 v236, v162, v163
	v_cvt_pk_bf16_f32 v237, v166, v167
	v_pk_mul_f32 v[160:161], v[58:59], v[160:161]
	v_pk_mul_f32 v[168:169], v[26:27], v[168:169]
	v_cvt_pk_bf16_f32 v233, v158, v159
	v_cvt_pk_bf16_f32 v238, v164, v165
	v_cvt_pk_bf16_f32 v235, v160, v161
	v_cvt_pk_bf16_f32 v239, v168, v169
	v_or_b32_e32 v162, s1, v144
	v_lshlrev_b32_e32 v162, 11, v162
	v_add_u32_e32 v163, v152, v162
	s_add_i32 s1, s0, 0x90
	s_nop 0
	v_add_u32_e32 v154, v151, v162
	v_cndmask_b32_e64 v240, v163, v154, s[4:5]
	global_store_dwordx4 v240, v[232:235], s[12:13]
	global_store_dwordx4 v240, v[236:239], s[12:13] offset:64
	v_or_b32_e32 v154, s1, v140
	s_nop 0
	v_lshl_add_u32 v158, v154, 12, v153
	global_load_dwordx4 v[154:157], v158, s[72:73] nt
	s_nop 0
	global_load_dwordx4 v[158:161], v158, s[72:73] offset:64 nt
	s_waitcnt vmcnt(1)
	v_lshlrev_b32_e32 v162, 16, v154
	v_and_b32_e32 v154, 0xffff0000, v154
	v_lshlrev_b32_e32 v163, 16, v155
	s_waitcnt vmcnt(0)
	v_lshlrev_b32_e32 v166, 16, v158
	v_and_b32_e32 v158, 0xffff0000, v158
	v_and_b32_e32 v155, 0xffff0000, v155
	v_lshlrev_b32_e32 v164, 16, v156
	v_lshlrev_b32_e32 v165, 16, v157
	v_lshlrev_b32_e32 v168, 16, v160
	v_and_b32_e32 v160, 0xffff0000, v160
	v_max_f32_e32 v162, v162, v162
	v_max_f32_e32 v170, v154, v154
	v_max_f32_e32 v163, v163, v163
	v_max_f32_e32 v166, v166, v166
	v_max_f32_e32 v174, v158, v158
	v_and_b32_e32 v156, 0xffff0000, v156
	v_and_b32_e32 v157, 0xffff0000, v157
	v_lshlrev_b32_e32 v167, 16, v159
	v_and_b32_e32 v159, 0xffff0000, v159
	v_lshlrev_b32_e32 v169, 16, v161
	v_and_b32_e32 v161, 0xffff0000, v161
	v_max_f32_e32 v164, v164, v164
	v_max_f32_e32 v165, v165, v165
	v_max_f32_e32 v172, v155, v155
	v_max_f32_e32 v168, v168, v168
	v_max_f32_e32 v175, v160, v160
	v_max_f32_e32 v154, 0xda24260, v162
	v_max_f32_e32 v155, 0xda24260, v170
	v_max_f32_e32 v158, 0xda24260, v163
	v_max_f32_e32 v162, 0xda24260, v166
	v_max_f32_e32 v163, 0xda24260, v174
	v_max_f32_e32 v171, v156, v156
	v_max_f32_e32 v173, v157, v157
	v_max_f32_e32 v167, v167, v167
	v_max_f32_e32 v169, v169, v169
	v_max_f32_e32 v176, v159, v159
	v_max_f32_e32 v177, v161, v161
	v_max_f32_e32 v156, 0xda24260, v164
	v_max_f32_e32 v160, 0xda24260, v165
	v_max_f32_e32 v159, 0xda24260, v172
	v_max_f32_e32 v164, 0xda24260, v168
	v_max_f32_e32 v165, 0xda24260, v175
	v_pk_mul_f32 v[154:155], v[52:53], v[154:155]
	v_pk_mul_f32 v[162:163], v[20:21], v[162:163]
	v_max_f32_e32 v157, 0xda24260, v171
	v_max_f32_e32 v161, 0xda24260, v173
	v_max_f32_e32 v166, 0xda24260, v167
	v_max_f32_e32 v168, 0xda24260, v169
	v_max_f32_e32 v167, 0xda24260, v176
	v_max_f32_e32 v169, 0xda24260, v177
	v_pk_mul_f32 v[158:159], v[54:55], v[158:159]
	v_pk_mul_f32 v[164:165], v[16:17], v[164:165]
	v_cvt_pk_bf16_f32 v232, v154, v155
	v_cvt_pk_bf16_f32 v236, v162, v163
	v_pk_mul_f32 v[160:161], v[50:51], v[160:161]
	v_pk_mul_f32 v[156:157], v[48:49], v[156:157]
	v_pk_mul_f32 v[166:167], v[22:23], v[166:167]
	v_pk_mul_f32 v[168:169], v[18:19], v[168:169]
	v_cvt_pk_bf16_f32 v233, v158, v159
	v_cvt_pk_bf16_f32 v238, v164, v165
	v_cvt_pk_bf16_f32 v234, v156, v157
	v_cvt_pk_bf16_f32 v235, v160, v161
	v_cvt_pk_bf16_f32 v237, v166, v167
	v_cvt_pk_bf16_f32 v239, v168, v169
	v_or_b32_e32 v162, s1, v144
	v_lshlrev_b32_e32 v162, 11, v162
	v_add_u32_e32 v163, v152, v162
	s_add_i32 s1, s0, 0xa0
	s_addk_i32 s0, 0xb0
	v_add_u32_e32 v154, v151, v162
	v_cndmask_b32_e64 v240, v163, v154, s[4:5]
	global_store_dwordx4 v240, v[232:235], s[12:13]
	global_store_dwordx4 v240, v[236:239], s[12:13] offset:64
	v_or_b32_e32 v154, s1, v140
	s_nop 0
	v_lshl_add_u32 v158, v154, 12, v153
	global_load_dwordx4 v[154:157], v158, s[72:73] nt
	s_nop 0
	global_load_dwordx4 v[158:161], v158, s[72:73] offset:64 nt
	s_waitcnt vmcnt(1)
; template <class T> DI T gld_nt(const void* base, unsigned off) { return __builtin_nontemporal_load((const T*)((const char*)base + off)); }
; DI u32x4 pk8(const f32x4& a, const f32x4& b) { u32x4 w; w.x = pk2(a[0], a[1]); w.y = pk2(a[2], a[3]); w.z = pk2(b[0], b[1]); w.w = pk2(b[2], b[3]); return w; }
; DI void unpk8(const u32x4& w, f32x4& a, f32x4& b) { a[0] = bf_lo(w.x); a[1] = bf_hi(w.x); a[2] = bf_lo(w.y); a[3] = bf_hi(w.y); b[0] = bf_lo(w.z); b[1] = bf_hi(w.z); b[2] = bf_lo(w.w); b[3] = bf_hi(w.w); }
; template <bool NT = false> DI void st_rows16(void* base, unsigned pitch_b, unsigned row0, unsigned col0, int fr, int fq, const u32x4& w0, const u32x4& w1) {
;   u32x4 x;
; #pragma unroll
;   for (int e = 0; e < 4; ++e) x[e] = (unsigned)__builtin_amdgcn_update_dpp(0, (int)w1[e], 0x128  , 0xf, 0xf, false);
;   const bool hi = fr >= 8;
;   u32x4 pa, pb;
; #pragma unroll
;   for (int e = 0; e < 4; ++e) { pa[e] = hi ? x[e] : w0[e]; pb[e] = hi ? w0[e] : x[e]; }
;   const unsigned ra = row0 + (unsigned)(fr & 7), ca = col0 + 8u * fq + (hi ? 32u : 0u), cb = col0 + 8u * fq + (hi ? 0u : 32u);
;   if (NT) { __builtin_nontemporal_store(pa, (u32x4*)((char*)base + (ra * pitch_b + ca * 2u))); __builtin_nontemporal_store(pb, (u32x4*)((char*)base + ((ra + 8u) * pitch_b + cb * 2u))); }
;   else { gst<u32x4>(base, ra * pitch_b + ca * 2u, pa); gst<u32x4>(base, (ra + 8u) * pitch_b + cb * 2u, pb); }
; }
;   DI void operator()(g8::Acc& acc, int pm, int pn, int wr, int wc, int fr, int fq) const {
;     ...
;     for (int ai = 0; ai < 2; ++ai)
; #pragma unroll
;       for (int m = 0; m < 4; ++m) {
;         const int row0 = pm * BM + ai * HALF + wr * 64 + m * 16, row = row0 + fr; u32x4 wv[2];
; #pragma unroll
;         for (int bj = 0; bj < 2; ++bj) {
;           const int col8 = pn * BM + wc * 64 + bj * 32 + fq * 8; const unsigned go = ((unsigned)row * 2048u + (unsigned)(1024 + col8)) * 2u;
;           f32x4 s0, s1; unpk8(gld_nt<u32x4>(gates, go), s0, s1);
; #pragma unroll
;           for (int e = 0; e < 4; ++e) { s0[e] = fmaxf(s0[e], 1e-30f); s1[e] = fmaxf(s1[e], 1e-30f); }
;           wv[bj] = pk8(acc[ai][bj][m][0] * s0, acc[ai][bj][m][1] * s1);
;         }
;         st_rows16(dst, DM * 2u, (unsigned)row0, (unsigned)(pn * BM + wc * 64), fr, fq, wv[0], wv[1]);
	v_lshlrev_b32_e32 v162, 16, v154
	v_and_b32_e32 v154, 0xffff0000, v154
	v_lshlrev_b32_e32 v163, 16, v155
	v_lshlrev_b32_e32 v164, 16, v156
	v_and_b32_e32 v156, 0xffff0000, v156
	v_lshlrev_b32_e32 v165, 16, v157
	v_and_b32_e32 v157, 0xffff0000, v157
	s_waitcnt vmcnt(0)
	v_lshlrev_b32_e32 v166, 16, v158
	v_and_b32_e32 v158, 0xffff0000, v158
	v_and_b32_e32 v155, 0xffff0000, v155
	v_lshlrev_b32_e32 v167, 16, v159
	v_and_b32_e32 v159, 0xffff0000, v159
	v_lshlrev_b32_e32 v168, 16, v160
	v_and_b32_e32 v160, 0xffff0000, v160
	v_lshlrev_b32_e32 v169, 16, v161
	v_and_b32_e32 v161, 0xffff0000, v161
	v_max_f32_e32 v162, v162, v162
	v_max_f32_e32 v164, v164, v164
	v_max_f32_e32 v170, v154, v154
	v_max_f32_e32 v171, v156, v156
	v_max_f32_e32 v163, v163, v163
	v_max_f32_e32 v165, v165, v165
	v_max_f32_e32 v173, v157, v157
	v_max_f32_e32 v166, v166, v166
	v_max_f32_e32 v174, v158, v158
	v_max_f32_e32 v172, v155, v155
	v_max_f32_e32 v168, v168, v168
	v_max_f32_e32 v175, v160, v160
	v_max_f32_e32 v167, v167, v167
	v_max_f32_e32 v176, v159, v159
	v_max_f32_e32 v177, v161, v161
	v_max_f32_e32 v154, 0xda24260, v162
	v_max_f32_e32 v156, 0xda24260, v164
	v_max_f32_e32 v155, 0xda24260, v170
	v_max_f32_e32 v157, 0xda24260, v171
	v_max_f32_e32 v158, 0xda24260, v163
	v_max_f32_e32 v160, 0xda24260, v165
	v_max_f32_e32 v161, 0xda24260, v173
	v_max_f32_e32 v162, 0xda24260, v166
	v_max_f32_e32 v163, 0xda24260, v174
	v_max_f32_e32 v169, v169, v169
	v_max_f32_e32 v159, 0xda24260, v172
	v_max_f32_e32 v164, 0xda24260, v168
	v_max_f32_e32 v165, 0xda24260, v175
	v_max_f32_e32 v166, 0xda24260, v167
	v_max_f32_e32 v167, 0xda24260, v176
	v_pk_mul_f32 v[154:155], v[44:45], v[154:155]
	v_pk_mul_f32 v[160:161], v[42:43], v[160:161]
	v_pk_mul_f32 v[156:157], v[40:41], v[156:157]
	v_pk_mul_f32 v[162:163], v[12:13], v[162:163]
	v_max_f32_e32 v168, 0xda24260, v169
	v_max_f32_e32 v169, 0xda24260, v177
	v_pk_mul_f32 v[158:159], v[46:47], v[158:159]
	v_pk_mul_f32 v[166:167], v[14:15], v[166:167]
	v_cvt_pk_bf16_f32 v232, v154, v155
	v_cvt_pk_bf16_f32 v234, v156, v157
	v_cvt_pk_bf16_f32 v235, v160, v161
	v_pk_mul_f32 v[154:155], v[8:9], v[164:165]
	v_cvt_pk_bf16_f32 v236, v162, v163
	v_pk_mul_f32 v[168:169], v[10:11], v[168:169]
	v_cvt_pk_bf16_f32 v233, v158, v159
	v_cvt_pk_bf16_f32 v237, v166, v167
	v_cvt_pk_bf16_f32 v238, v154, v155
	v_cvt_pk_bf16_f32 v239, v168, v169
	v_or_b32_e32 v162, s1, v144
	v_lshlrev_b32_e32 v162, 11, v162
	v_add_u32_e32 v163, v152, v162
	s_nop 1
	v_add_u32_e32 v154, v151, v162
	v_cndmask_b32_e64 v240, v163, v154, s[4:5]
	global_store_dwordx4 v240, v[232:235], s[12:13]
	global_store_dwordx4 v240, v[236:239], s[12:13] offset:64
	v_or_b32_e32 v154, s0, v140
	v_lshl_add_u32 v153, v154, 12, v153
	global_load_dwordx4 v[154:157], v153, s[72:73] nt
	global_load_dwordx4 v[158:161], v153, s[72:73] offset:64 nt
	s_waitcnt vmcnt(1)
	v_lshlrev_b32_e32 v162, 16, v155
	v_and_b32_e32 v155, 0xffff0000, v155
	v_lshlrev_b32_e32 v163, 16, v156
	v_and_b32_e32 v156, 0xffff0000, v156
	v_lshlrev_b32_e32 v153, 16, v154
	v_and_b32_e32 v154, 0xffff0000, v154
	v_lshlrev_b32_e32 v164, 16, v157
	v_and_b32_e32 v157, 0xffff0000, v157
	s_waitcnt vmcnt(0)
	v_lshlrev_b32_e32 v165, 16, v158
	v_and_b32_e32 v158, 0xffff0000, v158
	v_lshlrev_b32_e32 v166, 16, v159
	v_and_b32_e32 v159, 0xffff0000, v159
	v_lshlrev_b32_e32 v168, 16, v161
	v_and_b32_e32 v161, 0xffff0000, v161
	v_max_f32_e32 v163, v163, v163
	v_max_f32_e32 v170, v156, v156
	v_max_f32_e32 v162, v162, v162
	v_max_f32_e32 v171, v155, v155
	v_lshlrev_b32_e32 v167, 16, v160
	v_max_f32_e32 v153, v153, v153
	v_max_f32_e32 v169, v154, v154
	v_max_f32_e32 v172, v157, v157
	v_max_f32_e32 v165, v165, v165
	v_max_f32_e32 v173, v158, v158
	v_max_f32_e32 v168, v168, v168
	v_max_f32_e32 v175, v159, v159
	v_max_f32_e32 v176, v161, v161
	v_max_f32_e32 v156, 0xda24260, v163
	v_max_f32_e32 v157, 0xda24260, v170
	v_max_f32_e32 v158, 0xda24260, v162
	v_max_f32_e32 v159, 0xda24260, v171
	v_and_b32_e32 v160, 0xffff0000, v160
	v_max_f32_e32 v164, v164, v164
	v_max_f32_e32 v167, v167, v167
	v_max_f32_e32 v166, v166, v166
	v_max_f32_e32 v154, 0xda24260, v153
	v_max_f32_e32 v155, 0xda24260, v169
	v_max_f32_e32 v162, 0xda24260, v165
	v_max_f32_e32 v163, 0xda24260, v173
	v_max_f32_e32 v168, 0xda24260, v168
	v_max_f32_e32 v169, 0xda24260, v176
	v_pk_mul_f32 v[158:159], v[38:39], v[158:159]
	v_pk_mul_f32 v[156:157], v[32:33], v[156:157]
	v_max_f32_e32 v174, v160, v160
	v_max_f32_e32 v160, 0xda24260, v164
	v_max_f32_e32 v161, 0xda24260, v172
	v_max_f32_e32 v164, 0xda24260, v167
	v_max_f32_e32 v166, 0xda24260, v166
	v_max_f32_e32 v167, 0xda24260, v175
	v_pk_mul_f32 v[154:155], v[36:37], v[154:155]
	v_cvt_pk_bf16_f32 v233, v158, v159
	v_cvt_pk_bf16_f32 v234, v156, v157
	v_pk_mul_f32 v[156:157], v[4:5], v[162:163]
	v_pk_mul_f32 v[158:159], v[2:3], v[168:169]
	v_max_f32_e32 v165, 0xda24260, v174
	v_pk_mul_f32 v[160:161], v[34:35], v[160:161]
	v_cvt_pk_bf16_f32 v232, v154, v155
	v_pk_mul_f32 v[154:155], v[6:7], v[166:167]
	v_cvt_pk_bf16_f32 v236, v156, v157
	v_cvt_pk_bf16_f32 v239, v158, v159
	v_cvt_pk_bf16_f32 v235, v160, v161
	v_pk_mul_f32 v[160:161], v[0:1], v[164:165]
	v_cvt_pk_bf16_f32 v237, v154, v155
	v_cvt_pk_bf16_f32 v238, v160, v161
	v_or_b32_e32 v153, s0, v144
	v_lshlrev_b32_e32 v153, 11, v153
	v_add_u32_e32 v152, v152, v153
	v_add_u32_e32 v151, v151, v153
	v_cndmask_b32_e64 v240, v152, v151, s[4:5]
	global_store_dwordx4 v240, v[232:235], s[12:13]
	global_store_dwordx4 v240, v[236:239], s[12:13] offset:64
	s_cbranch_execnz .LBB0_488

; template <class T> DI T gld_nt(const void* base, unsigned off) { return __builtin_nontemporal_load((const T*)((const char*)base + off)); }
; template <bool NT = false> DI void st_rows16(void* base, unsigned pitch_b, unsigned row0, unsigned col0, int fr, int fq, const u32x4& w0, const u32x4& w1) {
;   u32x4 x;
; #pragma unroll
;   for (int e = 0; e < 4; ++e) x[e] = (unsigned)__builtin_amdgcn_update_dpp(0, (int)w1[e], 0x128  , 0xf, 0xf, false);
;   const bool hi = fr >= 8;
;   u32x4 pa, pb;
; #pragma unroll
;   for (int e = 0; e < 4; ++e) { pa[e] = hi ? x[e] : w0[e]; pb[e] = hi ? w0[e] : x[e]; }
;   const unsigned ra = row0 + (unsigned)(fr & 7), ca = col0 + 8u * fq + (hi ? 32u : 0u), cb = col0 + 8u * fq + (hi ? 0u : 32u);
;   if (NT) { __builtin_nontemporal_store(pa, (u32x4*)((char*)base + (ra * pitch_b + ca * 2u))); __builtin_nontemporal_store(pb, (u32x4*)((char*)base + ((ra + 8u) * pitch_b + cb * 2u))); }
;   else { gst<u32x4>(base, ra * pitch_b + ca * 2u, pa); gst<u32x4>(base, (ra + 8u) * pitch_b + cb * 2u, pb); }
; }
;   DI void operator()(g8::Acc& acc, int pm, int pn, int wr, int wc, int fr, int fq) const {
;     using namespace g8;
; #pragma unroll
;     for (int ai = 0; ai < 2; ++ai)
; #pragma unroll
;       for (int m = 0; m < 4; ++m) {
;         const int row = pm * BM + ai * HALF + wr * 64 + m * 16 + fr; float s = 0.f; u32x4 wv[2];
; #pragma unroll
;         for (int bj = 0; bj < 2; ++bj) {
;           const int col8 = pn * BM + wc * 64 + bj * 32 + fq * 8; const unsigned eo = (unsigned)row * DM + (unsigned)col8;
;           f32x4 r0, r1;
;           if (resf) { r0 = gld_nt<f32x4>(resf, eo * 4u); r1 = gld_nt<f32x4>(resf, eo * 4u + 16u); }
;           else unpk8(gld_nt<u32x4>(resb, eo * 2u), r0, r1);
;           const f32x4 o0 = r0 + acc[ai][bj][m][0], o1 = r1 + acc[ai][bj][m][1];
;           if (outf) { gst<f32x4>(outf, eo * 4u, o0); gst<f32x4>(outf, eo * 4u + 16u, o1); }
;           wv[bj] = pk8(o0, o1);
;           s += o0[0] * o0[0] + o0[1] * o0[1] + o0[2] * o0[2] + o0[3] * o0[3] + o1[0] * o1[0] + o1[1] * o1[1] + o1[2] * o1[2] + o1[3] * o1[3];
;         }
;         if (outb) st_rows16(outb, DM * 2u, (unsigned)(row - fr), (unsigned)(pn * BM + wc * 64), fr, fq, wv[0], wv[1]);
;         s += __shfl_xor(s, 16); s += __shfl_xor(s, 32);
;         if (fq == 0) atomicAdd(ssq + row, s);
;         __builtin_amdgcn_sched_barrier(0);
;       }
.LBB0_554:
	s_lshl_b32 s21, s58, 8
	s_add_i32 s21, s21, s11
	v_lshl_or_b32 v141, s54, 8, v144
	v_or_b32_e32 v140, s21, v142
	v_lshlrev_b32_e32 v154, 2, v141
	v_lshl_add_u32 v152, v140, 12, v154
	v_or_b32_e32 v153, 0x80, v152
	global_load_dwordx4 v[156:159], v152, s[16:17] nt
	global_load_dwordx4 v[160:163], v152, s[16:17] offset:16 nt
	global_load_dwordx4 v[164:167], v153, s[16:17] nt
	v_or_b32_e32 v152, 0x90, v152
	global_load_dwordx4 v[168:171], v152, s[16:17] nt
	v_or_b32_e32 v152, v141, v146
	v_or_b32_e32 v141, v141, v147
	v_lshlrev_b32_e32 v153, 1, v152
	v_lshl_add_u32 v152, v141, 1, v151
	s_waitcnt vmcnt(0)
	v_pk_add_f32 v[124:125], v[124:125], v[156:157]
	s_nop 0
	v_cvt_pk_bf16_f32 v176, v124, v125
	v_mul_f32_e32 v125, v125, v125
	v_pk_add_f32 v[116:117], v[116:117], v[164:165]
	v_fmac_f32_e32 v125, v124, v124
	v_mul_f32_e32 v124, v117, v117
	v_pk_add_f32 v[126:127], v[126:127], v[158:159]
	v_pk_add_f32 v[156:157], v[118:119], v[166:167]
	v_fmac_f32_e32 v124, v116, v116
	v_fmac_f32_e32 v125, v126, v126
	v_fmac_f32_e32 v124, v156, v156
	v_pk_add_f32 v[120:121], v[120:121], v[160:161]
	v_pk_add_f32 v[112:113], v[112:113], v[168:169]
	v_fmac_f32_e32 v125, v127, v127
	v_fmac_f32_e32 v124, v157, v157
	v_fmac_f32_e32 v125, v120, v120
	v_fmac_f32_e32 v124, v112, v112
	v_pk_add_f32 v[122:123], v[122:123], v[162:163]
	v_pk_add_f32 v[158:159], v[114:115], v[170:171]
	v_fmac_f32_e32 v125, v121, v121
	v_fmac_f32_e32 v124, v113, v113
	v_fmac_f32_e32 v125, v122, v122
	v_fmac_f32_e32 v124, v158, v158
	v_fmac_f32_e32 v125, v123, v123
	v_fmac_f32_e32 v124, v159, v159
	v_cvt_pk_bf16_f32 v182, v112, v113
	v_add_f32_e32 v112, v125, v124
	ds_bpermute_b32 v113, v214, v112
	v_cvt_pk_bf16_f32 v179, v122, v123
	v_cvt_pk_bf16_f32 v183, v158, v159
	v_cvt_pk_bf16_f32 v181, v156, v157
	v_cvt_pk_bf16_f32 v180, v116, v117
	s_waitcnt lgkmcnt(0)
	v_add_f32_e32 v112, v112, v113
	ds_bpermute_b32 v113, v213, v112
	v_or_b32_e32 v122, s21, v145
	v_cvt_pk_bf16_f32 v177, v126, v127
	v_cvt_pk_bf16_f32 v178, v120, v121
	v_lshlrev_b32_e32 v122, 11, v122
	v_add_u32_e32 v123, v153, v122
	v_add_u32_e32 v191, v152, v122
	v_cndmask_b32_e64 v190, v123, v191, s[6:7]
	global_store_dwordx4 v190, v[176:179], s[24:25]
	s_nop 1
	global_store_dwordx4 v190, v[180:183], s[24:25] offset:64
	s_and_saveexec_b64 s[0:1], s[4:5]
	s_cbranch_execz .LBB0_556
	v_ashrrev_i32_e32 v141, 31, v140
	s_waitcnt lgkmcnt(0)
	v_add_f32_e32 v114, v112, v113
	v_lshl_add_u64 v[112:113], v[140:141], 2, s[78:79]
	global_atomic_add_f32 v[112:113], v114, off
.LBB0_556:
	s_or_b64 exec, exec, s[0:1]
	s_or_b32 s0, s21, 16
	v_or_b32_e32 v112, s0, v142
	s_waitcnt lgkmcnt(0)
	v_lshl_add_u32 v113, v112, 12, v154
	v_or_b32_e32 v122, 0x80, v113
	global_load_dwordx4 v[114:117], v113, s[16:17] nt
	global_load_dwordx4 v[118:121], v113, s[16:17] offset:16 nt
	v_or_b32_e32 v113, 0x90, v113
	global_load_dwordx4 v[122:125], v122, s[16:17] nt
	global_load_dwordx4 v[156:159], v113, s[16:17] nt
	s_waitcnt vmcnt(3)
	v_pk_add_f32 v[108:109], v[108:109], v[114:115]
	s_waitcnt vmcnt(2)
	v_pk_add_f32 v[104:105], v[104:105], v[118:119]
	v_cvt_pk_bf16_f32 v176, v108, v109
	v_mul_f32_e32 v109, v109, v109
	s_waitcnt vmcnt(1)
	v_pk_add_f32 v[100:101], v[100:101], v[122:123]
	v_fmac_f32_e32 v109, v108, v108
	v_mul_f32_e32 v108, v101, v101
	v_pk_add_f32 v[110:111], v[110:111], v[116:117]
	v_pk_add_f32 v[114:115], v[102:103], v[124:125]
	v_fmac_f32_e32 v108, v100, v100
	v_fmac_f32_e32 v109, v110, v110
	v_fmac_f32_e32 v108, v114, v114
	s_waitcnt vmcnt(0)
	v_pk_add_f32 v[96:97], v[96:97], v[156:157]
	v_fmac_f32_e32 v109, v111, v111
	v_fmac_f32_e32 v108, v115, v115
	v_fmac_f32_e32 v109, v104, v104
	v_fmac_f32_e32 v108, v96, v96
	v_pk_add_f32 v[106:107], v[106:107], v[120:121]
	v_pk_add_f32 v[116:117], v[98:99], v[158:159]
	v_fmac_f32_e32 v109, v105, v105
	v_fmac_f32_e32 v108, v97, v97
	v_fmac_f32_e32 v109, v106, v106
	v_fmac_f32_e32 v108, v116, v116
	v_fmac_f32_e32 v109, v107, v107
	v_fmac_f32_e32 v108, v117, v117
	v_cvt_pk_bf16_f32 v182, v96, v97
	v_add_f32_e32 v96, v109, v108
	ds_bpermute_b32 v97, v214, v96
	v_cvt_pk_bf16_f32 v179, v106, v107
	v_cvt_pk_bf16_f32 v183, v116, v117
	v_cvt_pk_bf16_f32 v181, v114, v115
	v_cvt_pk_bf16_f32 v180, v100, v101
	s_waitcnt lgkmcnt(0)
	v_add_f32_e32 v96, v96, v97
	ds_bpermute_b32 v97, v213, v96
	v_or_b32_e32 v106, s0, v145
	v_cvt_pk_bf16_f32 v177, v110, v111
	v_cvt_pk_bf16_f32 v178, v104, v105
	v_lshlrev_b32_e32 v106, 11, v106
	v_add_u32_e32 v107, v153, v106
	v_add_u32_e32 v191, v152, v106
	v_cndmask_b32_e64 v190, v107, v191, s[6:7]
	global_store_dwordx4 v190, v[176:179], s[24:25]
	s_nop 1
	global_store_dwordx4 v190, v[180:183], s[24:25] offset:64
	s_and_saveexec_b64 s[0:1], s[4:5]
	s_cbranch_execz .LBB0_558
	v_ashrrev_i32_e32 v113, 31, v112
	s_waitcnt lgkmcnt(0)
	v_add_f32_e32 v98, v96, v97
	v_lshl_add_u64 v[96:97], v[112:113], 2, s[78:79]
	global_atomic_add_f32 v[96:97], v98, off
; template <class T> DI T gld_nt(const void* base, unsigned off) { return __builtin_nontemporal_load((const T*)((const char*)base + off)); }
; template <bool NT = false> DI void st_rows16(void* base, unsigned pitch_b, unsigned row0, unsigned col0, int fr, int fq, const u32x4& w0, const u32x4& w1) {
;   u32x4 x;
; #pragma unroll
;   for (int e = 0; e < 4; ++e) x[e] = (unsigned)__builtin_amdgcn_update_dpp(0, (int)w1[e], 0x128  , 0xf, 0xf, false);
;   const bool hi = fr >= 8;
;   u32x4 pa, pb;
; #pragma unroll
;   for (int e = 0; e < 4; ++e) { pa[e] = hi ? x[e] : w0[e]; pb[e] = hi ? w0[e] : x[e]; }
;   const unsigned ra = row0 + (unsigned)(fr & 7), ca = col0 + 8u * fq + (hi ? 32u : 0u), cb = col0 + 8u * fq + (hi ? 0u : 32u);
;   if (NT) { __builtin_nontemporal_store(pa, (u32x4*)((char*)base + (ra * pitch_b + ca * 2u))); __builtin_nontemporal_store(pb, (u32x4*)((char*)base + ((ra + 8u) * pitch_b + cb * 2u))); }
;   else { gst<u32x4>(base, ra * pitch_b + ca * 2u, pa); gst<u32x4>(base, (ra + 8u) * pitch_b + cb * 2u, pb); }
; }
;   DI void operator()(g8::Acc& acc, int pm, int pn, int wr, int wc, int fr, int fq) const {
;     using namespace g8;
; #pragma unroll
;     for (int ai = 0; ai < 2; ++ai)
; #pragma unroll
;       for (int m = 0; m < 4; ++m) {
;         const int row = pm * BM + ai * HALF + wr * 64 + m * 16 + fr; float s = 0.f; u32x4 wv[2];
; #pragma unroll
;         for (int bj = 0; bj < 2; ++bj) {
;           const int col8 = pn * BM + wc * 64 + bj * 32 + fq * 8; const unsigned eo = (unsigned)row * DM + (unsigned)col8;
;           f32x4 r0, r1;
;           if (resf) { r0 = gld_nt<f32x4>(resf, eo * 4u); r1 = gld_nt<f32x4>(resf, eo * 4u + 16u); }
;           else unpk8(gld_nt<u32x4>(resb, eo * 2u), r0, r1);
;           const f32x4 o0 = r0 + acc[ai][bj][m][0], o1 = r1 + acc[ai][bj][m][1];
;           if (outf) { gst<f32x4>(outf, eo * 4u, o0); gst<f32x4>(outf, eo * 4u + 16u, o1); }
;           wv[bj] = pk8(o0, o1);
;           s += o0[0] * o0[0] + o0[1] * o0[1] + o0[2] * o0[2] + o0[3] * o0[3] + o1[0] * o1[0] + o1[1] * o1[1] + o1[2] * o1[2] + o1[3] * o1[3];
;         }
;         if (outb) st_rows16(outb, DM * 2u, (unsigned)(row - fr), (unsigned)(pn * BM + wc * 64), fr, fq, wv[0], wv[1]);
;         s += __shfl_xor(s, 16); s += __shfl_xor(s, 32);
;         if (fq == 0) atomicAdd(ssq + row, s);
;         __builtin_amdgcn_sched_barrier(0);
;       }
.LBB0_558:
	s_or_b64 exec, exec, s[0:1]
	s_or_b32 s0, s21, 32
	v_or_b32_e32 v96, s0, v142
	s_waitcnt lgkmcnt(0)
	v_lshl_add_u32 v97, v96, 12, v154
	v_or_b32_e32 v106, 0x80, v97
	global_load_dwordx4 v[98:101], v97, s[16:17] nt
	global_load_dwordx4 v[102:105], v97, s[16:17] offset:16 nt
	v_or_b32_e32 v97, 0x90, v97
	global_load_dwordx4 v[106:109], v106, s[16:17] nt
	global_load_dwordx4 v[110:113], v97, s[16:17] nt
	s_waitcnt vmcnt(3)
	v_pk_add_f32 v[92:93], v[92:93], v[98:99]
	s_waitcnt vmcnt(2)
	v_pk_add_f32 v[88:89], v[88:89], v[102:103]
	v_cvt_pk_bf16_f32 v176, v92, v93
	v_mul_f32_e32 v93, v93, v93
	s_waitcnt vmcnt(1)
	v_pk_add_f32 v[84:85], v[84:85], v[106:107]
	v_fmac_f32_e32 v93, v92, v92
	v_mul_f32_e32 v92, v85, v85
	v_pk_add_f32 v[94:95], v[94:95], v[100:101]
	v_pk_add_f32 v[98:99], v[86:87], v[108:109]
	v_fmac_f32_e32 v92, v84, v84
	v_fmac_f32_e32 v93, v94, v94
	v_fmac_f32_e32 v92, v98, v98
	s_waitcnt vmcnt(0)
	v_pk_add_f32 v[80:81], v[80:81], v[110:111]
	v_fmac_f32_e32 v93, v95, v95
	v_fmac_f32_e32 v92, v99, v99
	v_fmac_f32_e32 v93, v88, v88
	v_fmac_f32_e32 v92, v80, v80
	v_pk_add_f32 v[90:91], v[90:91], v[104:105]
	v_pk_add_f32 v[100:101], v[82:83], v[112:113]
	v_fmac_f32_e32 v93, v89, v89
	v_fmac_f32_e32 v92, v81, v81
	v_fmac_f32_e32 v93, v90, v90
	v_fmac_f32_e32 v92, v100, v100
	v_fmac_f32_e32 v93, v91, v91
	v_fmac_f32_e32 v92, v101, v101
	v_cvt_pk_bf16_f32 v182, v80, v81
	v_add_f32_e32 v80, v93, v92
	ds_bpermute_b32 v81, v214, v80
	v_cvt_pk_bf16_f32 v179, v90, v91
	v_cvt_pk_bf16_f32 v183, v100, v101
	v_cvt_pk_bf16_f32 v181, v98, v99
	v_cvt_pk_bf16_f32 v180, v84, v85
	s_waitcnt lgkmcnt(0)
	v_add_f32_e32 v80, v80, v81
	ds_bpermute_b32 v81, v213, v80
	v_or_b32_e32 v90, s0, v145
	v_cvt_pk_bf16_f32 v177, v94, v95
	v_cvt_pk_bf16_f32 v178, v88, v89
	v_lshlrev_b32_e32 v90, 11, v90
	v_add_u32_e32 v91, v153, v90
	v_add_u32_e32 v191, v152, v90
	v_cndmask_b32_e64 v190, v91, v191, s[6:7]
	global_store_dwordx4 v190, v[176:179], s[24:25]
	s_nop 1
	global_store_dwordx4 v190, v[180:183], s[24:25] offset:64
	s_and_saveexec_b64 s[0:1], s[4:5]
	s_cbranch_execz .LBB0_560
	v_ashrrev_i32_e32 v97, 31, v96
	s_waitcnt lgkmcnt(0)
	v_add_f32_e32 v82, v80, v81
	v_lshl_add_u64 v[80:81], v[96:97], 2, s[78:79]
	global_atomic_add_f32 v[80:81], v82, off
.LBB0_560:
	s_or_b64 exec, exec, s[0:1]
	s_or_b32 s0, s21, 48
	v_or_b32_e32 v80, s0, v142
	s_waitcnt lgkmcnt(0)
	v_lshl_add_u32 v81, v80, 12, v154
	v_or_b32_e32 v90, 0x80, v81
	global_load_dwordx4 v[82:85], v81, s[16:17] nt
	global_load_dwordx4 v[86:89], v81, s[16:17] offset:16 nt
	v_or_b32_e32 v81, 0x90, v81
	global_load_dwordx4 v[90:93], v90, s[16:17] nt
	global_load_dwordx4 v[94:97], v81, s[16:17] nt
	s_waitcnt vmcnt(3)
	v_pk_add_f32 v[76:77], v[76:77], v[82:83]
	s_waitcnt vmcnt(2)
	v_pk_add_f32 v[72:73], v[72:73], v[86:87]
	v_cvt_pk_bf16_f32 v176, v76, v77
	v_mul_f32_e32 v77, v77, v77
	s_waitcnt vmcnt(1)
	v_pk_add_f32 v[68:69], v[68:69], v[90:91]
	v_fmac_f32_e32 v77, v76, v76
	v_mul_f32_e32 v76, v69, v69
	v_pk_add_f32 v[78:79], v[78:79], v[84:85]
	v_pk_add_f32 v[82:83], v[70:71], v[92:93]
	v_fmac_f32_e32 v76, v68, v68
	v_fmac_f32_e32 v77, v78, v78
	v_fmac_f32_e32 v76, v82, v82
	s_waitcnt vmcnt(0)
	v_pk_add_f32 v[64:65], v[64:65], v[94:95]
	v_fmac_f32_e32 v77, v79, v79
	v_fmac_f32_e32 v76, v83, v83
	v_fmac_f32_e32 v77, v72, v72
	v_fmac_f32_e32 v76, v64, v64
	v_pk_add_f32 v[74:75], v[74:75], v[88:89]
	v_pk_add_f32 v[84:85], v[66:67], v[96:97]
	v_fmac_f32_e32 v77, v73, v73
	v_fmac_f32_e32 v76, v65, v65
	v_fmac_f32_e32 v77, v74, v74
	v_fmac_f32_e32 v76, v84, v84
	v_fmac_f32_e32 v77, v75, v75
	v_fmac_f32_e32 v76, v85, v85
	v_cvt_pk_bf16_f32 v182, v64, v65
	v_add_f32_e32 v64, v77, v76
	ds_bpermute_b32 v65, v214, v64
	v_cvt_pk_bf16_f32 v179, v74, v75
	v_cvt_pk_bf16_f32 v183, v84, v85
	v_cvt_pk_bf16_f32 v181, v82, v83
	v_cvt_pk_bf16_f32 v180, v68, v69
	s_waitcnt lgkmcnt(0)
	v_add_f32_e32 v64, v64, v65
	ds_bpermute_b32 v65, v213, v64
	v_or_b32_e32 v74, s0, v145
	v_cvt_pk_bf16_f32 v177, v78, v79
	v_cvt_pk_bf16_f32 v178, v72, v73
	v_lshlrev_b32_e32 v74, 11, v74
	v_add_u32_e32 v75, v153, v74
	v_add_u32_e32 v191, v152, v74
	v_cndmask_b32_e64 v190, v75, v191, s[6:7]
	global_store_dwordx4 v190, v[176:179], s[24:25]
	s_nop 1
	global_store_dwordx4 v190, v[180:183], s[24:25] offset:64
	s_and_saveexec_b64 s[0:1], s[4:5]
	s_cbranch_execz .LBB0_562
	v_ashrrev_i32_e32 v81, 31, v80
	s_waitcnt lgkmcnt(0)
	v_add_f32_e32 v66, v64, v65
	v_lshl_add_u64 v[64:65], v[80:81], 2, s[78:79]
	global_atomic_add_f32 v[64:65], v66, off
.LBB0_562:
	s_or_b64 exec, exec, s[0:1]
	s_add_i32 s0, s21, 0x80
	v_or_b32_e32 v64, s0, v142
	s_waitcnt lgkmcnt(0)
	v_lshl_add_u32 v65, v64, 12, v154
	v_or_b32_e32 v74, 0x80, v65
	global_load_dwordx4 v[66:69], v65, s[16:17] nt
	global_load_dwordx4 v[70:73], v65, s[16:17] offset:16 nt
	v_or_b32_e32 v65, 0x90, v65
	global_load_dwordx4 v[74:77], v74, s[16:17] nt
	global_load_dwordx4 v[78:81], v65, s[16:17] nt
	s_waitcnt vmcnt(3)
	v_pk_add_f32 v[60:61], v[60:61], v[66:67]
	s_waitcnt vmcnt(2)
	v_pk_add_f32 v[56:57], v[56:57], v[70:71]
	v_cvt_pk_bf16_f32 v176, v60, v61
	v_mul_f32_e32 v61, v61, v61
	s_waitcnt vmcnt(1)
	v_pk_add_f32 v[52:53], v[52:53], v[74:75]
	v_fmac_f32_e32 v61, v60, v60
	v_mul_f32_e32 v60, v53, v53
	v_pk_add_f32 v[62:63], v[62:63], v[68:69]
	v_pk_add_f32 v[66:67], v[54:55], v[76:77]
	v_fmac_f32_e32 v60, v52, v52
	v_fmac_f32_e32 v61, v62, v62
	v_fmac_f32_e32 v60, v66, v66
	s_waitcnt vmcnt(0)
	v_pk_add_f32 v[48:49], v[48:49], v[78:79]
	v_fmac_f32_e32 v61, v63, v63
	v_fmac_f32_e32 v60, v67, v67
	v_fmac_f32_e32 v61, v56, v56
	v_fmac_f32_e32 v60, v48, v48
	v_pk_add_f32 v[58:59], v[58:59], v[72:73]
	v_pk_add_f32 v[68:69], v[50:51], v[80:81]
	v_fmac_f32_e32 v61, v57, v57
	v_fmac_f32_e32 v60, v49, v49
	v_fmac_f32_e32 v61, v58, v58
	v_fmac_f32_e32 v60, v68, v68
	v_fmac_f32_e32 v61, v59, v59
	v_fmac_f32_e32 v60, v69, v69
	v_cvt_pk_bf16_f32 v182, v48, v49
	v_add_f32_e32 v48, v61, v60
	ds_bpermute_b32 v49, v214, v48
	v_cvt_pk_bf16_f32 v179, v58, v59
	v_cvt_pk_bf16_f32 v183, v68, v69
	v_cvt_pk_bf16_f32 v181, v66, v67
	v_cvt_pk_bf16_f32 v180, v52, v53
	s_waitcnt lgkmcnt(0)
	v_add_f32_e32 v48, v48, v49
	ds_bpermute_b32 v49, v213, v48
	v_or_b32_e32 v58, s0, v145
	v_cvt_pk_bf16_f32 v177, v62, v63
	v_cvt_pk_bf16_f32 v178, v56, v57
	v_lshlrev_b32_e32 v58, 11, v58
	v_add_u32_e32 v59, v153, v58
	v_add_u32_e32 v191, v152, v58
	v_cndmask_b32_e64 v190, v59, v191, s[6:7]
	global_store_dwordx4 v190, v[176:179], s[24:25]
	s_nop 1
	global_store_dwordx4 v190, v[180:183], s[24:25] offset:64
	s_and_saveexec_b64 s[0:1], s[4:5]
	s_cbranch_execz .LBB0_564
	v_ashrrev_i32_e32 v65, 31, v64
	s_waitcnt lgkmcnt(0)
	v_add_f32_e32 v50, v48, v49
	v_lshl_add_u64 v[48:49], v[64:65], 2, s[78:79]
	global_atomic_add_f32 v[48:49], v50, off
; template <class T> DI T gld_nt(const void* base, unsigned off) { return __builtin_nontemporal_load((const T*)((const char*)base + off)); }
; template <bool NT = false> DI void st_rows16(void* base, unsigned pitch_b, unsigned row0, unsigned col0, int fr, int fq, const u32x4& w0, const u32x4& w1) {
;   u32x4 x;
; #pragma unroll
;   for (int e = 0; e < 4; ++e) x[e] = (unsigned)__builtin_amdgcn_update_dpp(0, (int)w1[e], 0x128  , 0xf, 0xf, false);
;   const bool hi = fr >= 8;
;   u32x4 pa, pb;
; #pragma unroll
;   for (int e = 0; e < 4; ++e) { pa[e] = hi ? x[e] : w0[e]; pb[e] = hi ? w0[e] : x[e]; }
;   const unsigned ra = row0 + (unsigned)(fr & 7), ca = col0 + 8u * fq + (hi ? 32u : 0u), cb = col0 + 8u * fq + (hi ? 0u : 32u);
;   if (NT) { __builtin_nontemporal_store(pa, (u32x4*)((char*)base + (ra * pitch_b + ca * 2u))); __builtin_nontemporal_store(pb, (u32x4*)((char*)base + ((ra + 8u) * pitch_b + cb * 2u))); }
;   else { gst<u32x4>(base, ra * pitch_b + ca * 2u, pa); gst<u32x4>(base, (ra + 8u) * pitch_b + cb * 2u, pb); }
; }
;   DI void operator()(g8::Acc& acc, int pm, int pn, int wr, int wc, int fr, int fq) const {
;     using namespace g8;
; #pragma unroll
;     for (int ai = 0; ai < 2; ++ai)
; #pragma unroll
;       for (int m = 0; m < 4; ++m) {
;         const int row = pm * BM + ai * HALF + wr * 64 + m * 16 + fr; float s = 0.f; u32x4 wv[2];
; #pragma unroll
;         for (int bj = 0; bj < 2; ++bj) {
;           const int col8 = pn * BM + wc * 64 + bj * 32 + fq * 8; const unsigned eo = (unsigned)row * DM + (unsigned)col8;
;           f32x4 r0, r1;
;           if (resf) { r0 = gld_nt<f32x4>(resf, eo * 4u); r1 = gld_nt<f32x4>(resf, eo * 4u + 16u); }
;           else unpk8(gld_nt<u32x4>(resb, eo * 2u), r0, r1);
;           const f32x4 o0 = r0 + acc[ai][bj][m][0], o1 = r1 + acc[ai][bj][m][1];
;           if (outf) { gst<f32x4>(outf, eo * 4u, o0); gst<f32x4>(outf, eo * 4u + 16u, o1); }
;           wv[bj] = pk8(o0, o1);
;           s += o0[0] * o0[0] + o0[1] * o0[1] + o0[2] * o0[2] + o0[3] * o0[3] + o1[0] * o1[0] + o1[1] * o1[1] + o1[2] * o1[2] + o1[3] * o1[3];
;         }
;         if (outb) st_rows16(outb, DM * 2u, (unsigned)(row - fr), (unsigned)(pn * BM + wc * 64), fr, fq, wv[0], wv[1]);
;         s += __shfl_xor(s, 16); s += __shfl_xor(s, 32);
;         if (fq == 0) atomicAdd(ssq + row, s);
;         __builtin_amdgcn_sched_barrier(0);
;       }
.LBB0_564:
	s_or_b64 exec, exec, s[0:1]
	s_add_i32 s0, s21, 0x90
	v_or_b32_e32 v48, s0, v142
	s_waitcnt lgkmcnt(0)
	v_lshl_add_u32 v49, v48, 12, v154
	v_or_b32_e32 v58, 0x80, v49
	global_load_dwordx4 v[50:53], v49, s[16:17] nt
	global_load_dwordx4 v[54:57], v49, s[16:17] offset:16 nt
	v_or_b32_e32 v49, 0x90, v49
	global_load_dwordx4 v[58:61], v58, s[16:17] nt
	global_load_dwordx4 v[62:65], v49, s[16:17] nt
	s_waitcnt vmcnt(3)
	v_pk_add_f32 v[44:45], v[44:45], v[50:51]
	s_waitcnt vmcnt(2)
	v_pk_add_f32 v[40:41], v[40:41], v[54:55]
	v_cvt_pk_bf16_f32 v176, v44, v45
	v_mul_f32_e32 v45, v45, v45
	s_waitcnt vmcnt(1)
	v_pk_add_f32 v[36:37], v[36:37], v[58:59]
	v_fmac_f32_e32 v45, v44, v44
	v_mul_f32_e32 v44, v37, v37
	v_pk_add_f32 v[46:47], v[46:47], v[52:53]
	v_pk_add_f32 v[50:51], v[38:39], v[60:61]
	v_fmac_f32_e32 v44, v36, v36
	v_fmac_f32_e32 v45, v46, v46
	v_fmac_f32_e32 v44, v50, v50
	s_waitcnt vmcnt(0)
	v_pk_add_f32 v[32:33], v[32:33], v[62:63]
	v_fmac_f32_e32 v45, v47, v47
	v_fmac_f32_e32 v44, v51, v51
	v_fmac_f32_e32 v45, v40, v40
	v_fmac_f32_e32 v44, v32, v32
	v_pk_add_f32 v[42:43], v[42:43], v[56:57]
	v_pk_add_f32 v[52:53], v[34:35], v[64:65]
	v_fmac_f32_e32 v45, v41, v41
	v_fmac_f32_e32 v44, v33, v33
	v_fmac_f32_e32 v45, v42, v42
	v_fmac_f32_e32 v44, v52, v52
	v_fmac_f32_e32 v45, v43, v43
	v_fmac_f32_e32 v44, v53, v53
	v_cvt_pk_bf16_f32 v182, v32, v33
	v_add_f32_e32 v32, v45, v44
	ds_bpermute_b32 v33, v214, v32
	v_cvt_pk_bf16_f32 v179, v42, v43
	v_cvt_pk_bf16_f32 v183, v52, v53
	v_cvt_pk_bf16_f32 v181, v50, v51
	v_cvt_pk_bf16_f32 v180, v36, v37
	s_waitcnt lgkmcnt(0)
	v_add_f32_e32 v32, v32, v33
	ds_bpermute_b32 v33, v213, v32
	v_or_b32_e32 v42, s0, v145
	v_cvt_pk_bf16_f32 v177, v46, v47
	v_cvt_pk_bf16_f32 v178, v40, v41
	v_lshlrev_b32_e32 v42, 11, v42
	v_add_u32_e32 v43, v153, v42
	v_add_u32_e32 v191, v152, v42
	v_cndmask_b32_e64 v190, v43, v191, s[6:7]
	global_store_dwordx4 v190, v[176:179], s[24:25]
	s_nop 1
	global_store_dwordx4 v190, v[180:183], s[24:25] offset:64
	s_and_saveexec_b64 s[0:1], s[4:5]
	s_cbranch_execz .LBB0_566
	v_ashrrev_i32_e32 v49, 31, v48
	s_waitcnt lgkmcnt(0)
	v_add_f32_e32 v34, v32, v33
	v_lshl_add_u64 v[32:33], v[48:49], 2, s[78:79]
	global_atomic_add_f32 v[32:33], v34, off
.LBB0_566:
	s_or_b64 exec, exec, s[0:1]
	s_add_i32 s0, s21, 0xa0
	v_or_b32_e32 v32, s0, v142
	s_waitcnt lgkmcnt(0)
	v_lshl_add_u32 v33, v32, 12, v154
	v_or_b32_e32 v42, 0x80, v33
	global_load_dwordx4 v[34:37], v33, s[16:17] nt
	global_load_dwordx4 v[38:41], v33, s[16:17] offset:16 nt
	v_or_b32_e32 v33, 0x90, v33
	global_load_dwordx4 v[42:45], v42, s[16:17] nt
	global_load_dwordx4 v[46:49], v33, s[16:17] nt
	s_waitcnt vmcnt(3)
	v_pk_add_f32 v[28:29], v[28:29], v[34:35]
	s_waitcnt vmcnt(2)
	v_pk_add_f32 v[24:25], v[24:25], v[38:39]
	v_cvt_pk_bf16_f32 v176, v28, v29
	v_mul_f32_e32 v29, v29, v29
	s_waitcnt vmcnt(1)
	v_pk_add_f32 v[20:21], v[20:21], v[42:43]
	v_fmac_f32_e32 v29, v28, v28
	v_mul_f32_e32 v28, v21, v21
	v_pk_add_f32 v[30:31], v[30:31], v[36:37]
	v_pk_add_f32 v[34:35], v[22:23], v[44:45]
	v_fmac_f32_e32 v28, v20, v20
	v_fmac_f32_e32 v29, v30, v30
	v_fmac_f32_e32 v28, v34, v34
	s_waitcnt vmcnt(0)
	v_pk_add_f32 v[16:17], v[16:17], v[46:47]
	v_fmac_f32_e32 v29, v31, v31
	v_fmac_f32_e32 v28, v35, v35
	v_fmac_f32_e32 v29, v24, v24
	v_fmac_f32_e32 v28, v16, v16
	v_pk_add_f32 v[26:27], v[26:27], v[40:41]
	v_pk_add_f32 v[36:37], v[18:19], v[48:49]
	v_fmac_f32_e32 v29, v25, v25
	v_fmac_f32_e32 v28, v17, v17
	v_fmac_f32_e32 v29, v26, v26
	v_fmac_f32_e32 v28, v36, v36
	v_fmac_f32_e32 v29, v27, v27
	v_fmac_f32_e32 v28, v37, v37
	v_cvt_pk_bf16_f32 v182, v16, v17
	v_add_f32_e32 v16, v29, v28
	ds_bpermute_b32 v17, v214, v16
	v_cvt_pk_bf16_f32 v179, v26, v27
	v_cvt_pk_bf16_f32 v183, v36, v37
	v_cvt_pk_bf16_f32 v181, v34, v35
	v_cvt_pk_bf16_f32 v180, v20, v21
	s_waitcnt lgkmcnt(0)
	v_add_f32_e32 v16, v16, v17
	ds_bpermute_b32 v17, v213, v16
	v_or_b32_e32 v26, s0, v145
	v_cvt_pk_bf16_f32 v177, v30, v31
	v_cvt_pk_bf16_f32 v178, v24, v25
	v_lshlrev_b32_e32 v26, 11, v26
	v_add_u32_e32 v27, v153, v26
	v_add_u32_e32 v191, v152, v26
	v_cndmask_b32_e64 v190, v27, v191, s[6:7]
	global_store_dwordx4 v190, v[176:179], s[24:25]
	s_nop 1
	global_store_dwordx4 v190, v[180:183], s[24:25] offset:64
	s_and_saveexec_b64 s[0:1], s[4:5]
	s_cbranch_execz .LBB0_568
	v_ashrrev_i32_e32 v33, 31, v32
	s_waitcnt lgkmcnt(0)
	v_add_f32_e32 v18, v16, v17
	v_lshl_add_u64 v[16:17], v[32:33], 2, s[78:79]
	global_atomic_add_f32 v[16:17], v18, off
.LBB0_568:
	s_or_b64 exec, exec, s[0:1]
	s_addk_i32 s21, 0xb0
	v_or_b32_e32 v16, s21, v142
	s_waitcnt lgkmcnt(0)
	v_lshl_add_u32 v17, v16, 12, v154
	v_or_b32_e32 v26, 0x80, v17
	global_load_dwordx4 v[18:21], v17, s[16:17] nt
	global_load_dwordx4 v[22:25], v17, s[16:17] offset:16 nt
	v_or_b32_e32 v17, 0x90, v17
	global_load_dwordx4 v[26:29], v26, s[16:17] nt
	global_load_dwordx4 v[30:33], v17, s[16:17] nt
	s_waitcnt vmcnt(3)
	v_pk_add_f32 v[12:13], v[12:13], v[18:19]
	s_waitcnt vmcnt(2)
	v_pk_add_f32 v[8:9], v[8:9], v[22:23]
	v_cvt_pk_bf16_f32 v176, v12, v13
	v_mul_f32_e32 v13, v13, v13
	s_waitcnt vmcnt(1)
	v_pk_add_f32 v[4:5], v[4:5], v[26:27]
	v_fmac_f32_e32 v13, v12, v12
	v_mul_f32_e32 v12, v5, v5
	v_pk_add_f32 v[14:15], v[14:15], v[20:21]
	v_pk_add_f32 v[18:19], v[6:7], v[28:29]
	v_fmac_f32_e32 v12, v4, v4
	v_fmac_f32_e32 v13, v14, v14
	v_fmac_f32_e32 v12, v18, v18
	s_waitcnt vmcnt(0)
	v_pk_add_f32 v[0:1], v[0:1], v[30:31]
	v_fmac_f32_e32 v13, v15, v15
	v_fmac_f32_e32 v12, v19, v19
	v_fmac_f32_e32 v13, v8, v8
	v_fmac_f32_e32 v12, v0, v0
	v_pk_add_f32 v[10:11], v[10:11], v[24:25]
	v_pk_add_f32 v[20:21], v[2:3], v[32:33]
	v_fmac_f32_e32 v13, v9, v9
	v_fmac_f32_e32 v12, v1, v1
	v_fmac_f32_e32 v13, v10, v10
	v_fmac_f32_e32 v12, v20, v20
	v_fmac_f32_e32 v13, v11, v11
	v_fmac_f32_e32 v12, v21, v21
	v_cvt_pk_bf16_f32 v182, v0, v1
	v_add_f32_e32 v0, v13, v12
	ds_bpermute_b32 v1, v214, v0
	v_cvt_pk_bf16_f32 v179, v10, v11
	v_cvt_pk_bf16_f32 v183, v20, v21
	v_cvt_pk_bf16_f32 v181, v18, v19
	v_cvt_pk_bf16_f32 v180, v4, v5
	s_waitcnt lgkmcnt(0)
	v_add_f32_e32 v0, v0, v1
	ds_bpermute_b32 v1, v213, v0
	v_or_b32_e32 v10, s21, v145
	v_cvt_pk_bf16_f32 v177, v14, v15
	v_cvt_pk_bf16_f32 v178, v8, v9
	v_lshlrev_b32_e32 v10, 11, v10
	v_add_u32_e32 v11, v153, v10
	v_add_u32_e32 v191, v152, v10
	v_cndmask_b32_e64 v190, v11, v191, s[6:7]
	global_store_dwordx4 v190, v[176:179], s[24:25]
	s_nop 1
	global_store_dwordx4 v190, v[180:183], s[24:25] offset:64
	s_and_saveexec_b64 s[0:1], s[4:5]
	s_cbranch_execz .LBB0_570
	v_ashrrev_i32_e32 v17, 31, v16
	s_waitcnt lgkmcnt(0)
	v_add_f32_e32 v2, v0, v1
	v_lshl_add_u64 v[0:1], v[16:17], 2, s[78:79]
	global_atomic_add_f32 v[0:1], v2, off

; DI u32x4 pk8(const f32x4& a, const f32x4& b) { u32x4 w; w.x = pk2(a[0], a[1]); w.y = pk2(a[2], a[3]); w.z = pk2(b[0], b[1]); w.w = pk2(b[2], b[3]); return w; }
; template <bool NT = false> DI void st_rows16(void* base, unsigned pitch_b, unsigned row0, unsigned col0, int fr, int fq, const u32x4& w0, const u32x4& w1) {
;   u32x4 x;
; #pragma unroll
;   for (int e = 0; e < 4; ++e) x[e] = (unsigned)__builtin_amdgcn_update_dpp(0, (int)w1[e], 0x128  , 0xf, 0xf, false);
;   const bool hi = fr >= 8;
;   u32x4 pa, pb;
; #pragma unroll
;   for (int e = 0; e < 4; ++e) { pa[e] = hi ? x[e] : w0[e]; pb[e] = hi ? w0[e] : x[e]; }
;   const unsigned ra = row0 + (unsigned)(fr & 7), ca = col0 + 8u * fq + (hi ? 32u : 0u), cb = col0 + 8u * fq + (hi ? 0u : 32u);
;   if (NT) { __builtin_nontemporal_store(pa, (u32x4*)((char*)base + (ra * pitch_b + ca * 2u))); __builtin_nontemporal_store(pb, (u32x4*)((char*)base + ((ra + 8u) * pitch_b + cb * 2u))); }
;   else { gst<u32x4>(base, ra * pitch_b + ca * 2u, pa); gst<u32x4>(base, (ra + 8u) * pitch_b + cb * 2u, pb); }
; }
;   DI void operator()(g8::Acc& acc, int pm, int pn, int wr, int wc, int fr, int fq) const {
;     using namespace g8;
; #pragma unroll
;     for (int ai = 0; ai < 2; ++ai)
; #pragma unroll
;       for (int m = 0; m < 4; ++m) {
;         const int row = pm * BM + ai * HALF + wr * 64 + m * 16 + fr; const float rs = rsqrtf(ssq[row] * (1.0f / DM) + RMS_EPS) * sc;
;         u32x4 wv[2];
; #pragma unroll
;         for (int bj = 0; bj < 2; ++bj) {
;           f32x4 o0 = acc[ai][bj][m][0] * rs, o1 = acc[ai][bj][m][1] * rs;
;           if (act) {
; #pragma unroll
;             for (int e = 0; e < 4; ++e) { const float a = fmaxf(o0[e], 0.f), b = fmaxf(o1[e], 0.f); o0[e] = a * a; o1[e] = b * b; } }
;           wv[bj] = pk8(o0, o1);
;         }
;         st_rows16(dst, (unsigned)ld * 2u, (unsigned)(row - fr), (unsigned)(pn * BM + wc * 64), fr, fq, wv[0], wv[1]);
;         __builtin_amdgcn_sched_barrier(0);
;       }
;   }
.LBB0_623:
	s_lshl_b32 s1, s46, 8
	s_add_i32 s1, s1, s14
	v_or_b32_e32 v150, s1, v140
	v_ashrrev_i32_e32 v151, 31, v150
	v_lshl_add_u64 v[150:151], v[150:151], 2, s[78:79]
	global_load_dword v152, v[150:151], off
	v_mov_b32_e32 v153, 0
	v_lshl_or_b32 v150, s0, 8, v145
	v_or_b32_e32 v151, v150, v143
	v_or_b32_e32 v157, s1, v142
	v_or_b32_e32 v150, v150, v144
	v_lshlrev_b32_e32 v151, 1, v151
	v_lshlrev_b32_e32 v157, 11, v157
	v_lshlrev_b32_e32 v150, 1, v150
	s_waitcnt vmcnt(0)
	v_fmamk_f32 v152, v152, 0x3a800000, v149
	v_mul_f32_e32 v158, 0x4b800000, v152
	v_cmp_gt_f32_e32 vcc, s21, v152
	s_nop 1
	v_cndmask_b32_e32 v152, v152, v158, vcc
	v_rsq_f32_e32 v152, v152
	v_add_u32_e32 v158, v151, v157
	v_mul_f32_e32 v159, 0x45800000, v152
	v_cndmask_b32_e32 v152, v152, v159, vcc
	v_mul_f32_e32 v152, 0x3db8aa3b, v152
	v_pk_mul_f32 v[118:119], v[118:119], v[152:153] op_sel_hi:[1,0]
	v_pk_mul_f32 v[116:117], v[116:117], v[152:153] op_sel_hi:[1,0]
	v_pk_mul_f32 v[114:115], v[114:115], v[152:153] op_sel_hi:[1,0]
	v_pk_mul_f32 v[112:113], v[112:113], v[152:153] op_sel_hi:[1,0]
	v_pk_mul_f32 v[126:127], v[126:127], v[152:153] op_sel_hi:[1,0]
	v_pk_mul_f32 v[124:125], v[124:125], v[152:153] op_sel_hi:[1,0]
	v_pk_mul_f32 v[122:123], v[122:123], v[152:153] op_sel_hi:[1,0]
	v_pk_mul_f32 v[120:121], v[120:121], v[152:153] op_sel_hi:[1,0]
	v_cvt_pk_bf16_f32 v168, v116, v117
	v_cvt_pk_bf16_f32 v169, v118, v119
	v_cvt_pk_bf16_f32 v170, v112, v113
	v_cvt_pk_bf16_f32 v171, v114, v115
	v_cvt_pk_bf16_f32 v164, v124, v125
	v_cvt_pk_bf16_f32 v165, v126, v127
	v_cvt_pk_bf16_f32 v166, v120, v121
	v_cvt_pk_bf16_f32 v167, v122, v123
	v_add3_u32 v181, v150, v157, s11
	v_cndmask_b32_e64 v180, v158, v181, s[4:5]
	global_store_dwordx4 v180, v[164:167], s[26:27]
	global_store_dwordx4 v180, v[168:171], s[26:27] offset:64
	s_or_b32 s0, s1, 16
	v_or_b32_e32 v112, s0, v140
	v_ashrrev_i32_e32 v113, 31, v112
	v_lshl_add_u64 v[112:113], v[112:113], 2, s[78:79]
	global_load_dword v112, v[112:113], off
	v_mov_b32_e32 v113, 0
	v_or_b32_e32 v117, s0, v142
	v_lshlrev_b32_e32 v117, 11, v117
	s_waitcnt vmcnt(0)
	v_fmamk_f32 v112, v112, 0x3a800000, v149
	v_mul_f32_e32 v118, 0x4b800000, v112
	v_cmp_gt_f32_e32 vcc, s21, v112
	s_nop 1
	v_cndmask_b32_e32 v112, v112, v118, vcc
	v_rsq_f32_e32 v112, v112
	v_add_u32_e32 v118, v151, v117
	v_mul_f32_e32 v119, 0x45800000, v112
	v_cndmask_b32_e32 v112, v112, v119, vcc
	v_mul_f32_e32 v112, 0x3db8aa3b, v112
	v_pk_mul_f32 v[102:103], v[102:103], v[112:113] op_sel_hi:[1,0]
	v_pk_mul_f32 v[100:101], v[100:101], v[112:113] op_sel_hi:[1,0]
	v_pk_mul_f32 v[98:99], v[98:99], v[112:113] op_sel_hi:[1,0]
	v_pk_mul_f32 v[96:97], v[96:97], v[112:113] op_sel_hi:[1,0]
	v_pk_mul_f32 v[110:111], v[110:111], v[112:113] op_sel_hi:[1,0]
	v_pk_mul_f32 v[108:109], v[108:109], v[112:113] op_sel_hi:[1,0]
	v_pk_mul_f32 v[106:107], v[106:107], v[112:113] op_sel_hi:[1,0]
	v_pk_mul_f32 v[104:105], v[104:105], v[112:113] op_sel_hi:[1,0]
	v_cvt_pk_bf16_f32 v168, v100, v101
	v_cvt_pk_bf16_f32 v169, v102, v103
	v_cvt_pk_bf16_f32 v170, v96, v97
	v_cvt_pk_bf16_f32 v171, v98, v99
	v_cvt_pk_bf16_f32 v164, v108, v109
	v_cvt_pk_bf16_f32 v165, v110, v111
	v_cvt_pk_bf16_f32 v166, v104, v105
	v_cvt_pk_bf16_f32 v167, v106, v107
	v_add3_u32 v181, v150, v117, s11
	v_cndmask_b32_e64 v180, v118, v181, s[4:5]
	global_store_dwordx4 v180, v[164:167], s[26:27]
	global_store_dwordx4 v180, v[168:171], s[26:27] offset:64
	s_or_b32 s0, s1, 32
	v_or_b32_e32 v96, s0, v140
	v_ashrrev_i32_e32 v97, 31, v96
	v_lshl_add_u64 v[96:97], v[96:97], 2, s[78:79]
	global_load_dword v96, v[96:97], off
	v_mov_b32_e32 v97, 0
	v_or_b32_e32 v101, s0, v142
	v_lshlrev_b32_e32 v101, 11, v101
	s_waitcnt vmcnt(0)
	v_fmamk_f32 v96, v96, 0x3a800000, v149
	v_mul_f32_e32 v102, 0x4b800000, v96
	v_cmp_gt_f32_e32 vcc, s21, v96
	s_nop 1
	v_cndmask_b32_e32 v96, v96, v102, vcc
	v_rsq_f32_e32 v96, v96
	v_add_u32_e32 v102, v151, v101
	v_mul_f32_e32 v103, 0x45800000, v96
	v_cndmask_b32_e32 v96, v96, v103, vcc
	v_mul_f32_e32 v96, 0x3db8aa3b, v96
	v_pk_mul_f32 v[86:87], v[86:87], v[96:97] op_sel_hi:[1,0]
	v_pk_mul_f32 v[84:85], v[84:85], v[96:97] op_sel_hi:[1,0]
	v_pk_mul_f32 v[82:83], v[82:83], v[96:97] op_sel_hi:[1,0]
	v_pk_mul_f32 v[80:81], v[80:81], v[96:97] op_sel_hi:[1,0]
	v_pk_mul_f32 v[94:95], v[94:95], v[96:97] op_sel_hi:[1,0]
	v_pk_mul_f32 v[92:93], v[92:93], v[96:97] op_sel_hi:[1,0]
	v_pk_mul_f32 v[90:91], v[90:91], v[96:97] op_sel_hi:[1,0]
	v_pk_mul_f32 v[88:89], v[88:89], v[96:97] op_sel_hi:[1,0]
	v_cvt_pk_bf16_f32 v168, v84, v85
	v_cvt_pk_bf16_f32 v169, v86, v87
	v_cvt_pk_bf16_f32 v170, v80, v81
	v_cvt_pk_bf16_f32 v171, v82, v83
	v_cvt_pk_bf16_f32 v164, v92, v93
	v_cvt_pk_bf16_f32 v165, v94, v95
	v_cvt_pk_bf16_f32 v166, v88, v89
	v_cvt_pk_bf16_f32 v167, v90, v91
	v_add3_u32 v181, v150, v101, s11
	v_cndmask_b32_e64 v180, v102, v181, s[4:5]
	global_store_dwordx4 v180, v[164:167], s[26:27]
	global_store_dwordx4 v180, v[168:171], s[26:27] offset:64
	s_or_b32 s0, s1, 48
	v_or_b32_e32 v80, s0, v140
	v_ashrrev_i32_e32 v81, 31, v80
	v_lshl_add_u64 v[80:81], v[80:81], 2, s[78:79]
	global_load_dword v80, v[80:81], off
	v_mov_b32_e32 v81, 0
	v_or_b32_e32 v85, s0, v142
	v_lshlrev_b32_e32 v85, 11, v85
	s_waitcnt vmcnt(0)
; DI u32x4 pk8(const f32x4& a, const f32x4& b) { u32x4 w; w.x = pk2(a[0], a[1]); w.y = pk2(a[2], a[3]); w.z = pk2(b[0], b[1]); w.w = pk2(b[2], b[3]); return w; }
; template <bool NT = false> DI void st_rows16(void* base, unsigned pitch_b, unsigned row0, unsigned col0, int fr, int fq, const u32x4& w0, const u32x4& w1) {
;   u32x4 x;
; #pragma unroll
;   for (int e = 0; e < 4; ++e) x[e] = (unsigned)__builtin_amdgcn_update_dpp(0, (int)w1[e], 0x128  , 0xf, 0xf, false);
;   const bool hi = fr >= 8;
;   u32x4 pa, pb;
; #pragma unroll
;   for (int e = 0; e < 4; ++e) { pa[e] = hi ? x[e] : w0[e]; pb[e] = hi ? w0[e] : x[e]; }
;   const unsigned ra = row0 + (unsigned)(fr & 7), ca = col0 + 8u * fq + (hi ? 32u : 0u), cb = col0 + 8u * fq + (hi ? 0u : 32u);
;   if (NT) { __builtin_nontemporal_store(pa, (u32x4*)((char*)base + (ra * pitch_b + ca * 2u))); __builtin_nontemporal_store(pb, (u32x4*)((char*)base + ((ra + 8u) * pitch_b + cb * 2u))); }
;   else { gst<u32x4>(base, ra * pitch_b + ca * 2u, pa); gst<u32x4>(base, (ra + 8u) * pitch_b + cb * 2u, pb); }
; }
;   DI void operator()(g8::Acc& acc, int pm, int pn, int wr, int wc, int fr, int fq) const {
;     using namespace g8;
; #pragma unroll
;     for (int ai = 0; ai < 2; ++ai)
; #pragma unroll
;       for (int m = 0; m < 4; ++m) {
;         const int row = pm * BM + ai * HALF + wr * 64 + m * 16 + fr; const float rs = rsqrtf(ssq[row] * (1.0f / DM) + RMS_EPS) * sc;
;         u32x4 wv[2];
; #pragma unroll
;         for (int bj = 0; bj < 2; ++bj) {
;           f32x4 o0 = acc[ai][bj][m][0] * rs, o1 = acc[ai][bj][m][1] * rs;
;           if (act) {
; #pragma unroll
;             for (int e = 0; e < 4; ++e) { const float a = fmaxf(o0[e], 0.f), b = fmaxf(o1[e], 0.f); o0[e] = a * a; o1[e] = b * b; } }
;           wv[bj] = pk8(o0, o1);
;         }
;         st_rows16(dst, (unsigned)ld * 2u, (unsigned)(row - fr), (unsigned)(pn * BM + wc * 64), fr, fq, wv[0], wv[1]);
;         __builtin_amdgcn_sched_barrier(0);
;       }
;   }
	v_fmamk_f32 v80, v80, 0x3a800000, v149
	v_mul_f32_e32 v86, 0x4b800000, v80
	v_cmp_gt_f32_e32 vcc, s21, v80
	s_nop 1
	v_cndmask_b32_e32 v80, v80, v86, vcc
	v_rsq_f32_e32 v80, v80
	v_add_u32_e32 v86, v151, v85
	v_mul_f32_e32 v87, 0x45800000, v80
	v_cndmask_b32_e32 v80, v80, v87, vcc
	v_mul_f32_e32 v80, 0x3db8aa3b, v80
	v_pk_mul_f32 v[70:71], v[70:71], v[80:81] op_sel_hi:[1,0]
	v_pk_mul_f32 v[68:69], v[68:69], v[80:81] op_sel_hi:[1,0]
	v_pk_mul_f32 v[66:67], v[66:67], v[80:81] op_sel_hi:[1,0]
	v_pk_mul_f32 v[64:65], v[64:65], v[80:81] op_sel_hi:[1,0]
	v_pk_mul_f32 v[78:79], v[78:79], v[80:81] op_sel_hi:[1,0]
	v_pk_mul_f32 v[76:77], v[76:77], v[80:81] op_sel_hi:[1,0]
	v_pk_mul_f32 v[74:75], v[74:75], v[80:81] op_sel_hi:[1,0]
	v_pk_mul_f32 v[72:73], v[72:73], v[80:81] op_sel_hi:[1,0]
	v_cvt_pk_bf16_f32 v168, v68, v69
	v_cvt_pk_bf16_f32 v169, v70, v71
	v_cvt_pk_bf16_f32 v170, v64, v65
	v_cvt_pk_bf16_f32 v171, v66, v67
	v_cvt_pk_bf16_f32 v164, v76, v77
	v_cvt_pk_bf16_f32 v165, v78, v79
	v_cvt_pk_bf16_f32 v166, v72, v73
	v_cvt_pk_bf16_f32 v167, v74, v75
	v_add3_u32 v181, v150, v85, s11
	v_cndmask_b32_e64 v180, v86, v181, s[4:5]
	global_store_dwordx4 v180, v[164:167], s[26:27]
	global_store_dwordx4 v180, v[168:171], s[26:27] offset:64
	s_add_i32 s0, s1, 0x80
	v_or_b32_e32 v64, s0, v140
	v_ashrrev_i32_e32 v65, 31, v64
	v_lshl_add_u64 v[64:65], v[64:65], 2, s[78:79]
	global_load_dword v64, v[64:65], off
	v_mov_b32_e32 v65, 0
	v_or_b32_e32 v69, s0, v142
	v_lshlrev_b32_e32 v69, 11, v69
	s_waitcnt vmcnt(0)
	v_fmamk_f32 v64, v64, 0x3a800000, v149
	v_mul_f32_e32 v70, 0x4b800000, v64
	v_cmp_gt_f32_e32 vcc, s21, v64
	s_nop 1
	v_cndmask_b32_e32 v64, v64, v70, vcc
	v_rsq_f32_e32 v64, v64
	v_add_u32_e32 v70, v151, v69
	v_mul_f32_e32 v71, 0x45800000, v64
	v_cndmask_b32_e32 v64, v64, v71, vcc
	v_mul_f32_e32 v64, 0x3db8aa3b, v64
	v_pk_mul_f32 v[54:55], v[54:55], v[64:65] op_sel_hi:[1,0]
	v_pk_mul_f32 v[52:53], v[52:53], v[64:65] op_sel_hi:[1,0]
	v_pk_mul_f32 v[50:51], v[50:51], v[64:65] op_sel_hi:[1,0]
	v_pk_mul_f32 v[48:49], v[48:49], v[64:65] op_sel_hi:[1,0]
	v_pk_mul_f32 v[62:63], v[62:63], v[64:65] op_sel_hi:[1,0]
	v_pk_mul_f32 v[60:61], v[60:61], v[64:65] op_sel_hi:[1,0]
	v_pk_mul_f32 v[58:59], v[58:59], v[64:65] op_sel_hi:[1,0]
	v_pk_mul_f32 v[56:57], v[56:57], v[64:65] op_sel_hi:[1,0]
	v_cvt_pk_bf16_f32 v168, v52, v53
	v_cvt_pk_bf16_f32 v169, v54, v55
	v_cvt_pk_bf16_f32 v170, v48, v49
	v_cvt_pk_bf16_f32 v171, v50, v51
	v_cvt_pk_bf16_f32 v164, v60, v61
	v_cvt_pk_bf16_f32 v165, v62, v63
	v_cvt_pk_bf16_f32 v166, v56, v57
	v_cvt_pk_bf16_f32 v167, v58, v59
	v_add3_u32 v181, v150, v69, s11
	v_cndmask_b32_e64 v180, v70, v181, s[4:5]
	global_store_dwordx4 v180, v[164:167], s[26:27]
	global_store_dwordx4 v180, v[168:171], s[26:27] offset:64
	s_add_i32 s0, s1, 0x90
	v_or_b32_e32 v48, s0, v140
	v_ashrrev_i32_e32 v49, 31, v48
	v_lshl_add_u64 v[48:49], v[48:49], 2, s[78:79]
	global_load_dword v48, v[48:49], off
	v_mov_b32_e32 v49, 0
	v_or_b32_e32 v53, s0, v142
	v_lshlrev_b32_e32 v53, 11, v53
	s_waitcnt vmcnt(0)
; DI u32x4 pk8(const f32x4& a, const f32x4& b) { u32x4 w; w.x = pk2(a[0], a[1]); w.y = pk2(a[2], a[3]); w.z = pk2(b[0], b[1]); w.w = pk2(b[2], b[3]); return w; }
; template <bool NT = false> DI void st_rows16(void* base, unsigned pitch_b, unsigned row0, unsigned col0, int fr, int fq, const u32x4& w0, const u32x4& w1) {
;   u32x4 x;
; #pragma unroll
;   for (int e = 0; e < 4; ++e) x[e] = (unsigned)__builtin_amdgcn_update_dpp(0, (int)w1[e], 0x128  , 0xf, 0xf, false);
;   const bool hi = fr >= 8;
;   u32x4 pa, pb;
; #pragma unroll
;   for (int e = 0; e < 4; ++e) { pa[e] = hi ? x[e] : w0[e]; pb[e] = hi ? w0[e] : x[e]; }
;   const unsigned ra = row0 + (unsigned)(fr & 7), ca = col0 + 8u * fq + (hi ? 32u : 0u), cb = col0 + 8u * fq + (hi ? 0u : 32u);
;   if (NT) { __builtin_nontemporal_store(pa, (u32x4*)((char*)base + (ra * pitch_b + ca * 2u))); __builtin_nontemporal_store(pb, (u32x4*)((char*)base + ((ra + 8u) * pitch_b + cb * 2u))); }
;   else { gst<u32x4>(base, ra * pitch_b + ca * 2u, pa); gst<u32x4>(base, (ra + 8u) * pitch_b + cb * 2u, pb); }
; }
;   DI void operator()(g8::Acc& acc, int pm, int pn, int wr, int wc, int fr, int fq) const {
;     using namespace g8;
; #pragma unroll
;     for (int ai = 0; ai < 2; ++ai)
; #pragma unroll
;       for (int m = 0; m < 4; ++m) {
;         const int row = pm * BM + ai * HALF + wr * 64 + m * 16 + fr; const float rs = rsqrtf(ssq[row] * (1.0f / DM) + RMS_EPS) * sc;
;         u32x4 wv[2];
; #pragma unroll
;         for (int bj = 0; bj < 2; ++bj) {
;           f32x4 o0 = acc[ai][bj][m][0] * rs, o1 = acc[ai][bj][m][1] * rs;
;           if (act) {
; #pragma unroll
;             for (int e = 0; e < 4; ++e) { const float a = fmaxf(o0[e], 0.f), b = fmaxf(o1[e], 0.f); o0[e] = a * a; o1[e] = b * b; } }
;           wv[bj] = pk8(o0, o1);
;         }
;         st_rows16(dst, (unsigned)ld * 2u, (unsigned)(row - fr), (unsigned)(pn * BM + wc * 64), fr, fq, wv[0], wv[1]);
;         __builtin_amdgcn_sched_barrier(0);
;       }
;   }
	v_fmamk_f32 v48, v48, 0x3a800000, v149
	v_mul_f32_e32 v54, 0x4b800000, v48
	v_cmp_gt_f32_e32 vcc, s21, v48
	s_nop 1
	v_cndmask_b32_e32 v48, v48, v54, vcc
	v_rsq_f32_e32 v48, v48
	v_add_u32_e32 v54, v151, v53
	v_mul_f32_e32 v55, 0x45800000, v48
	v_cndmask_b32_e32 v48, v48, v55, vcc
	v_mul_f32_e32 v48, 0x3db8aa3b, v48
	v_pk_mul_f32 v[38:39], v[38:39], v[48:49] op_sel_hi:[1,0]
	v_pk_mul_f32 v[36:37], v[36:37], v[48:49] op_sel_hi:[1,0]
	v_pk_mul_f32 v[34:35], v[34:35], v[48:49] op_sel_hi:[1,0]
	v_pk_mul_f32 v[32:33], v[32:33], v[48:49] op_sel_hi:[1,0]
	v_pk_mul_f32 v[46:47], v[46:47], v[48:49] op_sel_hi:[1,0]
	v_pk_mul_f32 v[44:45], v[44:45], v[48:49] op_sel_hi:[1,0]
	v_pk_mul_f32 v[42:43], v[42:43], v[48:49] op_sel_hi:[1,0]
	v_pk_mul_f32 v[40:41], v[40:41], v[48:49] op_sel_hi:[1,0]
	v_cvt_pk_bf16_f32 v168, v36, v37
	v_cvt_pk_bf16_f32 v169, v38, v39
	v_cvt_pk_bf16_f32 v170, v32, v33
	v_cvt_pk_bf16_f32 v171, v34, v35
	v_cvt_pk_bf16_f32 v164, v44, v45
	v_cvt_pk_bf16_f32 v165, v46, v47
	v_cvt_pk_bf16_f32 v166, v40, v41
	v_cvt_pk_bf16_f32 v167, v42, v43
	v_add3_u32 v181, v150, v53, s11
	v_cndmask_b32_e64 v180, v54, v181, s[4:5]
	global_store_dwordx4 v180, v[164:167], s[26:27]
	global_store_dwordx4 v180, v[168:171], s[26:27] offset:64
	s_add_i32 s0, s1, 0xa0
	v_or_b32_e32 v32, s0, v140
	v_ashrrev_i32_e32 v33, 31, v32
	v_lshl_add_u64 v[32:33], v[32:33], 2, s[78:79]
	global_load_dword v32, v[32:33], off
	v_mov_b32_e32 v33, 0
	v_or_b32_e32 v37, s0, v142
	v_lshlrev_b32_e32 v37, 11, v37
	s_waitcnt vmcnt(0)
	v_fmamk_f32 v32, v32, 0x3a800000, v149
	v_mul_f32_e32 v38, 0x4b800000, v32
	v_cmp_gt_f32_e32 vcc, s21, v32
	s_nop 1
	v_cndmask_b32_e32 v32, v32, v38, vcc
	v_rsq_f32_e32 v32, v32
	v_add_u32_e32 v38, v151, v37
	v_mul_f32_e32 v39, 0x45800000, v32
	v_cndmask_b32_e32 v32, v32, v39, vcc
	v_mul_f32_e32 v32, 0x3db8aa3b, v32
	v_pk_mul_f32 v[22:23], v[22:23], v[32:33] op_sel_hi:[1,0]
	v_pk_mul_f32 v[20:21], v[20:21], v[32:33] op_sel_hi:[1,0]
	v_pk_mul_f32 v[18:19], v[18:19], v[32:33] op_sel_hi:[1,0]
	v_pk_mul_f32 v[16:17], v[16:17], v[32:33] op_sel_hi:[1,0]
	v_pk_mul_f32 v[30:31], v[30:31], v[32:33] op_sel_hi:[1,0]
	v_pk_mul_f32 v[28:29], v[28:29], v[32:33] op_sel_hi:[1,0]
	v_pk_mul_f32 v[26:27], v[26:27], v[32:33] op_sel_hi:[1,0]
	v_pk_mul_f32 v[24:25], v[24:25], v[32:33] op_sel_hi:[1,0]
	v_cvt_pk_bf16_f32 v168, v20, v21
	v_cvt_pk_bf16_f32 v169, v22, v23
	v_cvt_pk_bf16_f32 v170, v16, v17
	v_cvt_pk_bf16_f32 v171, v18, v19
	v_cvt_pk_bf16_f32 v164, v28, v29
	v_cvt_pk_bf16_f32 v165, v30, v31
	v_cvt_pk_bf16_f32 v166, v24, v25
	v_cvt_pk_bf16_f32 v167, v26, v27
	v_add3_u32 v181, v150, v37, s11
	v_cndmask_b32_e64 v180, v38, v181, s[4:5]
	global_store_dwordx4 v180, v[164:167], s[26:27]
	global_store_dwordx4 v180, v[168:171], s[26:27] offset:64
	s_addk_i32 s1, 0xb0
	v_or_b32_e32 v16, s1, v140
	v_ashrrev_i32_e32 v17, 31, v16
	v_lshl_add_u64 v[16:17], v[16:17], 2, s[78:79]
	global_load_dword v16, v[16:17], off
	v_mov_b32_e32 v17, 0
	v_or_b32_e32 v21, s1, v142
	v_lshlrev_b32_e32 v21, 11, v21
	s_waitcnt vmcnt(0)
	v_fmamk_f32 v16, v16, 0x3a800000, v149
	v_mul_f32_e32 v22, 0x4b800000, v16
	v_cmp_gt_f32_e32 vcc, s21, v16
	s_nop 1
	v_cndmask_b32_e32 v16, v16, v22, vcc
	v_rsq_f32_e32 v16, v16
	v_add_u32_e32 v22, v151, v21
	v_mul_f32_e32 v23, 0x45800000, v16
	v_cndmask_b32_e32 v16, v16, v23, vcc
	v_mul_f32_e32 v16, 0x3db8aa3b, v16
	v_pk_mul_f32 v[6:7], v[6:7], v[16:17] op_sel_hi:[1,0]
	v_pk_mul_f32 v[4:5], v[4:5], v[16:17] op_sel_hi:[1,0]
	v_pk_mul_f32 v[2:3], v[2:3], v[16:17] op_sel_hi:[1,0]
	v_pk_mul_f32 v[0:1], v[0:1], v[16:17] op_sel_hi:[1,0]
	v_pk_mul_f32 v[12:13], v[12:13], v[16:17] op_sel_hi:[1,0]
	v_pk_mul_f32 v[14:15], v[14:15], v[16:17] op_sel_hi:[1,0]
	v_pk_mul_f32 v[8:9], v[8:9], v[16:17] op_sel_hi:[1,0]
	v_pk_mul_f32 v[10:11], v[10:11], v[16:17] op_sel_hi:[1,0]
	v_cvt_pk_bf16_f32 v168, v4, v5
	v_cvt_pk_bf16_f32 v169, v6, v7
	v_cvt_pk_bf16_f32 v170, v0, v1
	v_cvt_pk_bf16_f32 v171, v2, v3
	v_cvt_pk_bf16_f32 v167, v10, v11
	v_cvt_pk_bf16_f32 v166, v8, v9
	v_cvt_pk_bf16_f32 v165, v14, v15
	v_cvt_pk_bf16_f32 v164, v12, v13
	v_add3_u32 v181, v150, v21, s11
	v_cndmask_b32_e64 v180, v22, v181, s[4:5]
	global_store_dwordx4 v180, v[164:167], s[26:27]
	global_store_dwordx4 v180, v[168:171], s[26:27] offset:64
	s_andn2_b64 vcc, exec, s[38:39]
	s_mov_b64 s[0:1], -1
	s_cbranch_vccnz .LBB0_616
	s_andn2_b64 vcc, exec, s[6:7]
	s_cbranch_vccnz .LBB0_615
	s_barrier
	s_branch .LBB0_615

; template <class T> DI T gld_nt(const void* base, unsigned off) { return __builtin_nontemporal_load((const T*)((const char*)base + off)); }
; template <bool NT = false> DI void st_rows16(void* base, unsigned pitch_b, unsigned row0, unsigned col0, int fr, int fq, const u32x4& w0, const u32x4& w1) {
;   u32x4 x;
; #pragma unroll
;   for (int e = 0; e < 4; ++e) x[e] = (unsigned)__builtin_amdgcn_update_dpp(0, (int)w1[e], 0x128  , 0xf, 0xf, false);
;   const bool hi = fr >= 8;
;   u32x4 pa, pb;
; #pragma unroll
;   for (int e = 0; e < 4; ++e) { pa[e] = hi ? x[e] : w0[e]; pb[e] = hi ? w0[e] : x[e]; }
;   const unsigned ra = row0 + (unsigned)(fr & 7), ca = col0 + 8u * fq + (hi ? 32u : 0u), cb = col0 + 8u * fq + (hi ? 0u : 32u);
;   if (NT) { __builtin_nontemporal_store(pa, (u32x4*)((char*)base + (ra * pitch_b + ca * 2u))); __builtin_nontemporal_store(pb, (u32x4*)((char*)base + ((ra + 8u) * pitch_b + cb * 2u))); }
;   else { gst<u32x4>(base, ra * pitch_b + ca * 2u, pa); gst<u32x4>(base, (ra + 8u) * pitch_b + cb * 2u, pb); }
; }
;   DI void operator()(g8::Acc& acc, int pm, int pn, int wr, int wc, int fr, int fq) const {
;     using namespace g8;
; #pragma unroll
;     for (int ai = 0; ai < 2; ++ai)
; #pragma unroll
;       for (int m = 0; m < 4; ++m) {
;         const int row = pm * BM + ai * HALF + wr * 64 + m * 16 + fr; float s = 0.f; u32x4 wv[2];
; #pragma unroll
;         for (int bj = 0; bj < 2; ++bj) {
;           const int col8 = pn * BM + wc * 64 + bj * 32 + fq * 8; const unsigned eo = (unsigned)row * DM + (unsigned)col8;
;           f32x4 r0, r1;
;           if (resf) { r0 = gld_nt<f32x4>(resf, eo * 4u); r1 = gld_nt<f32x4>(resf, eo * 4u + 16u); }
;           else unpk8(gld_nt<u32x4>(resb, eo * 2u), r0, r1);
;           const f32x4 o0 = r0 + acc[ai][bj][m][0], o1 = r1 + acc[ai][bj][m][1];
;           if (outf) { gst<f32x4>(outf, eo * 4u, o0); gst<f32x4>(outf, eo * 4u + 16u, o1); }
;           wv[bj] = pk8(o0, o1);
;           s += o0[0] * o0[0] + o0[1] * o0[1] + o0[2] * o0[2] + o0[3] * o0[3] + o1[0] * o1[0] + o1[1] * o1[1] + o1[2] * o1[2] + o1[3] * o1[3];
;         }
;         if (outb) st_rows16(outb, DM * 2u, (unsigned)(row - fr), (unsigned)(pn * BM + wc * 64), fr, fq, wv[0], wv[1]);
;         s += __shfl_xor(s, 16); s += __shfl_xor(s, 32);
;         if (fq == 0) atomicAdd(ssq + row, s);
;         __builtin_amdgcn_sched_barrier(0);
;       }
.LBB0_694:
	s_lshl_b32 s21, s50, 8
	s_add_i32 s21, s21, s11
	v_lshl_or_b32 v141, s48, 8, v144
	v_or_b32_e32 v140, s21, v142
	v_lshlrev_b32_e32 v154, 1, v141
	v_lshl_add_u32 v152, v140, 11, v154
	global_load_dwordx4 v[156:159], v152, s[24:25] nt
	v_or_b32_e32 v152, 64, v152
	global_load_dwordx4 v[160:163], v152, s[24:25] nt
	v_or_b32_e32 v152, v141, v146
	v_or_b32_e32 v141, v141, v147
	v_lshlrev_b32_e32 v153, 1, v152
	v_lshl_add_u32 v152, v141, 1, v151
	s_waitcnt vmcnt(0)
	v_lshlrev_b32_e32 v164, 16, v156
	v_and_b32_e32 v165, 0xffff0000, v156
	v_lshlrev_b32_e32 v156, 16, v157
	v_and_b32_e32 v157, 0xffff0000, v157
	v_pk_add_f32 v[126:127], v[126:127], v[156:157]
	v_pk_add_f32 v[124:125], v[124:125], v[164:165]
	v_lshlrev_b32_e32 v156, 16, v160
	v_and_b32_e32 v157, 0xffff0000, v160
	v_lshlrev_b32_e32 v166, 16, v158
	v_and_b32_e32 v167, 0xffff0000, v158
	v_lshlrev_b32_e32 v158, 16, v159
	v_and_b32_e32 v159, 0xffff0000, v159
	v_cvt_pk_bf16_f32 v176, v124, v125
	v_mul_f32_e32 v125, v125, v125
	v_pk_add_f32 v[116:117], v[116:117], v[156:157]
	v_pk_add_f32 v[122:123], v[122:123], v[158:159]
	v_lshlrev_b32_e32 v158, 16, v161
	v_and_b32_e32 v159, 0xffff0000, v161
	v_fmac_f32_e32 v125, v124, v124
	v_mul_f32_e32 v124, v117, v117
	v_pk_add_f32 v[158:159], v[118:119], v[158:159]
	v_fmac_f32_e32 v124, v116, v116
	v_lshlrev_b32_e32 v160, 16, v162
	v_and_b32_e32 v161, 0xffff0000, v162
	v_fmac_f32_e32 v125, v126, v126
	v_fmac_f32_e32 v124, v158, v158
	v_pk_add_f32 v[120:121], v[120:121], v[166:167]
	v_pk_add_f32 v[112:113], v[112:113], v[160:161]
	v_fmac_f32_e32 v125, v127, v127
	v_fmac_f32_e32 v124, v159, v159
	v_lshlrev_b32_e32 v162, 16, v163
	v_and_b32_e32 v163, 0xffff0000, v163
	v_fmac_f32_e32 v125, v120, v120
	v_fmac_f32_e32 v124, v112, v112
	v_pk_add_f32 v[156:157], v[114:115], v[162:163]
	v_fmac_f32_e32 v125, v121, v121
	v_fmac_f32_e32 v124, v113, v113
	v_fmac_f32_e32 v125, v122, v122
	v_fmac_f32_e32 v124, v156, v156
	v_fmac_f32_e32 v125, v123, v123
	v_fmac_f32_e32 v124, v157, v157
	v_cvt_pk_bf16_f32 v182, v112, v113
	v_add_f32_e32 v112, v125, v124
	ds_bpermute_b32 v113, v214, v112
	v_cvt_pk_bf16_f32 v179, v122, v123
	v_cvt_pk_bf16_f32 v183, v156, v157
	v_cvt_pk_bf16_f32 v181, v158, v159
	v_cvt_pk_bf16_f32 v180, v116, v117
	s_waitcnt lgkmcnt(0)
	v_add_f32_e32 v112, v112, v113
	ds_bpermute_b32 v113, v213, v112
	v_or_b32_e32 v122, s21, v145
	v_cvt_pk_bf16_f32 v177, v126, v127
	v_cvt_pk_bf16_f32 v178, v120, v121
	v_lshlrev_b32_e32 v122, 11, v122
	v_add_u32_e32 v123, v153, v122
	v_add_u32_e32 v191, v152, v122
	v_cndmask_b32_e64 v190, v123, v191, s[6:7]
	global_store_dwordx4 v190, v[176:179], s[12:13]
	s_nop 1
	global_store_dwordx4 v190, v[180:183], s[12:13] offset:64
	s_and_saveexec_b64 s[0:1], s[4:5]
	s_cbranch_execz .LBB0_696
	v_ashrrev_i32_e32 v141, 31, v140
	v_lshl_add_u64 v[114:115], v[140:141], 2, s[16:17]
	s_waitcnt lgkmcnt(0)
	v_add_f32_e32 v112, v112, v113
	global_atomic_add_f32 v[114:115], v112, off
.LBB0_696:
	s_or_b64 exec, exec, s[0:1]
	s_or_b32 s0, s21, 16
	v_or_b32_e32 v112, s0, v142
	s_waitcnt lgkmcnt(0)
	v_lshl_add_u32 v113, v112, 11, v154
	global_load_dwordx4 v[114:117], v113, s[24:25] nt
	v_or_b32_e32 v113, 64, v113
	global_load_dwordx4 v[118:121], v113, s[24:25] nt
	s_waitcnt vmcnt(1)
	v_lshlrev_b32_e32 v122, 16, v114
	v_and_b32_e32 v123, 0xffff0000, v114
	v_lshlrev_b32_e32 v114, 16, v115
	v_and_b32_e32 v115, 0xffff0000, v115
	v_pk_add_f32 v[110:111], v[110:111], v[114:115]
	v_pk_add_f32 v[108:109], v[108:109], v[122:123]
	s_waitcnt vmcnt(0)
	v_lshlrev_b32_e32 v114, 16, v118
	v_and_b32_e32 v115, 0xffff0000, v118
	v_lshlrev_b32_e32 v124, 16, v116
	v_and_b32_e32 v125, 0xffff0000, v116
	v_lshlrev_b32_e32 v116, 16, v117
	v_and_b32_e32 v117, 0xffff0000, v117
	v_cvt_pk_bf16_f32 v176, v108, v109
	v_mul_f32_e32 v109, v109, v109
	v_pk_add_f32 v[100:101], v[100:101], v[114:115]
	v_pk_add_f32 v[106:107], v[106:107], v[116:117]
	v_lshlrev_b32_e32 v116, 16, v119
	v_and_b32_e32 v117, 0xffff0000, v119
	v_fmac_f32_e32 v109, v108, v108
	v_mul_f32_e32 v108, v101, v101
	v_pk_add_f32 v[116:117], v[102:103], v[116:117]
	v_fmac_f32_e32 v108, v100, v100
	v_lshlrev_b32_e32 v118, 16, v120
	v_and_b32_e32 v119, 0xffff0000, v120
	v_fmac_f32_e32 v109, v110, v110
	v_fmac_f32_e32 v108, v116, v116
	v_pk_add_f32 v[104:105], v[104:105], v[124:125]
	v_pk_add_f32 v[96:97], v[96:97], v[118:119]
	v_fmac_f32_e32 v109, v111, v111
	v_fmac_f32_e32 v108, v117, v117
	v_lshlrev_b32_e32 v120, 16, v121
	v_and_b32_e32 v121, 0xffff0000, v121
	v_fmac_f32_e32 v109, v104, v104
	v_fmac_f32_e32 v108, v96, v96
	v_pk_add_f32 v[114:115], v[98:99], v[120:121]
	v_fmac_f32_e32 v109, v105, v105
	v_fmac_f32_e32 v108, v97, v97
	v_fmac_f32_e32 v109, v106, v106
	v_fmac_f32_e32 v108, v114, v114
	v_fmac_f32_e32 v109, v107, v107
	v_fmac_f32_e32 v108, v115, v115
	v_cvt_pk_bf16_f32 v182, v96, v97
	v_add_f32_e32 v96, v109, v108
	ds_bpermute_b32 v97, v214, v96
	v_cvt_pk_bf16_f32 v179, v106, v107
	v_cvt_pk_bf16_f32 v183, v114, v115
	v_cvt_pk_bf16_f32 v181, v116, v117
	v_cvt_pk_bf16_f32 v180, v100, v101
	s_waitcnt lgkmcnt(0)
	v_add_f32_e32 v96, v96, v97
	ds_bpermute_b32 v97, v213, v96
	v_or_b32_e32 v106, s0, v145
	v_cvt_pk_bf16_f32 v177, v110, v111
	v_cvt_pk_bf16_f32 v178, v104, v105
	v_lshlrev_b32_e32 v106, 11, v106
	v_add_u32_e32 v107, v153, v106
	v_add_u32_e32 v191, v152, v106
	v_cndmask_b32_e64 v190, v107, v191, s[6:7]
	global_store_dwordx4 v190, v[176:179], s[12:13]
	s_nop 1
	global_store_dwordx4 v190, v[180:183], s[12:13] offset:64
	s_and_saveexec_b64 s[0:1], s[4:5]
	s_cbranch_execz .LBB0_698
	v_ashrrev_i32_e32 v113, 31, v112
	v_lshl_add_u64 v[98:99], v[112:113], 2, s[16:17]
	s_waitcnt lgkmcnt(0)
	v_add_f32_e32 v96, v96, v97
	global_atomic_add_f32 v[98:99], v96, off
; template <class T> DI T gld_nt(const void* base, unsigned off) { return __builtin_nontemporal_load((const T*)((const char*)base + off)); }
; template <bool NT = false> DI void st_rows16(void* base, unsigned pitch_b, unsigned row0, unsigned col0, int fr, int fq, const u32x4& w0, const u32x4& w1) {
;   u32x4 x;
; #pragma unroll
;   for (int e = 0; e < 4; ++e) x[e] = (unsigned)__builtin_amdgcn_update_dpp(0, (int)w1[e], 0x128  , 0xf, 0xf, false);
;   const bool hi = fr >= 8;
;   u32x4 pa, pb;
; #pragma unroll
;   for (int e = 0; e < 4; ++e) { pa[e] = hi ? x[e] : w0[e]; pb[e] = hi ? w0[e] : x[e]; }
;   const unsigned ra = row0 + (unsigned)(fr & 7), ca = col0 + 8u * fq + (hi ? 32u : 0u), cb = col0 + 8u * fq + (hi ? 0u : 32u);
;   if (NT) { __builtin_nontemporal_store(pa, (u32x4*)((char*)base + (ra * pitch_b + ca * 2u))); __builtin_nontemporal_store(pb, (u32x4*)((char*)base + ((ra + 8u) * pitch_b + cb * 2u))); }
;   else { gst<u32x4>(base, ra * pitch_b + ca * 2u, pa); gst<u32x4>(base, (ra + 8u) * pitch_b + cb * 2u, pb); }
; }
;   DI void operator()(g8::Acc& acc, int pm, int pn, int wr, int wc, int fr, int fq) const {
;     using namespace g8;
; #pragma unroll
;     for (int ai = 0; ai < 2; ++ai)
; #pragma unroll
;       for (int m = 0; m < 4; ++m) {
;         const int row = pm * BM + ai * HALF + wr * 64 + m * 16 + fr; float s = 0.f; u32x4 wv[2];
; #pragma unroll
;         for (int bj = 0; bj < 2; ++bj) {
;           const int col8 = pn * BM + wc * 64 + bj * 32 + fq * 8; const unsigned eo = (unsigned)row * DM + (unsigned)col8;
;           f32x4 r0, r1;
;           if (resf) { r0 = gld_nt<f32x4>(resf, eo * 4u); r1 = gld_nt<f32x4>(resf, eo * 4u + 16u); }
;           else unpk8(gld_nt<u32x4>(resb, eo * 2u), r0, r1);
;           const f32x4 o0 = r0 + acc[ai][bj][m][0], o1 = r1 + acc[ai][bj][m][1];
;           if (outf) { gst<f32x4>(outf, eo * 4u, o0); gst<f32x4>(outf, eo * 4u + 16u, o1); }
;           wv[bj] = pk8(o0, o1);
;           s += o0[0] * o0[0] + o0[1] * o0[1] + o0[2] * o0[2] + o0[3] * o0[3] + o1[0] * o1[0] + o1[1] * o1[1] + o1[2] * o1[2] + o1[3] * o1[3];
;         }
;         if (outb) st_rows16(outb, DM * 2u, (unsigned)(row - fr), (unsigned)(pn * BM + wc * 64), fr, fq, wv[0], wv[1]);
;         s += __shfl_xor(s, 16); s += __shfl_xor(s, 32);
;         if (fq == 0) atomicAdd(ssq + row, s);
;         __builtin_amdgcn_sched_barrier(0);
;       }
.LBB0_698:
	s_or_b64 exec, exec, s[0:1]
	s_or_b32 s0, s21, 32
	v_or_b32_e32 v96, s0, v142
	s_waitcnt lgkmcnt(0)
	v_lshl_add_u32 v97, v96, 11, v154
	global_load_dwordx4 v[98:101], v97, s[24:25] nt
	v_or_b32_e32 v97, 64, v97
	global_load_dwordx4 v[102:105], v97, s[24:25] nt
	s_waitcnt vmcnt(1)
	v_lshlrev_b32_e32 v106, 16, v98
	v_and_b32_e32 v107, 0xffff0000, v98
	v_lshlrev_b32_e32 v98, 16, v99
	v_and_b32_e32 v99, 0xffff0000, v99
	v_pk_add_f32 v[94:95], v[94:95], v[98:99]
	v_pk_add_f32 v[92:93], v[92:93], v[106:107]
	s_waitcnt vmcnt(0)
	v_lshlrev_b32_e32 v98, 16, v102
	v_and_b32_e32 v99, 0xffff0000, v102
	v_lshlrev_b32_e32 v108, 16, v100
	v_and_b32_e32 v109, 0xffff0000, v100
	v_lshlrev_b32_e32 v100, 16, v101
	v_and_b32_e32 v101, 0xffff0000, v101
	v_cvt_pk_bf16_f32 v176, v92, v93
	v_mul_f32_e32 v93, v93, v93
	v_pk_add_f32 v[84:85], v[84:85], v[98:99]
	v_pk_add_f32 v[90:91], v[90:91], v[100:101]
	v_lshlrev_b32_e32 v100, 16, v103
	v_and_b32_e32 v101, 0xffff0000, v103
	v_fmac_f32_e32 v93, v92, v92
	v_mul_f32_e32 v92, v85, v85
	v_pk_add_f32 v[100:101], v[86:87], v[100:101]
	v_fmac_f32_e32 v92, v84, v84
	v_lshlrev_b32_e32 v102, 16, v104
	v_and_b32_e32 v103, 0xffff0000, v104
	v_fmac_f32_e32 v93, v94, v94
	v_fmac_f32_e32 v92, v100, v100
	v_pk_add_f32 v[88:89], v[88:89], v[108:109]
	v_pk_add_f32 v[80:81], v[80:81], v[102:103]
	v_fmac_f32_e32 v93, v95, v95
	v_fmac_f32_e32 v92, v101, v101
	v_lshlrev_b32_e32 v104, 16, v105
	v_and_b32_e32 v105, 0xffff0000, v105
	v_fmac_f32_e32 v93, v88, v88
	v_fmac_f32_e32 v92, v80, v80
	v_pk_add_f32 v[98:99], v[82:83], v[104:105]
	v_fmac_f32_e32 v93, v89, v89
	v_fmac_f32_e32 v92, v81, v81
	v_fmac_f32_e32 v93, v90, v90
	v_fmac_f32_e32 v92, v98, v98
	v_fmac_f32_e32 v93, v91, v91
	v_fmac_f32_e32 v92, v99, v99
	v_cvt_pk_bf16_f32 v182, v80, v81
	v_add_f32_e32 v80, v93, v92
	ds_bpermute_b32 v81, v214, v80
	v_cvt_pk_bf16_f32 v179, v90, v91
	v_cvt_pk_bf16_f32 v183, v98, v99
	v_cvt_pk_bf16_f32 v181, v100, v101
	v_cvt_pk_bf16_f32 v180, v84, v85
	s_waitcnt lgkmcnt(0)
	v_add_f32_e32 v80, v80, v81
	ds_bpermute_b32 v81, v213, v80
	v_or_b32_e32 v90, s0, v145
	v_cvt_pk_bf16_f32 v177, v94, v95
	v_cvt_pk_bf16_f32 v178, v88, v89
	v_lshlrev_b32_e32 v90, 11, v90
	v_add_u32_e32 v91, v153, v90
	v_add_u32_e32 v191, v152, v90
	v_cndmask_b32_e64 v190, v91, v191, s[6:7]
	global_store_dwordx4 v190, v[176:179], s[12:13]
	s_nop 1
	global_store_dwordx4 v190, v[180:183], s[12:13] offset:64
	s_and_saveexec_b64 s[0:1], s[4:5]
	s_cbranch_execz .LBB0_700
	v_ashrrev_i32_e32 v97, 31, v96
	v_lshl_add_u64 v[82:83], v[96:97], 2, s[16:17]
	s_waitcnt lgkmcnt(0)
	v_add_f32_e32 v80, v80, v81
	global_atomic_add_f32 v[82:83], v80, off
.LBB0_700:
	s_or_b64 exec, exec, s[0:1]
	s_or_b32 s0, s21, 48
	v_or_b32_e32 v80, s0, v142
	s_waitcnt lgkmcnt(0)
	v_lshl_add_u32 v81, v80, 11, v154
	global_load_dwordx4 v[82:85], v81, s[24:25] nt
	v_or_b32_e32 v81, 64, v81
	global_load_dwordx4 v[86:89], v81, s[24:25] nt
	s_waitcnt vmcnt(1)
	v_lshlrev_b32_e32 v90, 16, v82
	v_and_b32_e32 v91, 0xffff0000, v82
	v_lshlrev_b32_e32 v82, 16, v83
	v_and_b32_e32 v83, 0xffff0000, v83
	v_pk_add_f32 v[78:79], v[78:79], v[82:83]
	v_pk_add_f32 v[76:77], v[76:77], v[90:91]
	s_waitcnt vmcnt(0)
	v_lshlrev_b32_e32 v82, 16, v86
	v_and_b32_e32 v83, 0xffff0000, v86
	v_lshlrev_b32_e32 v92, 16, v84
	v_and_b32_e32 v93, 0xffff0000, v84
	v_lshlrev_b32_e32 v84, 16, v85
	v_and_b32_e32 v85, 0xffff0000, v85
	v_cvt_pk_bf16_f32 v176, v76, v77
	v_mul_f32_e32 v77, v77, v77
	v_pk_add_f32 v[68:69], v[68:69], v[82:83]
	v_pk_add_f32 v[74:75], v[74:75], v[84:85]
	v_lshlrev_b32_e32 v84, 16, v87
	v_and_b32_e32 v85, 0xffff0000, v87
	v_fmac_f32_e32 v77, v76, v76
	v_mul_f32_e32 v76, v69, v69
	v_pk_add_f32 v[84:85], v[70:71], v[84:85]
	v_fmac_f32_e32 v76, v68, v68
	v_lshlrev_b32_e32 v86, 16, v88
	v_and_b32_e32 v87, 0xffff0000, v88
	v_fmac_f32_e32 v77, v78, v78
	v_fmac_f32_e32 v76, v84, v84
	v_pk_add_f32 v[72:73], v[72:73], v[92:93]
	v_pk_add_f32 v[64:65], v[64:65], v[86:87]
	v_fmac_f32_e32 v77, v79, v79
	v_fmac_f32_e32 v76, v85, v85
	v_lshlrev_b32_e32 v88, 16, v89
	v_and_b32_e32 v89, 0xffff0000, v89
	v_fmac_f32_e32 v77, v72, v72
	v_fmac_f32_e32 v76, v64, v64
	v_pk_add_f32 v[82:83], v[66:67], v[88:89]
	v_fmac_f32_e32 v77, v73, v73
	v_fmac_f32_e32 v76, v65, v65
	v_fmac_f32_e32 v77, v74, v74
	v_fmac_f32_e32 v76, v82, v82
	v_fmac_f32_e32 v77, v75, v75
	v_fmac_f32_e32 v76, v83, v83
	v_cvt_pk_bf16_f32 v182, v64, v65
	v_add_f32_e32 v64, v77, v76
	ds_bpermute_b32 v65, v214, v64
	v_cvt_pk_bf16_f32 v179, v74, v75
	v_cvt_pk_bf16_f32 v183, v82, v83
	v_cvt_pk_bf16_f32 v181, v84, v85
	v_cvt_pk_bf16_f32 v180, v68, v69
	s_waitcnt lgkmcnt(0)
	v_add_f32_e32 v64, v64, v65
	ds_bpermute_b32 v65, v213, v64
	v_or_b32_e32 v74, s0, v145
	v_cvt_pk_bf16_f32 v177, v78, v79
	v_cvt_pk_bf16_f32 v178, v72, v73
	v_lshlrev_b32_e32 v74, 11, v74
	v_add_u32_e32 v75, v153, v74
	v_add_u32_e32 v191, v152, v74
	v_cndmask_b32_e64 v190, v75, v191, s[6:7]
	global_store_dwordx4 v190, v[176:179], s[12:13]
	s_nop 1
	global_store_dwordx4 v190, v[180:183], s[12:13] offset:64
	s_and_saveexec_b64 s[0:1], s[4:5]
	s_cbranch_execz .LBB0_702
	v_ashrrev_i32_e32 v81, 31, v80
	v_lshl_add_u64 v[66:67], v[80:81], 2, s[16:17]
	s_waitcnt lgkmcnt(0)
	v_add_f32_e32 v64, v64, v65
	global_atomic_add_f32 v[66:67], v64, off
; template <class T> DI T gld_nt(const void* base, unsigned off) { return __builtin_nontemporal_load((const T*)((const char*)base + off)); }
; template <bool NT = false> DI void st_rows16(void* base, unsigned pitch_b, unsigned row0, unsigned col0, int fr, int fq, const u32x4& w0, const u32x4& w1) {
;   u32x4 x;
; #pragma unroll
;   for (int e = 0; e < 4; ++e) x[e] = (unsigned)__builtin_amdgcn_update_dpp(0, (int)w1[e], 0x128  , 0xf, 0xf, false);
;   const bool hi = fr >= 8;
;   u32x4 pa, pb;
; #pragma unroll
;   for (int e = 0; e < 4; ++e) { pa[e] = hi ? x[e] : w0[e]; pb[e] = hi ? w0[e] : x[e]; }
;   const unsigned ra = row0 + (unsigned)(fr & 7), ca = col0 + 8u * fq + (hi ? 32u : 0u), cb = col0 + 8u * fq + (hi ? 0u : 32u);
;   if (NT) { __builtin_nontemporal_store(pa, (u32x4*)((char*)base + (ra * pitch_b + ca * 2u))); __builtin_nontemporal_store(pb, (u32x4*)((char*)base + ((ra + 8u) * pitch_b + cb * 2u))); }
;   else { gst<u32x4>(base, ra * pitch_b + ca * 2u, pa); gst<u32x4>(base, (ra + 8u) * pitch_b + cb * 2u, pb); }
; }
;   DI void operator()(g8::Acc& acc, int pm, int pn, int wr, int wc, int fr, int fq) const {
;     using namespace g8;
; #pragma unroll
;     for (int ai = 0; ai < 2; ++ai)
; #pragma unroll
;       for (int m = 0; m < 4; ++m) {
;         const int row = pm * BM + ai * HALF + wr * 64 + m * 16 + fr; float s = 0.f; u32x4 wv[2];
; #pragma unroll
;         for (int bj = 0; bj < 2; ++bj) {
;           const int col8 = pn * BM + wc * 64 + bj * 32 + fq * 8; const unsigned eo = (unsigned)row * DM + (unsigned)col8;
;           f32x4 r0, r1;
;           if (resf) { r0 = gld_nt<f32x4>(resf, eo * 4u); r1 = gld_nt<f32x4>(resf, eo * 4u + 16u); }
;           else unpk8(gld_nt<u32x4>(resb, eo * 2u), r0, r1);
;           const f32x4 o0 = r0 + acc[ai][bj][m][0], o1 = r1 + acc[ai][bj][m][1];
;           if (outf) { gst<f32x4>(outf, eo * 4u, o0); gst<f32x4>(outf, eo * 4u + 16u, o1); }
;           wv[bj] = pk8(o0, o1);
;           s += o0[0] * o0[0] + o0[1] * o0[1] + o0[2] * o0[2] + o0[3] * o0[3] + o1[0] * o1[0] + o1[1] * o1[1] + o1[2] * o1[2] + o1[3] * o1[3];
;         }
;         if (outb) st_rows16(outb, DM * 2u, (unsigned)(row - fr), (unsigned)(pn * BM + wc * 64), fr, fq, wv[0], wv[1]);
;         s += __shfl_xor(s, 16); s += __shfl_xor(s, 32);
;         if (fq == 0) atomicAdd(ssq + row, s);
;         __builtin_amdgcn_sched_barrier(0);
;       }
.LBB0_702:
	s_or_b64 exec, exec, s[0:1]
	s_add_i32 s0, s21, 0x80
	v_or_b32_e32 v64, s0, v142
	s_waitcnt lgkmcnt(0)
	v_lshl_add_u32 v65, v64, 11, v154
	global_load_dwordx4 v[66:69], v65, s[24:25] nt
	v_or_b32_e32 v65, 64, v65
	global_load_dwordx4 v[70:73], v65, s[24:25] nt
	s_waitcnt vmcnt(1)
	v_lshlrev_b32_e32 v74, 16, v66
	v_and_b32_e32 v75, 0xffff0000, v66
	v_lshlrev_b32_e32 v66, 16, v67
	v_and_b32_e32 v67, 0xffff0000, v67
	v_pk_add_f32 v[62:63], v[62:63], v[66:67]
	v_pk_add_f32 v[60:61], v[60:61], v[74:75]
	s_waitcnt vmcnt(0)
	v_lshlrev_b32_e32 v66, 16, v70
	v_and_b32_e32 v67, 0xffff0000, v70
	v_lshlrev_b32_e32 v76, 16, v68
	v_and_b32_e32 v77, 0xffff0000, v68
	v_lshlrev_b32_e32 v68, 16, v69
	v_and_b32_e32 v69, 0xffff0000, v69
	v_cvt_pk_bf16_f32 v176, v60, v61
	v_mul_f32_e32 v61, v61, v61
	v_pk_add_f32 v[52:53], v[52:53], v[66:67]
	v_pk_add_f32 v[58:59], v[58:59], v[68:69]
	v_lshlrev_b32_e32 v68, 16, v71
	v_and_b32_e32 v69, 0xffff0000, v71
	v_fmac_f32_e32 v61, v60, v60
	v_mul_f32_e32 v60, v53, v53
	v_pk_add_f32 v[68:69], v[54:55], v[68:69]
	v_fmac_f32_e32 v60, v52, v52
	v_lshlrev_b32_e32 v70, 16, v72
	v_and_b32_e32 v71, 0xffff0000, v72
	v_fmac_f32_e32 v61, v62, v62
	v_fmac_f32_e32 v60, v68, v68
	v_pk_add_f32 v[56:57], v[56:57], v[76:77]
	v_pk_add_f32 v[48:49], v[48:49], v[70:71]
	v_fmac_f32_e32 v61, v63, v63
	v_fmac_f32_e32 v60, v69, v69
	v_lshlrev_b32_e32 v72, 16, v73
	v_and_b32_e32 v73, 0xffff0000, v73
	v_fmac_f32_e32 v61, v56, v56
	v_fmac_f32_e32 v60, v48, v48
	v_pk_add_f32 v[66:67], v[50:51], v[72:73]
	v_fmac_f32_e32 v61, v57, v57
	v_fmac_f32_e32 v60, v49, v49
	v_fmac_f32_e32 v61, v58, v58
	v_fmac_f32_e32 v60, v66, v66
	v_fmac_f32_e32 v61, v59, v59
	v_fmac_f32_e32 v60, v67, v67
	v_cvt_pk_bf16_f32 v182, v48, v49
	v_add_f32_e32 v48, v61, v60
	ds_bpermute_b32 v49, v214, v48
	v_cvt_pk_bf16_f32 v179, v58, v59
	v_cvt_pk_bf16_f32 v183, v66, v67
	v_cvt_pk_bf16_f32 v181, v68, v69
	v_cvt_pk_bf16_f32 v180, v52, v53
	s_waitcnt lgkmcnt(0)
	v_add_f32_e32 v48, v48, v49
	ds_bpermute_b32 v49, v213, v48
	v_or_b32_e32 v58, s0, v145
	v_cvt_pk_bf16_f32 v177, v62, v63
	v_cvt_pk_bf16_f32 v178, v56, v57
	v_lshlrev_b32_e32 v58, 11, v58
	v_add_u32_e32 v59, v153, v58
	v_add_u32_e32 v191, v152, v58
	v_cndmask_b32_e64 v190, v59, v191, s[6:7]
	global_store_dwordx4 v190, v[176:179], s[12:13]
	s_nop 1
	global_store_dwordx4 v190, v[180:183], s[12:13] offset:64
	s_and_saveexec_b64 s[0:1], s[4:5]
	s_cbranch_execz .LBB0_704
	v_ashrrev_i32_e32 v65, 31, v64
	v_lshl_add_u64 v[50:51], v[64:65], 2, s[16:17]
	s_waitcnt lgkmcnt(0)
	v_add_f32_e32 v48, v48, v49
	global_atomic_add_f32 v[50:51], v48, off
.LBB0_704:
	s_or_b64 exec, exec, s[0:1]
	s_add_i32 s0, s21, 0x90
	v_or_b32_e32 v48, s0, v142
	s_waitcnt lgkmcnt(0)
	v_lshl_add_u32 v49, v48, 11, v154
	global_load_dwordx4 v[50:53], v49, s[24:25] nt
	v_or_b32_e32 v49, 64, v49
	global_load_dwordx4 v[54:57], v49, s[24:25] nt
	s_waitcnt vmcnt(1)
	v_lshlrev_b32_e32 v58, 16, v50
	v_and_b32_e32 v59, 0xffff0000, v50
	v_lshlrev_b32_e32 v50, 16, v51
	v_and_b32_e32 v51, 0xffff0000, v51
	v_pk_add_f32 v[46:47], v[46:47], v[50:51]
	v_pk_add_f32 v[44:45], v[44:45], v[58:59]
	s_waitcnt vmcnt(0)
	v_lshlrev_b32_e32 v50, 16, v54
	v_and_b32_e32 v51, 0xffff0000, v54
	v_lshlrev_b32_e32 v60, 16, v52
	v_and_b32_e32 v61, 0xffff0000, v52
	v_lshlrev_b32_e32 v52, 16, v53
	v_and_b32_e32 v53, 0xffff0000, v53
	v_cvt_pk_bf16_f32 v176, v44, v45
	v_mul_f32_e32 v45, v45, v45
	v_pk_add_f32 v[36:37], v[36:37], v[50:51]
	v_pk_add_f32 v[42:43], v[42:43], v[52:53]
	v_lshlrev_b32_e32 v52, 16, v55
	v_and_b32_e32 v53, 0xffff0000, v55
	v_fmac_f32_e32 v45, v44, v44
	v_mul_f32_e32 v44, v37, v37
	v_pk_add_f32 v[52:53], v[38:39], v[52:53]
	v_fmac_f32_e32 v44, v36, v36
	v_lshlrev_b32_e32 v54, 16, v56
	v_and_b32_e32 v55, 0xffff0000, v56
	v_fmac_f32_e32 v45, v46, v46
	v_fmac_f32_e32 v44, v52, v52
	v_pk_add_f32 v[40:41], v[40:41], v[60:61]
	v_pk_add_f32 v[32:33], v[32:33], v[54:55]
	v_fmac_f32_e32 v45, v47, v47
	v_fmac_f32_e32 v44, v53, v53
	v_lshlrev_b32_e32 v56, 16, v57
	v_and_b32_e32 v57, 0xffff0000, v57
	v_fmac_f32_e32 v45, v40, v40
	v_fmac_f32_e32 v44, v32, v32
	v_pk_add_f32 v[50:51], v[34:35], v[56:57]
	v_fmac_f32_e32 v45, v41, v41
	v_fmac_f32_e32 v44, v33, v33
	v_fmac_f32_e32 v45, v42, v42
	v_fmac_f32_e32 v44, v50, v50
	v_fmac_f32_e32 v45, v43, v43
	v_fmac_f32_e32 v44, v51, v51
	v_cvt_pk_bf16_f32 v182, v32, v33
	v_add_f32_e32 v32, v45, v44
	ds_bpermute_b32 v33, v214, v32
	v_cvt_pk_bf16_f32 v179, v42, v43
	v_cvt_pk_bf16_f32 v183, v50, v51
	v_cvt_pk_bf16_f32 v181, v52, v53
	v_cvt_pk_bf16_f32 v180, v36, v37
	s_waitcnt lgkmcnt(0)
	v_add_f32_e32 v32, v32, v33
	ds_bpermute_b32 v33, v213, v32
	v_or_b32_e32 v42, s0, v145
	v_cvt_pk_bf16_f32 v177, v46, v47
	v_cvt_pk_bf16_f32 v178, v40, v41
	v_lshlrev_b32_e32 v42, 11, v42
	v_add_u32_e32 v43, v153, v42
	v_add_u32_e32 v191, v152, v42
	v_cndmask_b32_e64 v190, v43, v191, s[6:7]
	global_store_dwordx4 v190, v[176:179], s[12:13]
	s_nop 1
	global_store_dwordx4 v190, v[180:183], s[12:13] offset:64
	s_and_saveexec_b64 s[0:1], s[4:5]
	s_cbranch_execz .LBB0_706
	v_ashrrev_i32_e32 v49, 31, v48
	v_lshl_add_u64 v[34:35], v[48:49], 2, s[16:17]
	s_waitcnt lgkmcnt(0)
	v_add_f32_e32 v32, v32, v33
	global_atomic_add_f32 v[34:35], v32, off
; template <class T> DI T gld_nt(const void* base, unsigned off) { return __builtin_nontemporal_load((const T*)((const char*)base + off)); }
; template <bool NT = false> DI void st_rows16(void* base, unsigned pitch_b, unsigned row0, unsigned col0, int fr, int fq, const u32x4& w0, const u32x4& w1) {
;   u32x4 x;
; #pragma unroll
;   for (int e = 0; e < 4; ++e) x[e] = (unsigned)__builtin_amdgcn_update_dpp(0, (int)w1[e], 0x128  , 0xf, 0xf, false);
;   const bool hi = fr >= 8;
;   u32x4 pa, pb;
; #pragma unroll
;   for (int e = 0; e < 4; ++e) { pa[e] = hi ? x[e] : w0[e]; pb[e] = hi ? w0[e] : x[e]; }
;   const unsigned ra = row0 + (unsigned)(fr & 7), ca = col0 + 8u * fq + (hi ? 32u : 0u), cb = col0 + 8u * fq + (hi ? 0u : 32u);
;   if (NT) { __builtin_nontemporal_store(pa, (u32x4*)((char*)base + (ra * pitch_b + ca * 2u))); __builtin_nontemporal_store(pb, (u32x4*)((char*)base + ((ra + 8u) * pitch_b + cb * 2u))); }
;   else { gst<u32x4>(base, ra * pitch_b + ca * 2u, pa); gst<u32x4>(base, (ra + 8u) * pitch_b + cb * 2u, pb); }
; }
;   DI void operator()(g8::Acc& acc, int pm, int pn, int wr, int wc, int fr, int fq) const {
;     using namespace g8;
; #pragma unroll
;     for (int ai = 0; ai < 2; ++ai)
; #pragma unroll
;       for (int m = 0; m < 4; ++m) {
;         const int row = pm * BM + ai * HALF + wr * 64 + m * 16 + fr; float s = 0.f; u32x4 wv[2];
; #pragma unroll
;         for (int bj = 0; bj < 2; ++bj) {
;           const int col8 = pn * BM + wc * 64 + bj * 32 + fq * 8; const unsigned eo = (unsigned)row * DM + (unsigned)col8;
;           f32x4 r0, r1;
;           if (resf) { r0 = gld_nt<f32x4>(resf, eo * 4u); r1 = gld_nt<f32x4>(resf, eo * 4u + 16u); }
;           else unpk8(gld_nt<u32x4>(resb, eo * 2u), r0, r1);
;           const f32x4 o0 = r0 + acc[ai][bj][m][0], o1 = r1 + acc[ai][bj][m][1];
;           if (outf) { gst<f32x4>(outf, eo * 4u, o0); gst<f32x4>(outf, eo * 4u + 16u, o1); }
;           wv[bj] = pk8(o0, o1);
;           s += o0[0] * o0[0] + o0[1] * o0[1] + o0[2] * o0[2] + o0[3] * o0[3] + o1[0] * o1[0] + o1[1] * o1[1] + o1[2] * o1[2] + o1[3] * o1[3];
;         }
;         if (outb) st_rows16(outb, DM * 2u, (unsigned)(row - fr), (unsigned)(pn * BM + wc * 64), fr, fq, wv[0], wv[1]);
;         s += __shfl_xor(s, 16); s += __shfl_xor(s, 32);
;         if (fq == 0) atomicAdd(ssq + row, s);
;         __builtin_amdgcn_sched_barrier(0);
;       }
.LBB0_706:
	s_or_b64 exec, exec, s[0:1]
	s_add_i32 s0, s21, 0xa0
	v_or_b32_e32 v32, s0, v142
	s_waitcnt lgkmcnt(0)
	v_lshl_add_u32 v33, v32, 11, v154
	global_load_dwordx4 v[34:37], v33, s[24:25] nt
	v_or_b32_e32 v33, 64, v33
	global_load_dwordx4 v[38:41], v33, s[24:25] nt
	s_waitcnt vmcnt(1)
	v_lshlrev_b32_e32 v42, 16, v34
	v_and_b32_e32 v43, 0xffff0000, v34
	v_lshlrev_b32_e32 v34, 16, v35
	v_and_b32_e32 v35, 0xffff0000, v35
	v_pk_add_f32 v[30:31], v[30:31], v[34:35]
	v_pk_add_f32 v[28:29], v[28:29], v[42:43]
	s_waitcnt vmcnt(0)
	v_lshlrev_b32_e32 v34, 16, v38
	v_and_b32_e32 v35, 0xffff0000, v38
	v_lshlrev_b32_e32 v44, 16, v36
	v_and_b32_e32 v45, 0xffff0000, v36
	v_lshlrev_b32_e32 v36, 16, v37
	v_and_b32_e32 v37, 0xffff0000, v37
	v_cvt_pk_bf16_f32 v176, v28, v29
	v_mul_f32_e32 v29, v29, v29
	v_pk_add_f32 v[20:21], v[20:21], v[34:35]
	v_pk_add_f32 v[26:27], v[26:27], v[36:37]
	v_lshlrev_b32_e32 v36, 16, v39
	v_and_b32_e32 v37, 0xffff0000, v39
	v_fmac_f32_e32 v29, v28, v28
	v_mul_f32_e32 v28, v21, v21
	v_pk_add_f32 v[36:37], v[22:23], v[36:37]
	v_fmac_f32_e32 v28, v20, v20
	v_lshlrev_b32_e32 v38, 16, v40
	v_and_b32_e32 v39, 0xffff0000, v40
	v_fmac_f32_e32 v29, v30, v30
	v_fmac_f32_e32 v28, v36, v36
	v_pk_add_f32 v[24:25], v[24:25], v[44:45]
	v_pk_add_f32 v[16:17], v[16:17], v[38:39]
	v_fmac_f32_e32 v29, v31, v31
	v_fmac_f32_e32 v28, v37, v37
	v_lshlrev_b32_e32 v40, 16, v41
	v_and_b32_e32 v41, 0xffff0000, v41
	v_fmac_f32_e32 v29, v24, v24
	v_fmac_f32_e32 v28, v16, v16
	v_pk_add_f32 v[34:35], v[18:19], v[40:41]
	v_fmac_f32_e32 v29, v25, v25
	v_fmac_f32_e32 v28, v17, v17
	v_fmac_f32_e32 v29, v26, v26
	v_fmac_f32_e32 v28, v34, v34
	v_fmac_f32_e32 v29, v27, v27
	v_fmac_f32_e32 v28, v35, v35
	v_cvt_pk_bf16_f32 v182, v16, v17
	v_add_f32_e32 v16, v29, v28
	ds_bpermute_b32 v17, v214, v16
	v_cvt_pk_bf16_f32 v179, v26, v27
	v_cvt_pk_bf16_f32 v183, v34, v35
	v_cvt_pk_bf16_f32 v181, v36, v37
	v_cvt_pk_bf16_f32 v180, v20, v21
	s_waitcnt lgkmcnt(0)
	v_add_f32_e32 v16, v16, v17
	ds_bpermute_b32 v17, v213, v16
	v_or_b32_e32 v26, s0, v145
	v_cvt_pk_bf16_f32 v177, v30, v31
	v_cvt_pk_bf16_f32 v178, v24, v25
	v_lshlrev_b32_e32 v26, 11, v26
	v_add_u32_e32 v27, v153, v26
	v_add_u32_e32 v191, v152, v26
	v_cndmask_b32_e64 v190, v27, v191, s[6:7]
	global_store_dwordx4 v190, v[176:179], s[12:13]
	s_nop 1
	global_store_dwordx4 v190, v[180:183], s[12:13] offset:64
	s_and_saveexec_b64 s[0:1], s[4:5]
	s_cbranch_execz .LBB0_708
	v_ashrrev_i32_e32 v33, 31, v32
	v_lshl_add_u64 v[18:19], v[32:33], 2, s[16:17]
	s_waitcnt lgkmcnt(0)
	v_add_f32_e32 v16, v16, v17
	global_atomic_add_f32 v[18:19], v16, off
.LBB0_708:
	s_or_b64 exec, exec, s[0:1]
	s_addk_i32 s21, 0xb0
	v_or_b32_e32 v16, s21, v142
	s_waitcnt lgkmcnt(0)
	v_lshl_add_u32 v17, v16, 11, v154
	global_load_dwordx4 v[18:21], v17, s[24:25] nt
	v_or_b32_e32 v17, 64, v17
	global_load_dwordx4 v[22:25], v17, s[24:25] nt
	s_waitcnt vmcnt(1)
	v_lshlrev_b32_e32 v26, 16, v18
	v_and_b32_e32 v27, 0xffff0000, v18
	v_lshlrev_b32_e32 v18, 16, v19
	v_and_b32_e32 v19, 0xffff0000, v19
	v_pk_add_f32 v[14:15], v[14:15], v[18:19]
	v_pk_add_f32 v[12:13], v[12:13], v[26:27]
	s_waitcnt vmcnt(0)
	v_lshlrev_b32_e32 v18, 16, v22
	v_and_b32_e32 v19, 0xffff0000, v22
	v_lshlrev_b32_e32 v28, 16, v20
	v_and_b32_e32 v29, 0xffff0000, v20
	v_lshlrev_b32_e32 v20, 16, v21
	v_and_b32_e32 v21, 0xffff0000, v21
	v_cvt_pk_bf16_f32 v176, v12, v13
	v_mul_f32_e32 v13, v13, v13
	v_pk_add_f32 v[4:5], v[4:5], v[18:19]
	v_pk_add_f32 v[10:11], v[10:11], v[20:21]
	v_lshlrev_b32_e32 v20, 16, v23
	v_and_b32_e32 v21, 0xffff0000, v23
	v_fmac_f32_e32 v13, v12, v12
	v_mul_f32_e32 v12, v5, v5
	v_pk_add_f32 v[20:21], v[6:7], v[20:21]
	v_fmac_f32_e32 v12, v4, v4
	v_lshlrev_b32_e32 v22, 16, v24
	v_and_b32_e32 v23, 0xffff0000, v24
	v_fmac_f32_e32 v13, v14, v14
	v_fmac_f32_e32 v12, v20, v20
	v_pk_add_f32 v[8:9], v[8:9], v[28:29]
	v_pk_add_f32 v[0:1], v[0:1], v[22:23]
	v_fmac_f32_e32 v13, v15, v15
	v_fmac_f32_e32 v12, v21, v21
	v_lshlrev_b32_e32 v24, 16, v25
	v_and_b32_e32 v25, 0xffff0000, v25
	v_fmac_f32_e32 v13, v8, v8
	v_fmac_f32_e32 v12, v0, v0
	v_pk_add_f32 v[18:19], v[2:3], v[24:25]
	v_fmac_f32_e32 v13, v9, v9
	v_fmac_f32_e32 v12, v1, v1
	v_fmac_f32_e32 v13, v10, v10
	v_fmac_f32_e32 v12, v18, v18
	v_fmac_f32_e32 v13, v11, v11
	v_fmac_f32_e32 v12, v19, v19
	v_cvt_pk_bf16_f32 v182, v0, v1
	v_add_f32_e32 v0, v13, v12
	ds_bpermute_b32 v1, v214, v0
	v_cvt_pk_bf16_f32 v179, v10, v11
	v_cvt_pk_bf16_f32 v183, v18, v19
	v_cvt_pk_bf16_f32 v181, v20, v21
	v_cvt_pk_bf16_f32 v180, v4, v5
	s_waitcnt lgkmcnt(0)
	v_add_f32_e32 v0, v0, v1
	ds_bpermute_b32 v1, v213, v0
	v_or_b32_e32 v10, s21, v145
	v_cvt_pk_bf16_f32 v177, v14, v15
	v_cvt_pk_bf16_f32 v178, v8, v9
	v_lshlrev_b32_e32 v10, 11, v10
	v_add_u32_e32 v11, v153, v10
	v_add_u32_e32 v191, v152, v10
	v_cndmask_b32_e64 v190, v11, v191, s[6:7]
	global_store_dwordx4 v190, v[176:179], s[12:13]
	s_nop 1
	global_store_dwordx4 v190, v[180:183], s[12:13] offset:64
	s_and_saveexec_b64 s[0:1], s[4:5]
	s_cbranch_execz .LBB0_710
	v_ashrrev_i32_e32 v17, 31, v16
	v_lshl_add_u64 v[2:3], v[16:17], 2, s[16:17]
	s_waitcnt lgkmcnt(0)
	v_add_f32_e32 v0, v0, v1
	global_atomic_add_f32 v[2:3], v0, off

; DI u32x4 pk8(const f32x4& a, const f32x4& b) { u32x4 w; w.x = pk2(a[0], a[1]); w.y = pk2(a[2], a[3]); w.z = pk2(b[0], b[1]); w.w = pk2(b[2], b[3]); return w; }
; template <bool NT = false> DI void st_rows16(void* base, unsigned pitch_b, unsigned row0, unsigned col0, int fr, int fq, const u32x4& w0, const u32x4& w1) {
;   u32x4 x;
; #pragma unroll
;   for (int e = 0; e < 4; ++e) x[e] = (unsigned)__builtin_amdgcn_update_dpp(0, (int)w1[e], 0x128  , 0xf, 0xf, false);
;   const bool hi = fr >= 8;
;   u32x4 pa, pb;
; #pragma unroll
;   for (int e = 0; e < 4; ++e) { pa[e] = hi ? x[e] : w0[e]; pb[e] = hi ? w0[e] : x[e]; }
;   const unsigned ra = row0 + (unsigned)(fr & 7), ca = col0 + 8u * fq + (hi ? 32u : 0u), cb = col0 + 8u * fq + (hi ? 0u : 32u);
;   if (NT) { __builtin_nontemporal_store(pa, (u32x4*)((char*)base + (ra * pitch_b + ca * 2u))); __builtin_nontemporal_store(pb, (u32x4*)((char*)base + ((ra + 8u) * pitch_b + cb * 2u))); }
;   else { gst<u32x4>(base, ra * pitch_b + ca * 2u, pa); gst<u32x4>(base, (ra + 8u) * pitch_b + cb * 2u, pb); }
; }
;   DI void operator()(g8::Acc& acc, int pm, int pn, int wr, int wc, int fr, int fq) const {
;     using namespace g8;
; #pragma unroll
;     for (int ai = 0; ai < 2; ++ai)
; #pragma unroll
;       for (int m = 0; m < 4; ++m) {
;         const int row = pm * BM + ai * HALF + wr * 64 + m * 16 + fr; const float rs = rsqrtf(ssq[row] * (1.0f / DM) + RMS_EPS) * sc;
;         u32x4 wv[2];
; #pragma unroll
;         for (int bj = 0; bj < 2; ++bj) {
;           f32x4 o0 = acc[ai][bj][m][0] * rs, o1 = acc[ai][bj][m][1] * rs;
;           if (act) {
; #pragma unroll
;             for (int e = 0; e < 4; ++e) { const float a = fmaxf(o0[e], 0.f), b = fmaxf(o1[e], 0.f); o0[e] = a * a; o1[e] = b * b; } }
;           wv[bj] = pk8(o0, o1);
;         }
;         st_rows16(dst, (unsigned)ld * 2u, (unsigned)(row - fr), (unsigned)(pn * BM + wc * 64), fr, fq, wv[0], wv[1]);
;         __builtin_amdgcn_sched_barrier(0);
;       }
;   }
.LBB0_763:
	s_lshl_b32 s0, s42, 8
	s_add_i32 s0, s0, s14
	v_or_b32_e32 v150, s0, v140
	v_ashrrev_i32_e32 v151, 31, v150
	v_lshl_add_u64 v[150:151], v[150:151], 2, s[16:17]
	global_load_dword v152, v[150:151], off
	v_mov_b32_e32 v153, 0
	v_lshl_or_b32 v150, s1, 8, v145
	v_or_b32_e32 v151, v150, v143
	v_or_b32_e32 v157, s0, v142
	v_or_b32_e32 v150, v150, v144
	v_lshlrev_b32_e32 v151, 1, v151
	v_lshlrev_b32_e32 v157, 13, v157
	v_lshlrev_b32_e32 v150, 1, v150
	s_waitcnt vmcnt(0)
	v_fmamk_f32 v152, v152, 0x3a800000, v149
	v_mul_f32_e32 v158, 0x4b800000, v152
	v_cmp_gt_f32_e32 vcc, s21, v152
	s_nop 1
	v_cndmask_b32_e32 v152, v152, v158, vcc
	v_rsq_f32_e32 v152, v152
	v_add_u32_e32 v158, v151, v157
	v_mul_f32_e32 v159, 0x45800000, v152
	v_cndmask_b32_e32 v152, v152, v159, vcc
	v_pk_mul_f32 v[118:119], v[118:119], v[152:153] op_sel_hi:[1,0]
	v_pk_mul_f32 v[116:117], v[116:117], v[152:153] op_sel_hi:[1,0]
	v_pk_mul_f32 v[114:115], v[114:115], v[152:153] op_sel_hi:[1,0]
	v_pk_mul_f32 v[112:113], v[112:113], v[152:153] op_sel_hi:[1,0]
	v_pk_mul_f32 v[126:127], v[126:127], v[152:153] op_sel_hi:[1,0]
	v_pk_mul_f32 v[124:125], v[124:125], v[152:153] op_sel_hi:[1,0]
	v_pk_mul_f32 v[122:123], v[122:123], v[152:153] op_sel_hi:[1,0]
	v_pk_mul_f32 v[120:121], v[120:121], v[152:153] op_sel_hi:[1,0]
	v_max_f32_e32 v116, 0, v116
	v_max_f32_e32 v112, 0, v112
	v_max_f32_e32 v117, 0, v117
	v_max_f32_e32 v113, 0, v113
	v_max_f32_e32 v118, 0, v118
	v_max_f32_e32 v114, 0, v114
	v_max_f32_e32 v119, 0, v119
	v_max_f32_e32 v115, 0, v115
	v_max_f32_e32 v124, 0, v124
	v_max_f32_e32 v120, 0, v120
	v_max_f32_e32 v125, 0, v125
	v_max_f32_e32 v121, 0, v121
	v_max_f32_e32 v126, 0, v126
	v_max_f32_e32 v122, 0, v122
	v_max_f32_e32 v127, 0, v127
	v_max_f32_e32 v123, 0, v123
	v_pk_mul_f32 v[116:117], v[116:117], v[116:117]
	v_pk_mul_f32 v[112:113], v[112:113], v[112:113]
	v_pk_mul_f32 v[118:119], v[118:119], v[118:119]
	v_pk_mul_f32 v[114:115], v[114:115], v[114:115]
	v_pk_mul_f32 v[124:125], v[124:125], v[124:125]
	v_pk_mul_f32 v[120:121], v[120:121], v[120:121]
	v_pk_mul_f32 v[126:127], v[126:127], v[126:127]
	v_pk_mul_f32 v[122:123], v[122:123], v[122:123]
	v_cvt_pk_bf16_f32 v116, v116, v117
	v_cvt_pk_bf16_f32 v117, v118, v119
	v_cvt_pk_bf16_f32 v118, v112, v113
	v_cvt_pk_bf16_f32 v112, v124, v125
	v_cvt_pk_bf16_f32 v113, v126, v127
	v_cvt_pk_bf16_f32 v119, v114, v115
	v_cvt_pk_bf16_f32 v114, v120, v121
	v_cvt_pk_bf16_f32 v115, v122, v123
	v_add3_u32 v191, v150, v157, s11
	v_cndmask_b32_e64 v190, v158, v191, s[4:5]
	global_store_dwordx4 v190, v[112:115], s[24:25]
	global_store_dwordx4 v190, v[116:119], s[24:25] offset:64
	s_or_b32 s1, s0, 16
	v_or_b32_e32 v112, s1, v140
	v_ashrrev_i32_e32 v113, 31, v112
	v_lshl_add_u64 v[112:113], v[112:113], 2, s[16:17]
	global_load_dword v112, v[112:113], off
	v_mov_b32_e32 v113, 0
	v_or_b32_e32 v117, s1, v142
	v_lshlrev_b32_e32 v117, 13, v117
	s_waitcnt vmcnt(0)
	v_fmamk_f32 v112, v112, 0x3a800000, v149
	v_mul_f32_e32 v118, 0x4b800000, v112
	v_cmp_gt_f32_e32 vcc, s21, v112
	s_nop 1
	v_cndmask_b32_e32 v112, v112, v118, vcc
	v_rsq_f32_e32 v112, v112
	v_add_u32_e32 v118, v151, v117
	v_mul_f32_e32 v119, 0x45800000, v112
	v_cndmask_b32_e32 v112, v112, v119, vcc
	v_pk_mul_f32 v[102:103], v[102:103], v[112:113] op_sel_hi:[1,0]
	v_pk_mul_f32 v[100:101], v[100:101], v[112:113] op_sel_hi:[1,0]
	v_pk_mul_f32 v[98:99], v[98:99], v[112:113] op_sel_hi:[1,0]
	v_pk_mul_f32 v[96:97], v[96:97], v[112:113] op_sel_hi:[1,0]
	v_pk_mul_f32 v[110:111], v[110:111], v[112:113] op_sel_hi:[1,0]
	v_pk_mul_f32 v[108:109], v[108:109], v[112:113] op_sel_hi:[1,0]
	v_pk_mul_f32 v[106:107], v[106:107], v[112:113] op_sel_hi:[1,0]
	v_pk_mul_f32 v[104:105], v[104:105], v[112:113] op_sel_hi:[1,0]
	v_max_f32_e32 v100, 0, v100
	v_max_f32_e32 v96, 0, v96
	v_max_f32_e32 v101, 0, v101
	v_max_f32_e32 v97, 0, v97
	v_max_f32_e32 v102, 0, v102
	v_max_f32_e32 v98, 0, v98
	v_max_f32_e32 v103, 0, v103
	v_max_f32_e32 v99, 0, v99
	v_max_f32_e32 v108, 0, v108
	v_max_f32_e32 v104, 0, v104
	v_max_f32_e32 v109, 0, v109
	v_max_f32_e32 v105, 0, v105
	v_max_f32_e32 v110, 0, v110
	v_max_f32_e32 v106, 0, v106
	v_max_f32_e32 v111, 0, v111
	v_max_f32_e32 v107, 0, v107
	v_pk_mul_f32 v[100:101], v[100:101], v[100:101]
	v_pk_mul_f32 v[96:97], v[96:97], v[96:97]
	v_pk_mul_f32 v[102:103], v[102:103], v[102:103]
	v_pk_mul_f32 v[98:99], v[98:99], v[98:99]
	v_pk_mul_f32 v[108:109], v[108:109], v[108:109]
	v_pk_mul_f32 v[104:105], v[104:105], v[104:105]
	v_pk_mul_f32 v[110:111], v[110:111], v[110:111]
	v_pk_mul_f32 v[106:107], v[106:107], v[106:107]
	v_cvt_pk_bf16_f32 v100, v100, v101
	v_cvt_pk_bf16_f32 v101, v102, v103
	v_cvt_pk_bf16_f32 v102, v96, v97
	v_cvt_pk_bf16_f32 v96, v108, v109
	v_cvt_pk_bf16_f32 v97, v110, v111
	v_cvt_pk_bf16_f32 v103, v98, v99
	v_cvt_pk_bf16_f32 v98, v104, v105
	v_cvt_pk_bf16_f32 v99, v106, v107
	v_add3_u32 v191, v150, v117, s11
	v_cndmask_b32_e64 v190, v118, v191, s[4:5]
	global_store_dwordx4 v190, v[96:99], s[24:25]
	global_store_dwordx4 v190, v[100:103], s[24:25] offset:64
	s_or_b32 s1, s0, 32
	v_or_b32_e32 v96, s1, v140
	v_ashrrev_i32_e32 v97, 31, v96
	v_lshl_add_u64 v[96:97], v[96:97], 2, s[16:17]
	global_load_dword v96, v[96:97], off
	v_mov_b32_e32 v97, 0
	v_or_b32_e32 v101, s1, v142
	v_lshlrev_b32_e32 v101, 13, v101
	s_waitcnt vmcnt(0)
; DI u32x4 pk8(const f32x4& a, const f32x4& b) { u32x4 w; w.x = pk2(a[0], a[1]); w.y = pk2(a[2], a[3]); w.z = pk2(b[0], b[1]); w.w = pk2(b[2], b[3]); return w; }
; template <bool NT = false> DI void st_rows16(void* base, unsigned pitch_b, unsigned row0, unsigned col0, int fr, int fq, const u32x4& w0, const u32x4& w1) {
;   u32x4 x;
; #pragma unroll
;   for (int e = 0; e < 4; ++e) x[e] = (unsigned)__builtin_amdgcn_update_dpp(0, (int)w1[e], 0x128  , 0xf, 0xf, false);
;   const bool hi = fr >= 8;
;   u32x4 pa, pb;
; #pragma unroll
;   for (int e = 0; e < 4; ++e) { pa[e] = hi ? x[e] : w0[e]; pb[e] = hi ? w0[e] : x[e]; }
;   const unsigned ra = row0 + (unsigned)(fr & 7), ca = col0 + 8u * fq + (hi ? 32u : 0u), cb = col0 + 8u * fq + (hi ? 0u : 32u);
;   if (NT) { __builtin_nontemporal_store(pa, (u32x4*)((char*)base + (ra * pitch_b + ca * 2u))); __builtin_nontemporal_store(pb, (u32x4*)((char*)base + ((ra + 8u) * pitch_b + cb * 2u))); }
;   else { gst<u32x4>(base, ra * pitch_b + ca * 2u, pa); gst<u32x4>(base, (ra + 8u) * pitch_b + cb * 2u, pb); }
; }
;   DI void operator()(g8::Acc& acc, int pm, int pn, int wr, int wc, int fr, int fq) const {
;     using namespace g8;
; #pragma unroll
;     for (int ai = 0; ai < 2; ++ai)
; #pragma unroll
;       for (int m = 0; m < 4; ++m) {
;         const int row = pm * BM + ai * HALF + wr * 64 + m * 16 + fr; const float rs = rsqrtf(ssq[row] * (1.0f / DM) + RMS_EPS) * sc;
;         u32x4 wv[2];
; #pragma unroll
;         for (int bj = 0; bj < 2; ++bj) {
;           f32x4 o0 = acc[ai][bj][m][0] * rs, o1 = acc[ai][bj][m][1] * rs;
;           if (act) {
; #pragma unroll
;             for (int e = 0; e < 4; ++e) { const float a = fmaxf(o0[e], 0.f), b = fmaxf(o1[e], 0.f); o0[e] = a * a; o1[e] = b * b; } }
;           wv[bj] = pk8(o0, o1);
;         }
;         st_rows16(dst, (unsigned)ld * 2u, (unsigned)(row - fr), (unsigned)(pn * BM + wc * 64), fr, fq, wv[0], wv[1]);
;         __builtin_amdgcn_sched_barrier(0);
;       }
;   }
	v_fmamk_f32 v96, v96, 0x3a800000, v149
	v_mul_f32_e32 v102, 0x4b800000, v96
	v_cmp_gt_f32_e32 vcc, s21, v96
	s_nop 1
	v_cndmask_b32_e32 v96, v96, v102, vcc
	v_rsq_f32_e32 v96, v96
	v_add_u32_e32 v102, v151, v101
	v_mul_f32_e32 v103, 0x45800000, v96
	v_cndmask_b32_e32 v96, v96, v103, vcc
	v_pk_mul_f32 v[86:87], v[86:87], v[96:97] op_sel_hi:[1,0]
	v_pk_mul_f32 v[84:85], v[84:85], v[96:97] op_sel_hi:[1,0]
	v_pk_mul_f32 v[82:83], v[82:83], v[96:97] op_sel_hi:[1,0]
	v_pk_mul_f32 v[80:81], v[80:81], v[96:97] op_sel_hi:[1,0]
	v_pk_mul_f32 v[94:95], v[94:95], v[96:97] op_sel_hi:[1,0]
	v_pk_mul_f32 v[92:93], v[92:93], v[96:97] op_sel_hi:[1,0]
	v_pk_mul_f32 v[90:91], v[90:91], v[96:97] op_sel_hi:[1,0]
	v_pk_mul_f32 v[88:89], v[88:89], v[96:97] op_sel_hi:[1,0]
	v_max_f32_e32 v84, 0, v84
	v_max_f32_e32 v80, 0, v80
	v_max_f32_e32 v85, 0, v85
	v_max_f32_e32 v81, 0, v81
	v_max_f32_e32 v86, 0, v86
	v_max_f32_e32 v82, 0, v82
	v_max_f32_e32 v87, 0, v87
	v_max_f32_e32 v83, 0, v83
	v_max_f32_e32 v92, 0, v92
	v_max_f32_e32 v88, 0, v88
	v_max_f32_e32 v93, 0, v93
	v_max_f32_e32 v89, 0, v89
	v_max_f32_e32 v94, 0, v94
	v_max_f32_e32 v90, 0, v90
	v_max_f32_e32 v95, 0, v95
	v_max_f32_e32 v91, 0, v91
	v_pk_mul_f32 v[84:85], v[84:85], v[84:85]
	v_pk_mul_f32 v[80:81], v[80:81], v[80:81]
	v_pk_mul_f32 v[86:87], v[86:87], v[86:87]
	v_pk_mul_f32 v[82:83], v[82:83], v[82:83]
	v_pk_mul_f32 v[92:93], v[92:93], v[92:93]
	v_pk_mul_f32 v[88:89], v[88:89], v[88:89]
	v_pk_mul_f32 v[94:95], v[94:95], v[94:95]
	v_pk_mul_f32 v[90:91], v[90:91], v[90:91]
	v_cvt_pk_bf16_f32 v84, v84, v85
	v_cvt_pk_bf16_f32 v85, v86, v87
	v_cvt_pk_bf16_f32 v86, v80, v81
	v_cvt_pk_bf16_f32 v80, v92, v93
	v_cvt_pk_bf16_f32 v81, v94, v95
	v_cvt_pk_bf16_f32 v87, v82, v83
	v_cvt_pk_bf16_f32 v82, v88, v89
	v_cvt_pk_bf16_f32 v83, v90, v91
	v_add3_u32 v191, v150, v101, s11
	v_cndmask_b32_e64 v190, v102, v191, s[4:5]
	global_store_dwordx4 v190, v[80:83], s[24:25]
	global_store_dwordx4 v190, v[84:87], s[24:25] offset:64
	s_or_b32 s1, s0, 48
	v_or_b32_e32 v80, s1, v140
	v_ashrrev_i32_e32 v81, 31, v80
	v_lshl_add_u64 v[80:81], v[80:81], 2, s[16:17]
	global_load_dword v80, v[80:81], off
	v_mov_b32_e32 v81, 0
	v_or_b32_e32 v85, s1, v142
	v_lshlrev_b32_e32 v85, 13, v85
	s_waitcnt vmcnt(0)
	v_fmamk_f32 v80, v80, 0x3a800000, v149
	v_mul_f32_e32 v86, 0x4b800000, v80
	v_cmp_gt_f32_e32 vcc, s21, v80
	s_nop 1
	v_cndmask_b32_e32 v80, v80, v86, vcc
	v_rsq_f32_e32 v80, v80
	v_add_u32_e32 v86, v151, v85
	v_mul_f32_e32 v87, 0x45800000, v80
	v_cndmask_b32_e32 v80, v80, v87, vcc
	v_pk_mul_f32 v[70:71], v[70:71], v[80:81] op_sel_hi:[1,0]
	v_pk_mul_f32 v[68:69], v[68:69], v[80:81] op_sel_hi:[1,0]
	v_pk_mul_f32 v[66:67], v[66:67], v[80:81] op_sel_hi:[1,0]
	v_pk_mul_f32 v[64:65], v[64:65], v[80:81] op_sel_hi:[1,0]
	v_pk_mul_f32 v[78:79], v[78:79], v[80:81] op_sel_hi:[1,0]
	v_pk_mul_f32 v[76:77], v[76:77], v[80:81] op_sel_hi:[1,0]
	v_pk_mul_f32 v[74:75], v[74:75], v[80:81] op_sel_hi:[1,0]
	v_pk_mul_f32 v[72:73], v[72:73], v[80:81] op_sel_hi:[1,0]
	v_max_f32_e32 v68, 0, v68
	v_max_f32_e32 v64, 0, v64
	v_max_f32_e32 v69, 0, v69
	v_max_f32_e32 v65, 0, v65
	v_max_f32_e32 v70, 0, v70
	v_max_f32_e32 v66, 0, v66
	v_max_f32_e32 v71, 0, v71
	v_max_f32_e32 v67, 0, v67
	v_max_f32_e32 v76, 0, v76
	v_max_f32_e32 v72, 0, v72
	v_max_f32_e32 v77, 0, v77
	v_max_f32_e32 v73, 0, v73
	v_max_f32_e32 v78, 0, v78
	v_max_f32_e32 v74, 0, v74
	v_max_f32_e32 v79, 0, v79
	v_max_f32_e32 v75, 0, v75
	v_pk_mul_f32 v[68:69], v[68:69], v[68:69]
	v_pk_mul_f32 v[64:65], v[64:65], v[64:65]
	v_pk_mul_f32 v[70:71], v[70:71], v[70:71]
	v_pk_mul_f32 v[66:67], v[66:67], v[66:67]
	v_pk_mul_f32 v[76:77], v[76:77], v[76:77]
	v_pk_mul_f32 v[72:73], v[72:73], v[72:73]
	v_pk_mul_f32 v[78:79], v[78:79], v[78:79]
	v_pk_mul_f32 v[74:75], v[74:75], v[74:75]
	v_cvt_pk_bf16_f32 v68, v68, v69
	v_cvt_pk_bf16_f32 v69, v70, v71
	v_cvt_pk_bf16_f32 v70, v64, v65
	v_cvt_pk_bf16_f32 v64, v76, v77
	v_cvt_pk_bf16_f32 v65, v78, v79
	v_cvt_pk_bf16_f32 v71, v66, v67
	v_cvt_pk_bf16_f32 v66, v72, v73
	v_cvt_pk_bf16_f32 v67, v74, v75
	v_add3_u32 v191, v150, v85, s11
	v_cndmask_b32_e64 v190, v86, v191, s[4:5]
	global_store_dwordx4 v190, v[64:67], s[24:25]
	global_store_dwordx4 v190, v[68:71], s[24:25] offset:64
	s_add_i32 s1, s0, 0x80
	v_or_b32_e32 v64, s1, v140
	v_ashrrev_i32_e32 v65, 31, v64
	v_lshl_add_u64 v[64:65], v[64:65], 2, s[16:17]
	global_load_dword v64, v[64:65], off
	v_mov_b32_e32 v65, 0
	v_or_b32_e32 v69, s1, v142
	v_lshlrev_b32_e32 v69, 13, v69
	s_waitcnt vmcnt(0)
	v_fmamk_f32 v64, v64, 0x3a800000, v149
	v_mul_f32_e32 v70, 0x4b800000, v64
	v_cmp_gt_f32_e32 vcc, s21, v64
	s_nop 1
	v_cndmask_b32_e32 v64, v64, v70, vcc
	v_rsq_f32_e32 v64, v64
	v_add_u32_e32 v70, v151, v69
	v_mul_f32_e32 v71, 0x45800000, v64
	v_cndmask_b32_e32 v64, v64, v71, vcc
	v_pk_mul_f32 v[54:55], v[54:55], v[64:65] op_sel_hi:[1,0]
	v_pk_mul_f32 v[52:53], v[52:53], v[64:65] op_sel_hi:[1,0]
	v_pk_mul_f32 v[50:51], v[50:51], v[64:65] op_sel_hi:[1,0]
	v_pk_mul_f32 v[48:49], v[48:49], v[64:65] op_sel_hi:[1,0]
	v_pk_mul_f32 v[62:63], v[62:63], v[64:65] op_sel_hi:[1,0]
	v_pk_mul_f32 v[60:61], v[60:61], v[64:65] op_sel_hi:[1,0]
	v_pk_mul_f32 v[58:59], v[58:59], v[64:65] op_sel_hi:[1,0]
	v_pk_mul_f32 v[56:57], v[56:57], v[64:65] op_sel_hi:[1,0]
	v_max_f32_e32 v52, 0, v52
	v_max_f32_e32 v48, 0, v48
	v_max_f32_e32 v53, 0, v53
	v_max_f32_e32 v49, 0, v49
	v_max_f32_e32 v54, 0, v54
	v_max_f32_e32 v50, 0, v50
	v_max_f32_e32 v55, 0, v55
	v_max_f32_e32 v51, 0, v51
	v_max_f32_e32 v60, 0, v60
	v_max_f32_e32 v56, 0, v56
	v_max_f32_e32 v61, 0, v61
	v_max_f32_e32 v57, 0, v57
	v_max_f32_e32 v62, 0, v62
	v_max_f32_e32 v58, 0, v58
	v_max_f32_e32 v63, 0, v63
	v_max_f32_e32 v59, 0, v59
	v_pk_mul_f32 v[52:53], v[52:53], v[52:53]
	v_pk_mul_f32 v[48:49], v[48:49], v[48:49]
	v_pk_mul_f32 v[54:55], v[54:55], v[54:55]
	v_pk_mul_f32 v[50:51], v[50:51], v[50:51]
	v_pk_mul_f32 v[60:61], v[60:61], v[60:61]
	v_pk_mul_f32 v[56:57], v[56:57], v[56:57]
	v_pk_mul_f32 v[62:63], v[62:63], v[62:63]
	v_pk_mul_f32 v[58:59], v[58:59], v[58:59]
	v_cvt_pk_bf16_f32 v52, v52, v53
	v_cvt_pk_bf16_f32 v53, v54, v55
	v_cvt_pk_bf16_f32 v54, v48, v49
	v_cvt_pk_bf16_f32 v48, v60, v61
	v_cvt_pk_bf16_f32 v49, v62, v63
	v_cvt_pk_bf16_f32 v55, v50, v51
	v_cvt_pk_bf16_f32 v50, v56, v57
	v_cvt_pk_bf16_f32 v51, v58, v59
	v_add3_u32 v191, v150, v69, s11
	v_cndmask_b32_e64 v190, v70, v191, s[4:5]
	global_store_dwordx4 v190, v[48:51], s[24:25]
	global_store_dwordx4 v190, v[52:55], s[24:25] offset:64
	s_add_i32 s1, s0, 0x90
	v_or_b32_e32 v48, s1, v140
	v_ashrrev_i32_e32 v49, 31, v48
	v_lshl_add_u64 v[48:49], v[48:49], 2, s[16:17]
	global_load_dword v48, v[48:49], off
	v_mov_b32_e32 v49, 0
	v_or_b32_e32 v53, s1, v142
	v_lshlrev_b32_e32 v53, 13, v53
	s_waitcnt vmcnt(0)
; DI u32x4 pk8(const f32x4& a, const f32x4& b) { u32x4 w; w.x = pk2(a[0], a[1]); w.y = pk2(a[2], a[3]); w.z = pk2(b[0], b[1]); w.w = pk2(b[2], b[3]); return w; }
; template <bool NT = false> DI void st_rows16(void* base, unsigned pitch_b, unsigned row0, unsigned col0, int fr, int fq, const u32x4& w0, const u32x4& w1) {
;   u32x4 x;
; #pragma unroll
;   for (int e = 0; e < 4; ++e) x[e] = (unsigned)__builtin_amdgcn_update_dpp(0, (int)w1[e], 0x128  , 0xf, 0xf, false);
;   const bool hi = fr >= 8;
;   u32x4 pa, pb;
; #pragma unroll
;   for (int e = 0; e < 4; ++e) { pa[e] = hi ? x[e] : w0[e]; pb[e] = hi ? w0[e] : x[e]; }
;   const unsigned ra = row0 + (unsigned)(fr & 7), ca = col0 + 8u * fq + (hi ? 32u : 0u), cb = col0 + 8u * fq + (hi ? 0u : 32u);
;   if (NT) { __builtin_nontemporal_store(pa, (u32x4*)((char*)base + (ra * pitch_b + ca * 2u))); __builtin_nontemporal_store(pb, (u32x4*)((char*)base + ((ra + 8u) * pitch_b + cb * 2u))); }
;   else { gst<u32x4>(base, ra * pitch_b + ca * 2u, pa); gst<u32x4>(base, (ra + 8u) * pitch_b + cb * 2u, pb); }
; }
;   DI void operator()(g8::Acc& acc, int pm, int pn, int wr, int wc, int fr, int fq) const {
;     using namespace g8;
; #pragma unroll
;     for (int ai = 0; ai < 2; ++ai)
; #pragma unroll
;       for (int m = 0; m < 4; ++m) {
;         const int row = pm * BM + ai * HALF + wr * 64 + m * 16 + fr; const float rs = rsqrtf(ssq[row] * (1.0f / DM) + RMS_EPS) * sc;
;         u32x4 wv[2];
; #pragma unroll
;         for (int bj = 0; bj < 2; ++bj) {
;           f32x4 o0 = acc[ai][bj][m][0] * rs, o1 = acc[ai][bj][m][1] * rs;
;           if (act) {
; #pragma unroll
;             for (int e = 0; e < 4; ++e) { const float a = fmaxf(o0[e], 0.f), b = fmaxf(o1[e], 0.f); o0[e] = a * a; o1[e] = b * b; } }
;           wv[bj] = pk8(o0, o1);
;         }
;         st_rows16(dst, (unsigned)ld * 2u, (unsigned)(row - fr), (unsigned)(pn * BM + wc * 64), fr, fq, wv[0], wv[1]);
;         __builtin_amdgcn_sched_barrier(0);
;       }
;   }
	v_fmamk_f32 v48, v48, 0x3a800000, v149
	v_mul_f32_e32 v54, 0x4b800000, v48
	v_cmp_gt_f32_e32 vcc, s21, v48
	s_nop 1
	v_cndmask_b32_e32 v48, v48, v54, vcc
	v_rsq_f32_e32 v48, v48
	v_add_u32_e32 v54, v151, v53
	v_mul_f32_e32 v55, 0x45800000, v48
	v_cndmask_b32_e32 v48, v48, v55, vcc
	v_pk_mul_f32 v[38:39], v[38:39], v[48:49] op_sel_hi:[1,0]
	v_pk_mul_f32 v[36:37], v[36:37], v[48:49] op_sel_hi:[1,0]
	v_pk_mul_f32 v[34:35], v[34:35], v[48:49] op_sel_hi:[1,0]
	v_pk_mul_f32 v[32:33], v[32:33], v[48:49] op_sel_hi:[1,0]
	v_pk_mul_f32 v[46:47], v[46:47], v[48:49] op_sel_hi:[1,0]
	v_pk_mul_f32 v[44:45], v[44:45], v[48:49] op_sel_hi:[1,0]
	v_pk_mul_f32 v[42:43], v[42:43], v[48:49] op_sel_hi:[1,0]
	v_pk_mul_f32 v[40:41], v[40:41], v[48:49] op_sel_hi:[1,0]
	v_max_f32_e32 v36, 0, v36
	v_max_f32_e32 v32, 0, v32
	v_max_f32_e32 v37, 0, v37
	v_max_f32_e32 v33, 0, v33
	v_max_f32_e32 v38, 0, v38
	v_max_f32_e32 v34, 0, v34
	v_max_f32_e32 v39, 0, v39
	v_max_f32_e32 v35, 0, v35
	v_max_f32_e32 v44, 0, v44
	v_max_f32_e32 v40, 0, v40
	v_max_f32_e32 v45, 0, v45
	v_max_f32_e32 v41, 0, v41
	v_max_f32_e32 v46, 0, v46
	v_max_f32_e32 v42, 0, v42
	v_max_f32_e32 v47, 0, v47
	v_max_f32_e32 v43, 0, v43
	v_pk_mul_f32 v[36:37], v[36:37], v[36:37]
	v_pk_mul_f32 v[32:33], v[32:33], v[32:33]
	v_pk_mul_f32 v[38:39], v[38:39], v[38:39]
	v_pk_mul_f32 v[34:35], v[34:35], v[34:35]
	v_pk_mul_f32 v[44:45], v[44:45], v[44:45]
	v_pk_mul_f32 v[40:41], v[40:41], v[40:41]
	v_pk_mul_f32 v[46:47], v[46:47], v[46:47]
	v_pk_mul_f32 v[42:43], v[42:43], v[42:43]
	v_cvt_pk_bf16_f32 v36, v36, v37
	v_cvt_pk_bf16_f32 v37, v38, v39
	v_cvt_pk_bf16_f32 v38, v32, v33
	v_cvt_pk_bf16_f32 v32, v44, v45
	v_cvt_pk_bf16_f32 v33, v46, v47
	v_cvt_pk_bf16_f32 v39, v34, v35
	v_cvt_pk_bf16_f32 v34, v40, v41
	v_cvt_pk_bf16_f32 v35, v42, v43
	v_add3_u32 v191, v150, v53, s11
	v_cndmask_b32_e64 v190, v54, v191, s[4:5]
	global_store_dwordx4 v190, v[32:35], s[24:25]
	global_store_dwordx4 v190, v[36:39], s[24:25] offset:64
	s_add_i32 s1, s0, 0xa0
	v_or_b32_e32 v32, s1, v140
	v_ashrrev_i32_e32 v33, 31, v32
	v_lshl_add_u64 v[32:33], v[32:33], 2, s[16:17]
	global_load_dword v32, v[32:33], off
	v_mov_b32_e32 v33, 0
	v_or_b32_e32 v37, s1, v142
	v_lshlrev_b32_e32 v37, 13, v37
	s_waitcnt vmcnt(0)
	v_fmamk_f32 v32, v32, 0x3a800000, v149
	v_mul_f32_e32 v38, 0x4b800000, v32
	v_cmp_gt_f32_e32 vcc, s21, v32
	s_nop 1
	v_cndmask_b32_e32 v32, v32, v38, vcc
	v_rsq_f32_e32 v32, v32
	v_add_u32_e32 v38, v151, v37
	v_mul_f32_e32 v39, 0x45800000, v32
	v_cndmask_b32_e32 v32, v32, v39, vcc
	v_pk_mul_f32 v[22:23], v[22:23], v[32:33] op_sel_hi:[1,0]
	v_pk_mul_f32 v[20:21], v[20:21], v[32:33] op_sel_hi:[1,0]
	v_pk_mul_f32 v[18:19], v[18:19], v[32:33] op_sel_hi:[1,0]
	v_pk_mul_f32 v[16:17], v[16:17], v[32:33] op_sel_hi:[1,0]
	v_pk_mul_f32 v[30:31], v[30:31], v[32:33] op_sel_hi:[1,0]
	v_pk_mul_f32 v[28:29], v[28:29], v[32:33] op_sel_hi:[1,0]
	v_pk_mul_f32 v[26:27], v[26:27], v[32:33] op_sel_hi:[1,0]
	v_pk_mul_f32 v[24:25], v[24:25], v[32:33] op_sel_hi:[1,0]
	v_max_f32_e32 v20, 0, v20
	v_max_f32_e32 v16, 0, v16
	v_max_f32_e32 v21, 0, v21
	v_max_f32_e32 v17, 0, v17
	v_max_f32_e32 v22, 0, v22
	v_max_f32_e32 v18, 0, v18
	v_max_f32_e32 v23, 0, v23
	v_max_f32_e32 v19, 0, v19
	v_max_f32_e32 v28, 0, v28
	v_max_f32_e32 v24, 0, v24
	v_max_f32_e32 v29, 0, v29
	v_max_f32_e32 v25, 0, v25
	v_max_f32_e32 v30, 0, v30
	v_max_f32_e32 v26, 0, v26
	v_max_f32_e32 v31, 0, v31
	v_max_f32_e32 v27, 0, v27
	v_pk_mul_f32 v[20:21], v[20:21], v[20:21]
	v_pk_mul_f32 v[16:17], v[16:17], v[16:17]
	v_pk_mul_f32 v[22:23], v[22:23], v[22:23]
	v_pk_mul_f32 v[18:19], v[18:19], v[18:19]
	v_pk_mul_f32 v[28:29], v[28:29], v[28:29]
	v_pk_mul_f32 v[24:25], v[24:25], v[24:25]
	v_pk_mul_f32 v[30:31], v[30:31], v[30:31]
	v_pk_mul_f32 v[26:27], v[26:27], v[26:27]
	v_cvt_pk_bf16_f32 v20, v20, v21
	v_cvt_pk_bf16_f32 v21, v22, v23
	v_cvt_pk_bf16_f32 v22, v16, v17
	v_cvt_pk_bf16_f32 v16, v28, v29
	v_cvt_pk_bf16_f32 v17, v30, v31
	v_cvt_pk_bf16_f32 v23, v18, v19
	v_cvt_pk_bf16_f32 v18, v24, v25
	v_cvt_pk_bf16_f32 v19, v26, v27
	v_add3_u32 v191, v150, v37, s11
	v_cndmask_b32_e64 v190, v38, v191, s[4:5]
	global_store_dwordx4 v190, v[16:19], s[24:25]
	global_store_dwordx4 v190, v[20:23], s[24:25] offset:64
	s_addk_i32 s0, 0xb0
	v_or_b32_e32 v16, s0, v140
	v_ashrrev_i32_e32 v17, 31, v16
	v_lshl_add_u64 v[16:17], v[16:17], 2, s[16:17]
	global_load_dword v16, v[16:17], off
	v_mov_b32_e32 v17, 0
	v_or_b32_e32 v21, s0, v142
	v_lshlrev_b32_e32 v21, 13, v21
	s_waitcnt vmcnt(0)
	v_fmamk_f32 v16, v16, 0x3a800000, v149
	v_mul_f32_e32 v22, 0x4b800000, v16
	v_cmp_gt_f32_e32 vcc, s21, v16
	s_nop 1
	v_cndmask_b32_e32 v16, v16, v22, vcc
	v_rsq_f32_e32 v16, v16
	v_add_u32_e32 v22, v151, v21
	v_mul_f32_e32 v23, 0x45800000, v16
	v_cndmask_b32_e32 v16, v16, v23, vcc
	v_pk_mul_f32 v[6:7], v[6:7], v[16:17] op_sel_hi:[1,0]
	v_pk_mul_f32 v[4:5], v[4:5], v[16:17] op_sel_hi:[1,0]
	v_pk_mul_f32 v[2:3], v[2:3], v[16:17] op_sel_hi:[1,0]
	v_pk_mul_f32 v[0:1], v[0:1], v[16:17] op_sel_hi:[1,0]
	v_pk_mul_f32 v[14:15], v[14:15], v[16:17] op_sel_hi:[1,0]
	v_pk_mul_f32 v[12:13], v[12:13], v[16:17] op_sel_hi:[1,0]
	v_pk_mul_f32 v[10:11], v[10:11], v[16:17] op_sel_hi:[1,0]
	v_pk_mul_f32 v[8:9], v[8:9], v[16:17] op_sel_hi:[1,0]
	v_max_f32_e32 v4, 0, v4
	v_max_f32_e32 v0, 0, v0
	v_max_f32_e32 v5, 0, v5
	v_max_f32_e32 v1, 0, v1
	v_max_f32_e32 v6, 0, v6
	v_max_f32_e32 v2, 0, v2
	v_max_f32_e32 v7, 0, v7
	v_max_f32_e32 v3, 0, v3
	v_max_f32_e32 v12, 0, v12
	v_max_f32_e32 v8, 0, v8
	v_max_f32_e32 v13, 0, v13
	v_max_f32_e32 v9, 0, v9
	v_max_f32_e32 v14, 0, v14
	v_max_f32_e32 v10, 0, v10
	v_max_f32_e32 v15, 0, v15
	v_max_f32_e32 v11, 0, v11
	v_pk_mul_f32 v[4:5], v[4:5], v[4:5]
	v_pk_mul_f32 v[0:1], v[0:1], v[0:1]
	v_pk_mul_f32 v[6:7], v[6:7], v[6:7]
	v_pk_mul_f32 v[2:3], v[2:3], v[2:3]
	v_pk_mul_f32 v[12:13], v[12:13], v[12:13]
	v_pk_mul_f32 v[8:9], v[8:9], v[8:9]
	v_pk_mul_f32 v[14:15], v[14:15], v[14:15]
	v_pk_mul_f32 v[10:11], v[10:11], v[10:11]
	v_cvt_pk_bf16_f32 v4, v4, v5
	v_cvt_pk_bf16_f32 v5, v6, v7
	v_cvt_pk_bf16_f32 v6, v0, v1
	v_cvt_pk_bf16_f32 v0, v12, v13
	v_cvt_pk_bf16_f32 v1, v14, v15
	v_cvt_pk_bf16_f32 v7, v2, v3
	v_cvt_pk_bf16_f32 v2, v8, v9
	v_cvt_pk_bf16_f32 v3, v10, v11
	v_add3_u32 v191, v150, v21, s11
	v_cndmask_b32_e64 v190, v22, v191, s[4:5]
	global_store_dwordx4 v190, v[0:3], s[24:25]
	global_store_dwordx4 v190, v[4:7], s[24:25] offset:64
	s_andn2_b64 vcc, exec, s[36:37]
	s_mov_b64 s[0:1], -1
	s_cbranch_vccnz .LBB0_756
	s_andn2_b64 vcc, exec, s[6:7]
	s_cbranch_vccnz .LBB0_755
	s_barrier
	s_branch .LBB0_755
